# per-token key/S/W lists stored transposed in LDS (4(16g+a)): lanes read 16 keys/weights with 4 ds_read_b128, all ds_bpermute removed from U and V loops
# speedup vs baseline: 1.0091x; 1.0076x over previous
; DEV void sort_lists(int lane, int& myi0, int& myi1, float& myg0, float& myg1) {
; #pragma unroll
;     for (int k = 2; k <= 128; k <<= 1) {
; #pragma unroll
;       for (int j = k >> 1; j >= 1; j >>= 1) {
;         if (j == 64) {
;           const bool sw_ = myi1 < myi0;
;           const int ti = sw_ ? myi1 : myi0, tj = sw_ ? myi0 : myi1; const float tg = sw_ ? myg1 : myg0, th = sw_ ? myg0 : myg1;
;           myi0 = ti; myi1 = tj; myg0 = tg; myg1 = th;
;         } else {
;           const bool lower = (lane & j) == 0;
;           {
;             const bool up = (k == 128) ? true : ((k == 64) ? true : ((lane & k) == 0));
;             const int oi = __shfl_xor(myi0, j); const float og = __shfl_xor(myg0, j);
;             const bool take = (lower == up) ? (oi < myi0) : (oi > myi0);
;             myi0 = take ? oi : myi0; myg0 = take ? og : myg0;
;           }
;           {
;             const bool up = (k == 128) ? true : ((k == 64) ? false : ((lane & k) == 0));
;             const int oi = __shfl_xor(myi1, j); const float og = __shfl_xor(myg1, j);
;             const bool take = (lower == up) ? (oi < myi1) : (oi > myi1);
;             myi1 = take ? oi : myi1; myg1 = take ? og : myg1;
;           }
;         }
;       }
;     }
; }
.Lpg0_p0:
	v_readlane_b32 s82, v231, 26
	v_readlane_b32 s83, v231, 27
	s_nop 4
	s_lshl_b32 s98, s2, 2
	s_add_u32 s98, s98, s33
	s_add_u32 s98, s98, 0
	s_lshl_b32 s98, s98, 9
	v_add_u32_e32 v116, s98, v234
	global_load_dword v241, v116, s[82:83]
	global_load_dword v242, v116, s[82:83] offset:256
	s_lshl_b32 s98, s2, 2
	s_add_u32 s98, s98, s33
	s_add_u32 s98, s98, 1
	s_lshl_b32 s98, s98, 9
	v_add_u32_e32 v117, s98, v234
	global_load_dword v243, v117, s[82:83]
	global_load_dword v244, v117, s[82:83] offset:256
	s_lshl_b32 s98, s2, 2
	s_add_u32 s98, s98, s33
	s_add_u32 s98, s98, 2
	s_lshl_b32 s98, s98, 9
	v_add_u32_e32 v118, s98, v234
	global_load_dword v245, v118, s[82:83]
	global_load_dword v246, v118, s[82:83] offset:256
	s_lshl_b32 s98, s2, 2
	s_add_u32 s98, s98, s33
	s_add_u32 s98, s98, 3
	s_lshl_b32 s98, s98, 9
	v_add_u32_e32 v119, s98, v234
	global_load_dword v247, v119, s[82:83]
	global_load_dword v248, v119, s[82:83] offset:256
	s_waitcnt vmcnt(0)
	v_or_b32_e32 v116, 64, v233
	v_lshl_or_b32 v241, v241, 7, v233
	v_lshl_or_b32 v242, v242, 7, v116
	v_lshl_or_b32 v243, v243, 7, v233
	v_lshl_or_b32 v244, v244, 7, v116
	v_lshl_or_b32 v245, v245, 7, v233
	v_lshl_or_b32 v246, v246, 7, v116
	v_lshl_or_b32 v247, v247, 7, v233
	v_lshl_or_b32 v248, v248, 7, v116
	v_xor_b32_e32 v116, 4, v234
	ds_bpermute_b32 v0, v116, v241
	ds_bpermute_b32 v1, v116, v243
	ds_bpermute_b32 v2, v116, v245
	ds_bpermute_b32 v3, v116, v247
	ds_bpermute_b32 v4, v116, v242
	ds_bpermute_b32 v5, v116, v244
	ds_bpermute_b32 v6, v116, v246
	ds_bpermute_b32 v7, v116, v248
	s_waitcnt lgkmcnt(0)
	s_mov_b32 s88, 0x99999999
	s_mov_b32 s89, 0x99999999
	v_min_u32_e32 v104, v241, v0
	v_max_u32_e32 v105, v241, v0
	v_cndmask_b32_e64 v241, v105, v104, s[88:89]
	v_min_u32_e32 v106, v243, v1
	v_max_u32_e32 v107, v243, v1
	v_cndmask_b32_e64 v243, v107, v106, s[88:89]
	v_min_u32_e32 v104, v245, v2
	v_max_u32_e32 v105, v245, v2
	v_cndmask_b32_e64 v245, v105, v104, s[88:89]
	v_min_u32_e32 v106, v247, v3
	v_max_u32_e32 v107, v247, v3
	v_cndmask_b32_e64 v247, v107, v106, s[88:89]
	v_min_u32_e32 v104, v242, v4
	v_max_u32_e32 v105, v242, v4
	v_cndmask_b32_e64 v242, v105, v104, s[88:89]
	v_min_u32_e32 v106, v244, v5
	v_max_u32_e32 v107, v244, v5
	v_cndmask_b32_e64 v244, v107, v106, s[88:89]
	v_min_u32_e32 v104, v246, v6
	v_max_u32_e32 v105, v246, v6
	v_cndmask_b32_e64 v246, v105, v104, s[88:89]
	v_min_u32_e32 v106, v248, v7
	v_max_u32_e32 v107, v248, v7
	v_cndmask_b32_e64 v248, v107, v106, s[88:89]
	v_xor_b32_e32 v116, 8, v234
	ds_bpermute_b32 v0, v116, v241
	ds_bpermute_b32 v1, v116, v243
	ds_bpermute_b32 v2, v116, v245
	ds_bpermute_b32 v3, v116, v247
	ds_bpermute_b32 v4, v116, v242
	ds_bpermute_b32 v5, v116, v244
	ds_bpermute_b32 v6, v116, v246
	ds_bpermute_b32 v7, v116, v248
	s_waitcnt lgkmcnt(0)
	s_mov_b32 s88, 0xc3c3c3c3
	s_mov_b32 s89, 0xc3c3c3c3
	v_min_u32_e32 v104, v241, v0
	v_max_u32_e32 v105, v241, v0
	v_cndmask_b32_e64 v241, v105, v104, s[88:89]
	v_min_u32_e32 v106, v243, v1
	v_max_u32_e32 v107, v243, v1
	v_cndmask_b32_e64 v243, v107, v106, s[88:89]
	v_min_u32_e32 v104, v245, v2
	v_max_u32_e32 v105, v245, v2
	v_cndmask_b32_e64 v245, v105, v104, s[88:89]
	v_min_u32_e32 v106, v247, v3
	v_max_u32_e32 v107, v247, v3
	v_cndmask_b32_e64 v247, v107, v106, s[88:89]
	v_min_u32_e32 v104, v242, v4
	v_max_u32_e32 v105, v242, v4
	v_cndmask_b32_e64 v242, v105, v104, s[88:89]
	v_min_u32_e32 v106, v244, v5
	v_max_u32_e32 v107, v244, v5
	v_cndmask_b32_e64 v244, v107, v106, s[88:89]
	v_min_u32_e32 v104, v246, v6
	v_max_u32_e32 v105, v246, v6
	v_cndmask_b32_e64 v246, v105, v104, s[88:89]
	v_min_u32_e32 v106, v248, v7
	v_max_u32_e32 v107, v248, v7
	v_cndmask_b32_e64 v248, v107, v106, s[88:89]
	v_xor_b32_e32 v116, 4, v234
	ds_bpermute_b32 v0, v116, v241
	ds_bpermute_b32 v1, v116, v243
	ds_bpermute_b32 v2, v116, v245
	ds_bpermute_b32 v3, v116, v247
	ds_bpermute_b32 v4, v116, v242
	ds_bpermute_b32 v5, v116, v244
	ds_bpermute_b32 v6, v116, v246
	ds_bpermute_b32 v7, v116, v248
	s_waitcnt lgkmcnt(0)
	s_mov_b32 s88, 0xa5a5a5a5
	s_mov_b32 s89, 0xa5a5a5a5
	v_min_u32_e32 v104, v241, v0
	v_max_u32_e32 v105, v241, v0
	v_cndmask_b32_e64 v241, v105, v104, s[88:89]
	v_min_u32_e32 v106, v243, v1
	v_max_u32_e32 v107, v243, v1
	v_cndmask_b32_e64 v243, v107, v106, s[88:89]
	v_min_u32_e32 v104, v245, v2
	v_max_u32_e32 v105, v245, v2
	v_cndmask_b32_e64 v245, v105, v104, s[88:89]
	v_min_u32_e32 v106, v247, v3
	v_max_u32_e32 v107, v247, v3
	v_cndmask_b32_e64 v247, v107, v106, s[88:89]
	v_min_u32_e32 v104, v242, v4
	v_max_u32_e32 v105, v242, v4
	v_cndmask_b32_e64 v242, v105, v104, s[88:89]
	v_min_u32_e32 v106, v244, v5
	v_max_u32_e32 v107, v244, v5
	v_cndmask_b32_e64 v244, v107, v106, s[88:89]
	v_min_u32_e32 v104, v246, v6
	v_max_u32_e32 v105, v246, v6
	v_cndmask_b32_e64 v246, v105, v104, s[88:89]
	v_min_u32_e32 v106, v248, v7
	v_max_u32_e32 v107, v248, v7
	v_cndmask_b32_e64 v248, v107, v106, s[88:89]
	v_xor_b32_e32 v116, 16, v234
	ds_bpermute_b32 v0, v116, v241
	ds_bpermute_b32 v1, v116, v243
	ds_bpermute_b32 v2, v116, v245
	ds_bpermute_b32 v3, v116, v247
	ds_bpermute_b32 v4, v116, v242
	ds_bpermute_b32 v5, v116, v244
	ds_bpermute_b32 v6, v116, v246
	ds_bpermute_b32 v7, v116, v248
	s_waitcnt lgkmcnt(0)
; DEV void sort_lists(int lane, int& myi0, int& myi1, float& myg0, float& myg1) {
; #pragma unroll
;     for (int k = 2; k <= 128; k <<= 1) {
; #pragma unroll
;       for (int j = k >> 1; j >= 1; j >>= 1) {
;         if (j == 64) {
;           const bool sw_ = myi1 < myi0;
;           const int ti = sw_ ? myi1 : myi0, tj = sw_ ? myi0 : myi1; const float tg = sw_ ? myg1 : myg0, th = sw_ ? myg0 : myg1;
;           myi0 = ti; myi1 = tj; myg0 = tg; myg1 = th;
;         } else {
;           const bool lower = (lane & j) == 0;
;           {
;             const bool up = (k == 128) ? true : ((k == 64) ? true : ((lane & k) == 0));
;             const int oi = __shfl_xor(myi0, j); const float og = __shfl_xor(myg0, j);
;             const bool take = (lower == up) ? (oi < myi0) : (oi > myi0);
;             myi0 = take ? oi : myi0; myg0 = take ? og : myg0;
;           }
;           {
;             const bool up = (k == 128) ? true : ((k == 64) ? false : ((lane & k) == 0));
;             const int oi = __shfl_xor(myi1, j); const float og = __shfl_xor(myg1, j);
;             const bool take = (lower == up) ? (oi < myi1) : (oi > myi1);
;             myi1 = take ? oi : myi1; myg1 = take ? og : myg1;
;           }
;         }
;       }
;     }
; }
	s_mov_b32 s88, 0xf00ff00f
	s_mov_b32 s89, 0xf00ff00f
	v_min_u32_e32 v104, v241, v0
	v_max_u32_e32 v105, v241, v0
	v_cndmask_b32_e64 v241, v105, v104, s[88:89]
	v_min_u32_e32 v106, v243, v1
	v_max_u32_e32 v107, v243, v1
	v_cndmask_b32_e64 v243, v107, v106, s[88:89]
	v_min_u32_e32 v104, v245, v2
	v_max_u32_e32 v105, v245, v2
	v_cndmask_b32_e64 v245, v105, v104, s[88:89]
	v_min_u32_e32 v106, v247, v3
	v_max_u32_e32 v107, v247, v3
	v_cndmask_b32_e64 v247, v107, v106, s[88:89]
	v_min_u32_e32 v104, v242, v4
	v_max_u32_e32 v105, v242, v4
	v_cndmask_b32_e64 v242, v105, v104, s[88:89]
	v_min_u32_e32 v106, v244, v5
	v_max_u32_e32 v107, v244, v5
	v_cndmask_b32_e64 v244, v107, v106, s[88:89]
	v_min_u32_e32 v104, v246, v6
	v_max_u32_e32 v105, v246, v6
	v_cndmask_b32_e64 v246, v105, v104, s[88:89]
	v_min_u32_e32 v106, v248, v7
	v_max_u32_e32 v107, v248, v7
	v_cndmask_b32_e64 v248, v107, v106, s[88:89]
	v_xor_b32_e32 v116, 8, v234
	ds_bpermute_b32 v0, v116, v241
	ds_bpermute_b32 v1, v116, v243
	ds_bpermute_b32 v2, v116, v245
	ds_bpermute_b32 v3, v116, v247
	ds_bpermute_b32 v4, v116, v242
	ds_bpermute_b32 v5, v116, v244
	ds_bpermute_b32 v6, v116, v246
	ds_bpermute_b32 v7, v116, v248
	s_waitcnt lgkmcnt(0)
	s_mov_b32 s88, 0xcc33cc33
	s_mov_b32 s89, 0xcc33cc33
	v_min_u32_e32 v104, v241, v0
	v_max_u32_e32 v105, v241, v0
	v_cndmask_b32_e64 v241, v105, v104, s[88:89]
	v_min_u32_e32 v106, v243, v1
	v_max_u32_e32 v107, v243, v1
	v_cndmask_b32_e64 v243, v107, v106, s[88:89]
	v_min_u32_e32 v104, v245, v2
	v_max_u32_e32 v105, v245, v2
	v_cndmask_b32_e64 v245, v105, v104, s[88:89]
	v_min_u32_e32 v106, v247, v3
	v_max_u32_e32 v107, v247, v3
	v_cndmask_b32_e64 v247, v107, v106, s[88:89]
	v_min_u32_e32 v104, v242, v4
	v_max_u32_e32 v105, v242, v4
	v_cndmask_b32_e64 v242, v105, v104, s[88:89]
	v_min_u32_e32 v106, v244, v5
	v_max_u32_e32 v107, v244, v5
	v_cndmask_b32_e64 v244, v107, v106, s[88:89]
	v_min_u32_e32 v104, v246, v6
	v_max_u32_e32 v105, v246, v6
	v_cndmask_b32_e64 v246, v105, v104, s[88:89]
	v_min_u32_e32 v106, v248, v7
	v_max_u32_e32 v107, v248, v7
	v_cndmask_b32_e64 v248, v107, v106, s[88:89]
	v_xor_b32_e32 v116, 4, v234
	ds_bpermute_b32 v0, v116, v241
	ds_bpermute_b32 v1, v116, v243
	ds_bpermute_b32 v2, v116, v245
	ds_bpermute_b32 v3, v116, v247
	ds_bpermute_b32 v4, v116, v242
	ds_bpermute_b32 v5, v116, v244
	ds_bpermute_b32 v6, v116, v246
	ds_bpermute_b32 v7, v116, v248
	s_waitcnt lgkmcnt(0)
	s_mov_b32 s88, 0xaa55aa55
	s_mov_b32 s89, 0xaa55aa55
	v_min_u32_e32 v104, v241, v0
	v_max_u32_e32 v105, v241, v0
	v_cndmask_b32_e64 v241, v105, v104, s[88:89]
	v_min_u32_e32 v106, v243, v1
	v_max_u32_e32 v107, v243, v1
	v_cndmask_b32_e64 v243, v107, v106, s[88:89]
	v_min_u32_e32 v104, v245, v2
	v_max_u32_e32 v105, v245, v2
	v_cndmask_b32_e64 v245, v105, v104, s[88:89]
	v_min_u32_e32 v106, v247, v3
	v_max_u32_e32 v107, v247, v3
	v_cndmask_b32_e64 v247, v107, v106, s[88:89]
	v_min_u32_e32 v104, v242, v4
	v_max_u32_e32 v105, v242, v4
	v_cndmask_b32_e64 v242, v105, v104, s[88:89]
	v_min_u32_e32 v106, v244, v5
	v_max_u32_e32 v107, v244, v5
	v_cndmask_b32_e64 v244, v107, v106, s[88:89]
	v_min_u32_e32 v104, v246, v6
	v_max_u32_e32 v105, v246, v6
	v_cndmask_b32_e64 v246, v105, v104, s[88:89]
	v_min_u32_e32 v106, v248, v7
	v_max_u32_e32 v107, v248, v7
	v_cndmask_b32_e64 v248, v107, v106, s[88:89]
	v_xor_b32_e32 v116, 32, v234
	ds_bpermute_b32 v0, v116, v241
	ds_bpermute_b32 v1, v116, v243
	ds_bpermute_b32 v2, v116, v245
	ds_bpermute_b32 v3, v116, v247
	ds_bpermute_b32 v4, v116, v242
	ds_bpermute_b32 v5, v116, v244
	ds_bpermute_b32 v6, v116, v246
	ds_bpermute_b32 v7, v116, v248
	s_waitcnt lgkmcnt(0)
	s_mov_b32 s88, 0xff0000ff
	s_mov_b32 s89, 0xff0000ff
	v_min_u32_e32 v104, v241, v0
	v_max_u32_e32 v105, v241, v0
	v_cndmask_b32_e64 v241, v105, v104, s[88:89]
	v_min_u32_e32 v106, v243, v1
	v_max_u32_e32 v107, v243, v1
	v_cndmask_b32_e64 v243, v107, v106, s[88:89]
	v_min_u32_e32 v104, v245, v2
	v_max_u32_e32 v105, v245, v2
	v_cndmask_b32_e64 v245, v105, v104, s[88:89]
	v_min_u32_e32 v106, v247, v3
	v_max_u32_e32 v107, v247, v3
	v_cndmask_b32_e64 v247, v107, v106, s[88:89]
	v_min_u32_e32 v104, v242, v4
	v_max_u32_e32 v105, v242, v4
	v_cndmask_b32_e64 v242, v105, v104, s[88:89]
	v_min_u32_e32 v106, v244, v5
	v_max_u32_e32 v107, v244, v5
	v_cndmask_b32_e64 v244, v107, v106, s[88:89]
	v_min_u32_e32 v104, v246, v6
	v_max_u32_e32 v105, v246, v6
	v_cndmask_b32_e64 v246, v105, v104, s[88:89]
	v_min_u32_e32 v106, v248, v7
	v_max_u32_e32 v107, v248, v7
	v_cndmask_b32_e64 v248, v107, v106, s[88:89]
	v_xor_b32_e32 v116, 16, v234
	ds_bpermute_b32 v0, v116, v241
	ds_bpermute_b32 v1, v116, v243
	ds_bpermute_b32 v2, v116, v245
	ds_bpermute_b32 v3, v116, v247
	ds_bpermute_b32 v4, v116, v242
	ds_bpermute_b32 v5, v116, v244
	ds_bpermute_b32 v6, v116, v246
	ds_bpermute_b32 v7, v116, v248
	s_waitcnt lgkmcnt(0)
	s_mov_b32 s88, 0xf0f00f0f
	s_mov_b32 s89, 0xf0f00f0f
	v_min_u32_e32 v104, v241, v0
	v_max_u32_e32 v105, v241, v0
	v_cndmask_b32_e64 v241, v105, v104, s[88:89]
	v_min_u32_e32 v106, v243, v1
	v_max_u32_e32 v107, v243, v1
	v_cndmask_b32_e64 v243, v107, v106, s[88:89]
	v_min_u32_e32 v104, v245, v2
	v_max_u32_e32 v105, v245, v2
	v_cndmask_b32_e64 v245, v105, v104, s[88:89]
	v_min_u32_e32 v106, v247, v3
	v_max_u32_e32 v107, v247, v3
	v_cndmask_b32_e64 v247, v107, v106, s[88:89]
	v_min_u32_e32 v104, v242, v4
	v_max_u32_e32 v105, v242, v4
	v_cndmask_b32_e64 v242, v105, v104, s[88:89]
	v_min_u32_e32 v106, v244, v5
	v_max_u32_e32 v107, v244, v5
	v_cndmask_b32_e64 v244, v107, v106, s[88:89]
	v_min_u32_e32 v104, v246, v6
	v_max_u32_e32 v105, v246, v6
	v_cndmask_b32_e64 v246, v105, v104, s[88:89]
	v_min_u32_e32 v106, v248, v7
	v_max_u32_e32 v107, v248, v7
	v_cndmask_b32_e64 v248, v107, v106, s[88:89]
	v_xor_b32_e32 v116, 8, v234
	ds_bpermute_b32 v0, v116, v241
	ds_bpermute_b32 v1, v116, v243
	ds_bpermute_b32 v2, v116, v245
	ds_bpermute_b32 v3, v116, v247
	ds_bpermute_b32 v4, v116, v242
	ds_bpermute_b32 v5, v116, v244
	ds_bpermute_b32 v6, v116, v246
	ds_bpermute_b32 v7, v116, v248
	s_waitcnt lgkmcnt(0)
; DEV void sort_lists(int lane, int& myi0, int& myi1, float& myg0, float& myg1) {
; #pragma unroll
;     for (int k = 2; k <= 128; k <<= 1) {
; #pragma unroll
;       for (int j = k >> 1; j >= 1; j >>= 1) {
;         if (j == 64) {
;           const bool sw_ = myi1 < myi0;
;           const int ti = sw_ ? myi1 : myi0, tj = sw_ ? myi0 : myi1; const float tg = sw_ ? myg1 : myg0, th = sw_ ? myg0 : myg1;
;           myi0 = ti; myi1 = tj; myg0 = tg; myg1 = th;
;         } else {
;           const bool lower = (lane & j) == 0;
;           {
;             const bool up = (k == 128) ? true : ((k == 64) ? true : ((lane & k) == 0));
;             const int oi = __shfl_xor(myi0, j); const float og = __shfl_xor(myg0, j);
;             const bool take = (lower == up) ? (oi < myi0) : (oi > myi0);
;             myi0 = take ? oi : myi0; myg0 = take ? og : myg0;
;           }
;           {
;             const bool up = (k == 128) ? true : ((k == 64) ? false : ((lane & k) == 0));
;             const int oi = __shfl_xor(myi1, j); const float og = __shfl_xor(myg1, j);
;             const bool take = (lower == up) ? (oi < myi1) : (oi > myi1);
;             myi1 = take ? oi : myi1; myg1 = take ? og : myg1;
;           }
;         }
;       }
;     }
; }
	s_mov_b32 s88, 0xcccc3333
	s_mov_b32 s89, 0xcccc3333
	v_min_u32_e32 v104, v241, v0
	v_max_u32_e32 v105, v241, v0
	v_cndmask_b32_e64 v241, v105, v104, s[88:89]
	v_min_u32_e32 v106, v243, v1
	v_max_u32_e32 v107, v243, v1
	v_cndmask_b32_e64 v243, v107, v106, s[88:89]
	v_min_u32_e32 v104, v245, v2
	v_max_u32_e32 v105, v245, v2
	v_cndmask_b32_e64 v245, v105, v104, s[88:89]
	v_min_u32_e32 v106, v247, v3
	v_max_u32_e32 v107, v247, v3
	v_cndmask_b32_e64 v247, v107, v106, s[88:89]
	v_min_u32_e32 v104, v242, v4
	v_max_u32_e32 v105, v242, v4
	v_cndmask_b32_e64 v242, v105, v104, s[88:89]
	v_min_u32_e32 v106, v244, v5
	v_max_u32_e32 v107, v244, v5
	v_cndmask_b32_e64 v244, v107, v106, s[88:89]
	v_min_u32_e32 v104, v246, v6
	v_max_u32_e32 v105, v246, v6
	v_cndmask_b32_e64 v246, v105, v104, s[88:89]
	v_min_u32_e32 v106, v248, v7
	v_max_u32_e32 v107, v248, v7
	v_cndmask_b32_e64 v248, v107, v106, s[88:89]
	v_xor_b32_e32 v116, 4, v234
	ds_bpermute_b32 v0, v116, v241
	ds_bpermute_b32 v1, v116, v243
	ds_bpermute_b32 v2, v116, v245
	ds_bpermute_b32 v3, v116, v247
	ds_bpermute_b32 v4, v116, v242
	ds_bpermute_b32 v5, v116, v244
	ds_bpermute_b32 v6, v116, v246
	ds_bpermute_b32 v7, v116, v248
	s_waitcnt lgkmcnt(0)
	s_mov_b32 s88, 0xaaaa5555
	s_mov_b32 s89, 0xaaaa5555
	v_min_u32_e32 v104, v241, v0
	v_max_u32_e32 v105, v241, v0
	v_cndmask_b32_e64 v241, v105, v104, s[88:89]
	v_min_u32_e32 v106, v243, v1
	v_max_u32_e32 v107, v243, v1
	v_cndmask_b32_e64 v243, v107, v106, s[88:89]
	v_min_u32_e32 v104, v245, v2
	v_max_u32_e32 v105, v245, v2
	v_cndmask_b32_e64 v245, v105, v104, s[88:89]
	v_min_u32_e32 v106, v247, v3
	v_max_u32_e32 v107, v247, v3
	v_cndmask_b32_e64 v247, v107, v106, s[88:89]
	v_min_u32_e32 v104, v242, v4
	v_max_u32_e32 v105, v242, v4
	v_cndmask_b32_e64 v242, v105, v104, s[88:89]
	v_min_u32_e32 v106, v244, v5
	v_max_u32_e32 v107, v244, v5
	v_cndmask_b32_e64 v244, v107, v106, s[88:89]
	v_min_u32_e32 v104, v246, v6
	v_max_u32_e32 v105, v246, v6
	v_cndmask_b32_e64 v246, v105, v104, s[88:89]
	v_min_u32_e32 v106, v248, v7
	v_max_u32_e32 v107, v248, v7
	v_cndmask_b32_e64 v248, v107, v106, s[88:89]
	v_xor_b32_e32 v116, 64, v234
	ds_bpermute_b32 v0, v116, v241
	ds_bpermute_b32 v1, v116, v243
	ds_bpermute_b32 v2, v116, v245
	ds_bpermute_b32 v3, v116, v247
	ds_bpermute_b32 v4, v116, v242
	ds_bpermute_b32 v5, v116, v244
	ds_bpermute_b32 v6, v116, v246
	ds_bpermute_b32 v7, v116, v248
	s_waitcnt lgkmcnt(0)
	s_mov_b32 s88, 0xffff
	s_mov_b32 s89, 0xffff0000
	v_min_u32_e32 v104, v241, v0
	v_max_u32_e32 v105, v241, v0
	v_cndmask_b32_e64 v241, v105, v104, s[88:89]
	v_min_u32_e32 v106, v243, v1
	v_max_u32_e32 v107, v243, v1
	v_cndmask_b32_e64 v243, v107, v106, s[88:89]
	v_min_u32_e32 v104, v245, v2
	v_max_u32_e32 v105, v245, v2
	v_cndmask_b32_e64 v245, v105, v104, s[88:89]
	v_min_u32_e32 v106, v247, v3
	v_max_u32_e32 v107, v247, v3
	v_cndmask_b32_e64 v247, v107, v106, s[88:89]
	v_min_u32_e32 v104, v242, v4
	v_max_u32_e32 v105, v242, v4
	v_cndmask_b32_e64 v242, v105, v104, s[88:89]
	v_min_u32_e32 v106, v244, v5
	v_max_u32_e32 v107, v244, v5
	v_cndmask_b32_e64 v244, v107, v106, s[88:89]
	v_min_u32_e32 v104, v246, v6
	v_max_u32_e32 v105, v246, v6
	v_cndmask_b32_e64 v246, v105, v104, s[88:89]
	v_min_u32_e32 v106, v248, v7
	v_max_u32_e32 v107, v248, v7
	v_cndmask_b32_e64 v248, v107, v106, s[88:89]
	v_xor_b32_e32 v116, 32, v234
	ds_bpermute_b32 v0, v116, v241
	ds_bpermute_b32 v1, v116, v243
	ds_bpermute_b32 v2, v116, v245
	ds_bpermute_b32 v3, v116, v247
	ds_bpermute_b32 v4, v116, v242
	ds_bpermute_b32 v5, v116, v244
	ds_bpermute_b32 v6, v116, v246
	ds_bpermute_b32 v7, v116, v248
	s_waitcnt lgkmcnt(0)
	s_mov_b32 s88, 0xff00ff
	s_mov_b32 s89, 0xff00ff00
	v_min_u32_e32 v104, v241, v0
	v_max_u32_e32 v105, v241, v0
	v_cndmask_b32_e64 v241, v105, v104, s[88:89]
	v_min_u32_e32 v106, v243, v1
	v_max_u32_e32 v107, v243, v1
	v_cndmask_b32_e64 v243, v107, v106, s[88:89]
	v_min_u32_e32 v104, v245, v2
	v_max_u32_e32 v105, v245, v2
	v_cndmask_b32_e64 v245, v105, v104, s[88:89]
	v_min_u32_e32 v106, v247, v3
	v_max_u32_e32 v107, v247, v3
	v_cndmask_b32_e64 v247, v107, v106, s[88:89]
	v_min_u32_e32 v104, v242, v4
	v_max_u32_e32 v105, v242, v4
	v_cndmask_b32_e64 v242, v105, v104, s[88:89]
	v_min_u32_e32 v106, v244, v5
	v_max_u32_e32 v107, v244, v5
	v_cndmask_b32_e64 v244, v107, v106, s[88:89]
	v_min_u32_e32 v104, v246, v6
	v_max_u32_e32 v105, v246, v6
	v_cndmask_b32_e64 v246, v105, v104, s[88:89]
	v_min_u32_e32 v106, v248, v7
	v_max_u32_e32 v107, v248, v7
	v_cndmask_b32_e64 v248, v107, v106, s[88:89]
	v_xor_b32_e32 v116, 16, v234
	ds_bpermute_b32 v0, v116, v241
	ds_bpermute_b32 v1, v116, v243
	ds_bpermute_b32 v2, v116, v245
	ds_bpermute_b32 v3, v116, v247
	ds_bpermute_b32 v4, v116, v242
	ds_bpermute_b32 v5, v116, v244
	ds_bpermute_b32 v6, v116, v246
	ds_bpermute_b32 v7, v116, v248
	s_waitcnt lgkmcnt(0)
	s_mov_b32 s88, 0xf0f0f0f
	s_mov_b32 s89, 0xf0f0f0f0
	v_min_u32_e32 v104, v241, v0
	v_max_u32_e32 v105, v241, v0
	v_cndmask_b32_e64 v241, v105, v104, s[88:89]
	v_min_u32_e32 v106, v243, v1
	v_max_u32_e32 v107, v243, v1
	v_cndmask_b32_e64 v243, v107, v106, s[88:89]
	v_min_u32_e32 v104, v245, v2
	v_max_u32_e32 v105, v245, v2
	v_cndmask_b32_e64 v245, v105, v104, s[88:89]
	v_min_u32_e32 v106, v247, v3
	v_max_u32_e32 v107, v247, v3
	v_cndmask_b32_e64 v247, v107, v106, s[88:89]
	v_min_u32_e32 v104, v242, v4
	v_max_u32_e32 v105, v242, v4
	v_cndmask_b32_e64 v242, v105, v104, s[88:89]
	v_min_u32_e32 v106, v244, v5
	v_max_u32_e32 v107, v244, v5
	v_cndmask_b32_e64 v244, v107, v106, s[88:89]
	v_min_u32_e32 v104, v246, v6
	v_max_u32_e32 v105, v246, v6
	v_cndmask_b32_e64 v246, v105, v104, s[88:89]
	v_min_u32_e32 v106, v248, v7
	v_max_u32_e32 v107, v248, v7
	v_cndmask_b32_e64 v248, v107, v106, s[88:89]
	v_xor_b32_e32 v116, 8, v234
	ds_bpermute_b32 v0, v116, v241
	ds_bpermute_b32 v1, v116, v243
	ds_bpermute_b32 v2, v116, v245
	ds_bpermute_b32 v3, v116, v247
	ds_bpermute_b32 v4, v116, v242
	ds_bpermute_b32 v5, v116, v244
	ds_bpermute_b32 v6, v116, v246
	ds_bpermute_b32 v7, v116, v248
	s_waitcnt lgkmcnt(0)
; DEV void sort_lists(int lane, int& myi0, int& myi1, float& myg0, float& myg1) {
; #pragma unroll
;     for (int k = 2; k <= 128; k <<= 1) {
; #pragma unroll
;       for (int j = k >> 1; j >= 1; j >>= 1) {
;         if (j == 64) {
;           const bool sw_ = myi1 < myi0;
;           const int ti = sw_ ? myi1 : myi0, tj = sw_ ? myi0 : myi1; const float tg = sw_ ? myg1 : myg0, th = sw_ ? myg0 : myg1;
;           myi0 = ti; myi1 = tj; myg0 = tg; myg1 = th;
;         } else {
;           const bool lower = (lane & j) == 0;
;           {
;             const bool up = (k == 128) ? true : ((k == 64) ? true : ((lane & k) == 0));
;             const int oi = __shfl_xor(myi0, j); const float og = __shfl_xor(myg0, j);
;             const bool take = (lower == up) ? (oi < myi0) : (oi > myi0);
;             myi0 = take ? oi : myi0; myg0 = take ? og : myg0;
;           }
;           {
;             const bool up = (k == 128) ? true : ((k == 64) ? false : ((lane & k) == 0));
;             const int oi = __shfl_xor(myi1, j); const float og = __shfl_xor(myg1, j);
;             const bool take = (lower == up) ? (oi < myi1) : (oi > myi1);
;             myi1 = take ? oi : myi1; myg1 = take ? og : myg1;
;           }
;         }
;       }
;     }
; }
	s_mov_b32 s88, 0x33333333
	s_mov_b32 s89, 0xcccccccc
	v_min_u32_e32 v104, v241, v0
	v_max_u32_e32 v105, v241, v0
	v_cndmask_b32_e64 v241, v105, v104, s[88:89]
	v_min_u32_e32 v106, v243, v1
	v_max_u32_e32 v107, v243, v1
	v_cndmask_b32_e64 v243, v107, v106, s[88:89]
	v_min_u32_e32 v104, v245, v2
	v_max_u32_e32 v105, v245, v2
	v_cndmask_b32_e64 v245, v105, v104, s[88:89]
	v_min_u32_e32 v106, v247, v3
	v_max_u32_e32 v107, v247, v3
	v_cndmask_b32_e64 v247, v107, v106, s[88:89]
	v_min_u32_e32 v104, v242, v4
	v_max_u32_e32 v105, v242, v4
	v_cndmask_b32_e64 v242, v105, v104, s[88:89]
	v_min_u32_e32 v106, v244, v5
	v_max_u32_e32 v107, v244, v5
	v_cndmask_b32_e64 v244, v107, v106, s[88:89]
	v_min_u32_e32 v104, v246, v6
	v_max_u32_e32 v105, v246, v6
	v_cndmask_b32_e64 v246, v105, v104, s[88:89]
	v_min_u32_e32 v106, v248, v7
	v_max_u32_e32 v107, v248, v7
	v_cndmask_b32_e64 v248, v107, v106, s[88:89]
	v_xor_b32_e32 v116, 4, v234
	ds_bpermute_b32 v0, v116, v241
	ds_bpermute_b32 v1, v116, v243
	ds_bpermute_b32 v2, v116, v245
	ds_bpermute_b32 v3, v116, v247
	ds_bpermute_b32 v4, v116, v242
	ds_bpermute_b32 v5, v116, v244
	ds_bpermute_b32 v6, v116, v246
	ds_bpermute_b32 v7, v116, v248
	s_waitcnt lgkmcnt(0)
	s_mov_b32 s88, 0x55555555
	s_mov_b32 s89, 0xaaaaaaaa
	v_min_u32_e32 v104, v241, v0
	v_max_u32_e32 v105, v241, v0
	v_cndmask_b32_e64 v241, v105, v104, s[88:89]
	v_min_u32_e32 v106, v243, v1
	v_max_u32_e32 v107, v243, v1
	v_cndmask_b32_e64 v243, v107, v106, s[88:89]
	v_min_u32_e32 v104, v245, v2
	v_max_u32_e32 v105, v245, v2
	v_cndmask_b32_e64 v245, v105, v104, s[88:89]
	v_min_u32_e32 v106, v247, v3
	v_max_u32_e32 v107, v247, v3
	v_cndmask_b32_e64 v247, v107, v106, s[88:89]
	v_min_u32_e32 v104, v242, v4
	v_max_u32_e32 v105, v242, v4
	v_cndmask_b32_e64 v242, v105, v104, s[88:89]
	v_min_u32_e32 v106, v244, v5
	v_max_u32_e32 v107, v244, v5
	v_cndmask_b32_e64 v244, v107, v106, s[88:89]
	v_min_u32_e32 v104, v246, v6
	v_max_u32_e32 v105, v246, v6
	v_cndmask_b32_e64 v246, v105, v104, s[88:89]
	v_min_u32_e32 v106, v248, v7
	v_max_u32_e32 v107, v248, v7
	v_cndmask_b32_e64 v248, v107, v106, s[88:89]
	v_xor_b32_e32 v116, 128, v234
	ds_bpermute_b32 v0, v116, v241
	ds_bpermute_b32 v1, v116, v243
	ds_bpermute_b32 v2, v116, v245
	ds_bpermute_b32 v3, v116, v247
	ds_bpermute_b32 v4, v116, v242
	ds_bpermute_b32 v5, v116, v244
	ds_bpermute_b32 v6, v116, v246
	ds_bpermute_b32 v7, v116, v248
	s_waitcnt lgkmcnt(0)
	s_mov_b32 s88, 0xffffffff
	s_mov_b32 s89, 0x0
	v_min_u32_e32 v104, v241, v0
	v_max_u32_e32 v105, v241, v0
	v_cndmask_b32_e64 v241, v105, v104, s[88:89]
	v_min_u32_e32 v106, v243, v1
	v_max_u32_e32 v107, v243, v1
	v_cndmask_b32_e64 v243, v107, v106, s[88:89]
	v_min_u32_e32 v104, v245, v2
	v_max_u32_e32 v105, v245, v2
	v_cndmask_b32_e64 v245, v105, v104, s[88:89]
	v_min_u32_e32 v106, v247, v3
	v_max_u32_e32 v107, v247, v3
	v_cndmask_b32_e64 v247, v107, v106, s[88:89]
	s_mov_b32 s88, 0x0
	s_mov_b32 s89, 0xffffffff
	v_min_u32_e32 v104, v242, v4
	v_max_u32_e32 v105, v242, v4
	v_cndmask_b32_e64 v242, v105, v104, s[88:89]
	v_min_u32_e32 v106, v244, v5
	v_max_u32_e32 v107, v244, v5
	v_cndmask_b32_e64 v244, v107, v106, s[88:89]
	v_min_u32_e32 v104, v246, v6
	v_max_u32_e32 v105, v246, v6
	v_cndmask_b32_e64 v246, v105, v104, s[88:89]
	v_min_u32_e32 v106, v248, v7
	v_max_u32_e32 v107, v248, v7
	v_cndmask_b32_e64 v248, v107, v106, s[88:89]
	v_xor_b32_e32 v116, 64, v234
	ds_bpermute_b32 v0, v116, v241
	ds_bpermute_b32 v1, v116, v243
	ds_bpermute_b32 v2, v116, v245
	ds_bpermute_b32 v3, v116, v247
	ds_bpermute_b32 v4, v116, v242
	ds_bpermute_b32 v5, v116, v244
	ds_bpermute_b32 v6, v116, v246
	ds_bpermute_b32 v7, v116, v248
	s_waitcnt lgkmcnt(0)
	s_mov_b32 s88, 0xffff
	s_mov_b32 s89, 0xffff
	v_min_u32_e32 v104, v241, v0
	v_max_u32_e32 v105, v241, v0
	v_cndmask_b32_e64 v241, v105, v104, s[88:89]
	v_min_u32_e32 v106, v243, v1
	v_max_u32_e32 v107, v243, v1
	v_cndmask_b32_e64 v243, v107, v106, s[88:89]
	v_min_u32_e32 v104, v245, v2
	v_max_u32_e32 v105, v245, v2
	v_cndmask_b32_e64 v245, v105, v104, s[88:89]
	v_min_u32_e32 v106, v247, v3
	v_max_u32_e32 v107, v247, v3
	v_cndmask_b32_e64 v247, v107, v106, s[88:89]
	s_mov_b32 s88, 0xffff0000
	s_mov_b32 s89, 0xffff0000
	v_min_u32_e32 v104, v242, v4
	v_max_u32_e32 v105, v242, v4
	v_cndmask_b32_e64 v242, v105, v104, s[88:89]
	v_min_u32_e32 v106, v244, v5
	v_max_u32_e32 v107, v244, v5
	v_cndmask_b32_e64 v244, v107, v106, s[88:89]
	v_min_u32_e32 v104, v246, v6
	v_max_u32_e32 v105, v246, v6
	v_cndmask_b32_e64 v246, v105, v104, s[88:89]
	v_min_u32_e32 v106, v248, v7
	v_max_u32_e32 v107, v248, v7
	v_cndmask_b32_e64 v248, v107, v106, s[88:89]
	v_xor_b32_e32 v116, 32, v234
	ds_bpermute_b32 v0, v116, v241
	ds_bpermute_b32 v1, v116, v243
	ds_bpermute_b32 v2, v116, v245
	ds_bpermute_b32 v3, v116, v247
	ds_bpermute_b32 v4, v116, v242
	ds_bpermute_b32 v5, v116, v244
	ds_bpermute_b32 v6, v116, v246
	ds_bpermute_b32 v7, v116, v248
	s_waitcnt lgkmcnt(0)
	s_mov_b32 s88, 0xff00ff
	s_mov_b32 s89, 0xff00ff
	v_min_u32_e32 v104, v241, v0
	v_max_u32_e32 v105, v241, v0
	v_cndmask_b32_e64 v241, v105, v104, s[88:89]
	v_min_u32_e32 v106, v243, v1
	v_max_u32_e32 v107, v243, v1
	v_cndmask_b32_e64 v243, v107, v106, s[88:89]
	v_min_u32_e32 v104, v245, v2
	v_max_u32_e32 v105, v245, v2
	v_cndmask_b32_e64 v245, v105, v104, s[88:89]
	v_min_u32_e32 v106, v247, v3
	v_max_u32_e32 v107, v247, v3
	v_cndmask_b32_e64 v247, v107, v106, s[88:89]
	s_mov_b32 s88, 0xff00ff00
	s_mov_b32 s89, 0xff00ff00
	v_min_u32_e32 v104, v242, v4
	v_max_u32_e32 v105, v242, v4
	v_cndmask_b32_e64 v242, v105, v104, s[88:89]
	v_min_u32_e32 v106, v244, v5
	v_max_u32_e32 v107, v244, v5
	v_cndmask_b32_e64 v244, v107, v106, s[88:89]
	v_min_u32_e32 v104, v246, v6
	v_max_u32_e32 v105, v246, v6
	v_cndmask_b32_e64 v246, v105, v104, s[88:89]
	v_min_u32_e32 v106, v248, v7
	v_max_u32_e32 v107, v248, v7
	v_cndmask_b32_e64 v248, v107, v106, s[88:89]
	v_xor_b32_e32 v116, 16, v234
	ds_bpermute_b32 v0, v116, v241
	ds_bpermute_b32 v1, v116, v243
	ds_bpermute_b32 v2, v116, v245
	ds_bpermute_b32 v3, v116, v247
	ds_bpermute_b32 v4, v116, v242
	ds_bpermute_b32 v5, v116, v244
	ds_bpermute_b32 v6, v116, v246
	ds_bpermute_b32 v7, v116, v248
	s_waitcnt lgkmcnt(0)
; DEV void sort_lists(int lane, int& myi0, int& myi1, float& myg0, float& myg1) {
; #pragma unroll
;     for (int k = 2; k <= 128; k <<= 1) {
; #pragma unroll
;       for (int j = k >> 1; j >= 1; j >>= 1) {
;         if (j == 64) {
;           const bool sw_ = myi1 < myi0;
;           const int ti = sw_ ? myi1 : myi0, tj = sw_ ? myi0 : myi1; const float tg = sw_ ? myg1 : myg0, th = sw_ ? myg0 : myg1;
;           myi0 = ti; myi1 = tj; myg0 = tg; myg1 = th;
;         } else {
;           const bool lower = (lane & j) == 0;
;           {
;             const bool up = (k == 128) ? true : ((k == 64) ? true : ((lane & k) == 0));
;             const int oi = __shfl_xor(myi0, j); const float og = __shfl_xor(myg0, j);
;             const bool take = (lower == up) ? (oi < myi0) : (oi > myi0);
;             myi0 = take ? oi : myi0; myg0 = take ? og : myg0;
;           }
;           {
;             const bool up = (k == 128) ? true : ((k == 64) ? false : ((lane & k) == 0));
;             const int oi = __shfl_xor(myi1, j); const float og = __shfl_xor(myg1, j);
;             const bool take = (lower == up) ? (oi < myi1) : (oi > myi1);
;             myi1 = take ? oi : myi1; myg1 = take ? og : myg1;
;           }
;         }
;       }
;     }
; }
	s_mov_b32 s88, 0xf0f0f0f
	s_mov_b32 s89, 0xf0f0f0f
	v_min_u32_e32 v104, v241, v0
	v_max_u32_e32 v105, v241, v0
	v_cndmask_b32_e64 v241, v105, v104, s[88:89]
	v_min_u32_e32 v106, v243, v1
	v_max_u32_e32 v107, v243, v1
	v_cndmask_b32_e64 v243, v107, v106, s[88:89]
	v_min_u32_e32 v104, v245, v2
	v_max_u32_e32 v105, v245, v2
	v_cndmask_b32_e64 v245, v105, v104, s[88:89]
	v_min_u32_e32 v106, v247, v3
	v_max_u32_e32 v107, v247, v3
	v_cndmask_b32_e64 v247, v107, v106, s[88:89]
	s_mov_b32 s88, 0xf0f0f0f0
	s_mov_b32 s89, 0xf0f0f0f0
	v_min_u32_e32 v104, v242, v4
	v_max_u32_e32 v105, v242, v4
	v_cndmask_b32_e64 v242, v105, v104, s[88:89]
	v_min_u32_e32 v106, v244, v5
	v_max_u32_e32 v107, v244, v5
	v_cndmask_b32_e64 v244, v107, v106, s[88:89]
	v_min_u32_e32 v104, v246, v6
	v_max_u32_e32 v105, v246, v6
	v_cndmask_b32_e64 v246, v105, v104, s[88:89]
	v_min_u32_e32 v106, v248, v7
	v_max_u32_e32 v107, v248, v7
	v_cndmask_b32_e64 v248, v107, v106, s[88:89]
	v_xor_b32_e32 v116, 8, v234
	ds_bpermute_b32 v0, v116, v241
	ds_bpermute_b32 v1, v116, v243
	ds_bpermute_b32 v2, v116, v245
	ds_bpermute_b32 v3, v116, v247
	ds_bpermute_b32 v4, v116, v242
	ds_bpermute_b32 v5, v116, v244
	ds_bpermute_b32 v6, v116, v246
	ds_bpermute_b32 v7, v116, v248
	s_waitcnt lgkmcnt(0)
	s_mov_b32 s88, 0x33333333
	s_mov_b32 s89, 0x33333333
	v_min_u32_e32 v104, v241, v0
	v_max_u32_e32 v105, v241, v0
	v_cndmask_b32_e64 v241, v105, v104, s[88:89]
	v_min_u32_e32 v106, v243, v1
	v_max_u32_e32 v107, v243, v1
	v_cndmask_b32_e64 v243, v107, v106, s[88:89]
	v_min_u32_e32 v104, v245, v2
	v_max_u32_e32 v105, v245, v2
	v_cndmask_b32_e64 v245, v105, v104, s[88:89]
	v_min_u32_e32 v106, v247, v3
	v_max_u32_e32 v107, v247, v3
	v_cndmask_b32_e64 v247, v107, v106, s[88:89]
	s_mov_b32 s88, 0xcccccccc
	s_mov_b32 s89, 0xcccccccc
	v_min_u32_e32 v104, v242, v4
	v_max_u32_e32 v105, v242, v4
	v_cndmask_b32_e64 v242, v105, v104, s[88:89]
	v_min_u32_e32 v106, v244, v5
	v_max_u32_e32 v107, v244, v5
	v_cndmask_b32_e64 v244, v107, v106, s[88:89]
	v_min_u32_e32 v104, v246, v6
	v_max_u32_e32 v105, v246, v6
	v_cndmask_b32_e64 v246, v105, v104, s[88:89]
	v_min_u32_e32 v106, v248, v7
	v_max_u32_e32 v107, v248, v7
	v_cndmask_b32_e64 v248, v107, v106, s[88:89]
	v_xor_b32_e32 v116, 4, v234
	ds_bpermute_b32 v0, v116, v241
	ds_bpermute_b32 v1, v116, v243
	ds_bpermute_b32 v2, v116, v245
	ds_bpermute_b32 v3, v116, v247
	ds_bpermute_b32 v4, v116, v242
	ds_bpermute_b32 v5, v116, v244
	ds_bpermute_b32 v6, v116, v246
	ds_bpermute_b32 v7, v116, v248
	s_waitcnt lgkmcnt(0)
	s_mov_b32 s88, 0x55555555
	s_mov_b32 s89, 0x55555555
	v_min_u32_e32 v104, v241, v0
	v_max_u32_e32 v105, v241, v0
	v_cndmask_b32_e64 v241, v105, v104, s[88:89]
	v_min_u32_e32 v106, v243, v1
	v_max_u32_e32 v107, v243, v1
	v_cndmask_b32_e64 v243, v107, v106, s[88:89]
	v_min_u32_e32 v104, v245, v2
	v_max_u32_e32 v105, v245, v2
	v_cndmask_b32_e64 v245, v105, v104, s[88:89]
	v_min_u32_e32 v106, v247, v3
	v_max_u32_e32 v107, v247, v3
	v_cndmask_b32_e64 v247, v107, v106, s[88:89]
	s_mov_b32 s88, 0xaaaaaaaa
	s_mov_b32 s89, 0xaaaaaaaa
	v_min_u32_e32 v104, v242, v4
	v_max_u32_e32 v105, v242, v4
	v_cndmask_b32_e64 v242, v105, v104, s[88:89]
	v_min_u32_e32 v106, v244, v5
	v_max_u32_e32 v107, v244, v5
	v_cndmask_b32_e64 v244, v107, v106, s[88:89]
	v_min_u32_e32 v104, v246, v6
	v_max_u32_e32 v105, v246, v6
	v_cndmask_b32_e64 v246, v105, v104, s[88:89]
	v_min_u32_e32 v106, v248, v7
	v_max_u32_e32 v107, v248, v7
	v_cndmask_b32_e64 v248, v107, v106, s[88:89]
	v_min_u32_e32 v104, v241, v242
	v_max_u32_e32 v242, v241, v242
	v_mov_b32_e32 v241, v104
	v_min_u32_e32 v106, v243, v244
	v_max_u32_e32 v244, v243, v244
	v_mov_b32_e32 v243, v106
	v_min_u32_e32 v104, v245, v246
	v_max_u32_e32 v246, v245, v246
	v_mov_b32_e32 v245, v104
	v_min_u32_e32 v106, v247, v248
	v_max_u32_e32 v248, v247, v248
	v_mov_b32_e32 v247, v106
	v_xor_b32_e32 v116, 128, v234
	ds_bpermute_b32 v0, v116, v241
	ds_bpermute_b32 v1, v116, v243
	ds_bpermute_b32 v2, v116, v245
	ds_bpermute_b32 v3, v116, v247
	ds_bpermute_b32 v4, v116, v242
	ds_bpermute_b32 v5, v116, v244
	ds_bpermute_b32 v6, v116, v246
	ds_bpermute_b32 v7, v116, v248
	s_waitcnt lgkmcnt(0)
	s_mov_b32 s88, 0xffffffff
	s_mov_b32 s89, 0x0
	v_min_u32_e32 v104, v241, v0
	v_max_u32_e32 v105, v241, v0
	v_cndmask_b32_e64 v241, v105, v104, s[88:89]
	v_min_u32_e32 v106, v243, v1
	v_max_u32_e32 v107, v243, v1
	v_cndmask_b32_e64 v243, v107, v106, s[88:89]
	v_min_u32_e32 v104, v245, v2
	v_max_u32_e32 v105, v245, v2
	v_cndmask_b32_e64 v245, v105, v104, s[88:89]
	v_min_u32_e32 v106, v247, v3
	v_max_u32_e32 v107, v247, v3
	v_cndmask_b32_e64 v247, v107, v106, s[88:89]
	v_min_u32_e32 v104, v242, v4
	v_max_u32_e32 v105, v242, v4
	v_cndmask_b32_e64 v242, v105, v104, s[88:89]
	v_min_u32_e32 v106, v244, v5
	v_max_u32_e32 v107, v244, v5
	v_cndmask_b32_e64 v244, v107, v106, s[88:89]
	v_min_u32_e32 v104, v246, v6
	v_max_u32_e32 v105, v246, v6
	v_cndmask_b32_e64 v246, v105, v104, s[88:89]
	v_min_u32_e32 v106, v248, v7
	v_max_u32_e32 v107, v248, v7
	v_cndmask_b32_e64 v248, v107, v106, s[88:89]
	v_xor_b32_e32 v116, 64, v234
	ds_bpermute_b32 v0, v116, v241
	ds_bpermute_b32 v1, v116, v243
	ds_bpermute_b32 v2, v116, v245
	ds_bpermute_b32 v3, v116, v247
	ds_bpermute_b32 v4, v116, v242
	ds_bpermute_b32 v5, v116, v244
	ds_bpermute_b32 v6, v116, v246
	ds_bpermute_b32 v7, v116, v248
	s_waitcnt lgkmcnt(0)
; DEV void sort_lists(int lane, int& myi0, int& myi1, float& myg0, float& myg1) {
;     ...
;     for (int k = 2; k <= 128; k <<= 1) {
; #pragma unroll
;       for (int j = k >> 1; j >= 1; j >>= 1) {
;         if (j == 64) {
;           const bool sw_ = myi1 < myi0;
;           const int ti = sw_ ? myi1 : myi0, tj = sw_ ? myi0 : myi1; const float tg = sw_ ? myg1 : myg0, th = sw_ ? myg0 : myg1;
;           myi0 = ti; myi1 = tj; myg0 = tg; myg1 = th;
;         } else {
;           const bool lower = (lane & j) == 0;
;           {
;             const bool up = (k == 128) ? true : ((k == 64) ? true : ((lane & k) == 0));
;             const int oi = __shfl_xor(myi0, j); const float og = __shfl_xor(myg0, j);
;             const bool take = (lower == up) ? (oi < myi0) : (oi > myi0);
;             myi0 = take ? oi : myi0; myg0 = take ? og : myg0;
;           }
;           {
;             const bool up = (k == 128) ? true : ((k == 64) ? false : ((lane & k) == 0));
;             const int oi = __shfl_xor(myi1, j); const float og = __shfl_xor(myg1, j);
;             const bool take = (lower == up) ? (oi < myi1) : (oi > myi1);
;             myi1 = take ? oi : myi1; myg1 = take ? og : myg1;
;           }
;         }
;       }
;     }
; }
; DEV void peer_gather(const Params& P, int l, int m0, const int* idxs, const float* gs) {
;     ...
;   int ni0 = idxs[(wid * 16) * 128 + lane], ni1 = idxs[(wid * 16) * 128 + 64 + lane];
;   float ng0 = gs[(wid * 16) * 128 + lane], ng1 = gs[(wid * 16) * 128 + 64 + lane];
;   sort_lists(lane, ni0, ni1, ng0, ng1);
	s_mov_b32 s88, 0xffff
	s_mov_b32 s89, 0xffff
	v_min_u32_e32 v104, v241, v0
	v_max_u32_e32 v105, v241, v0
	v_cndmask_b32_e64 v241, v105, v104, s[88:89]
	v_min_u32_e32 v106, v243, v1
	v_max_u32_e32 v107, v243, v1
	v_cndmask_b32_e64 v243, v107, v106, s[88:89]
	v_min_u32_e32 v104, v245, v2
	v_max_u32_e32 v105, v245, v2
	v_cndmask_b32_e64 v245, v105, v104, s[88:89]
	v_min_u32_e32 v106, v247, v3
	v_max_u32_e32 v107, v247, v3
	v_cndmask_b32_e64 v247, v107, v106, s[88:89]
	v_min_u32_e32 v104, v242, v4
	v_max_u32_e32 v105, v242, v4
	v_cndmask_b32_e64 v242, v105, v104, s[88:89]
	v_min_u32_e32 v106, v244, v5
	v_max_u32_e32 v107, v244, v5
	v_cndmask_b32_e64 v244, v107, v106, s[88:89]
	v_min_u32_e32 v104, v246, v6
	v_max_u32_e32 v105, v246, v6
	v_cndmask_b32_e64 v246, v105, v104, s[88:89]
	v_min_u32_e32 v106, v248, v7
	v_max_u32_e32 v107, v248, v7
	v_cndmask_b32_e64 v248, v107, v106, s[88:89]
	v_xor_b32_e32 v116, 32, v234
	ds_bpermute_b32 v0, v116, v241
	ds_bpermute_b32 v1, v116, v243
	ds_bpermute_b32 v2, v116, v245
	ds_bpermute_b32 v3, v116, v247
	ds_bpermute_b32 v4, v116, v242
	ds_bpermute_b32 v5, v116, v244
	ds_bpermute_b32 v6, v116, v246
	ds_bpermute_b32 v7, v116, v248
	s_waitcnt lgkmcnt(0)
	s_mov_b32 s88, 0xff00ff
	s_mov_b32 s89, 0xff00ff
	v_min_u32_e32 v104, v241, v0
	v_max_u32_e32 v105, v241, v0
	v_cndmask_b32_e64 v241, v105, v104, s[88:89]
	v_min_u32_e32 v106, v243, v1
	v_max_u32_e32 v107, v243, v1
	v_cndmask_b32_e64 v243, v107, v106, s[88:89]
	v_min_u32_e32 v104, v245, v2
	v_max_u32_e32 v105, v245, v2
	v_cndmask_b32_e64 v245, v105, v104, s[88:89]
	v_min_u32_e32 v106, v247, v3
	v_max_u32_e32 v107, v247, v3
	v_cndmask_b32_e64 v247, v107, v106, s[88:89]
	v_min_u32_e32 v104, v242, v4
	v_max_u32_e32 v105, v242, v4
	v_cndmask_b32_e64 v242, v105, v104, s[88:89]
	v_min_u32_e32 v106, v244, v5
	v_max_u32_e32 v107, v244, v5
	v_cndmask_b32_e64 v244, v107, v106, s[88:89]
	v_min_u32_e32 v104, v246, v6
	v_max_u32_e32 v105, v246, v6
	v_cndmask_b32_e64 v246, v105, v104, s[88:89]
	v_min_u32_e32 v106, v248, v7
	v_max_u32_e32 v107, v248, v7
	v_cndmask_b32_e64 v248, v107, v106, s[88:89]
	v_xor_b32_e32 v116, 16, v234
	ds_bpermute_b32 v0, v116, v241
	ds_bpermute_b32 v1, v116, v243
	ds_bpermute_b32 v2, v116, v245
	ds_bpermute_b32 v3, v116, v247
	ds_bpermute_b32 v4, v116, v242
	ds_bpermute_b32 v5, v116, v244
	ds_bpermute_b32 v6, v116, v246
	ds_bpermute_b32 v7, v116, v248
	s_waitcnt lgkmcnt(0)
	s_mov_b32 s88, 0xf0f0f0f
	s_mov_b32 s89, 0xf0f0f0f
	v_min_u32_e32 v104, v241, v0
	v_max_u32_e32 v105, v241, v0
	v_cndmask_b32_e64 v241, v105, v104, s[88:89]
	v_min_u32_e32 v106, v243, v1
	v_max_u32_e32 v107, v243, v1
	v_cndmask_b32_e64 v243, v107, v106, s[88:89]
	v_min_u32_e32 v104, v245, v2
	v_max_u32_e32 v105, v245, v2
	v_cndmask_b32_e64 v245, v105, v104, s[88:89]
	v_min_u32_e32 v106, v247, v3
	v_max_u32_e32 v107, v247, v3
	v_cndmask_b32_e64 v247, v107, v106, s[88:89]
	v_min_u32_e32 v104, v242, v4
	v_max_u32_e32 v105, v242, v4
	v_cndmask_b32_e64 v242, v105, v104, s[88:89]
	v_min_u32_e32 v106, v244, v5
	v_max_u32_e32 v107, v244, v5
	v_cndmask_b32_e64 v244, v107, v106, s[88:89]
	v_min_u32_e32 v104, v246, v6
	v_max_u32_e32 v105, v246, v6
	v_cndmask_b32_e64 v246, v105, v104, s[88:89]
	v_min_u32_e32 v106, v248, v7
	v_max_u32_e32 v107, v248, v7
	v_cndmask_b32_e64 v248, v107, v106, s[88:89]
	v_xor_b32_e32 v116, 8, v234
	ds_bpermute_b32 v0, v116, v241
	ds_bpermute_b32 v1, v116, v243
	ds_bpermute_b32 v2, v116, v245
	ds_bpermute_b32 v3, v116, v247
	ds_bpermute_b32 v4, v116, v242
	ds_bpermute_b32 v5, v116, v244
	ds_bpermute_b32 v6, v116, v246
	ds_bpermute_b32 v7, v116, v248
	s_waitcnt lgkmcnt(0)
	s_mov_b32 s88, 0x33333333
	s_mov_b32 s89, 0x33333333
	v_min_u32_e32 v104, v241, v0
	v_max_u32_e32 v105, v241, v0
	v_cndmask_b32_e64 v241, v105, v104, s[88:89]
	v_min_u32_e32 v106, v243, v1
	v_max_u32_e32 v107, v243, v1
	v_cndmask_b32_e64 v243, v107, v106, s[88:89]
	v_min_u32_e32 v104, v245, v2
	v_max_u32_e32 v105, v245, v2
	v_cndmask_b32_e64 v245, v105, v104, s[88:89]
	v_min_u32_e32 v106, v247, v3
	v_max_u32_e32 v107, v247, v3
	v_cndmask_b32_e64 v247, v107, v106, s[88:89]
	v_min_u32_e32 v104, v242, v4
	v_max_u32_e32 v105, v242, v4
	v_cndmask_b32_e64 v242, v105, v104, s[88:89]
	v_min_u32_e32 v106, v244, v5
	v_max_u32_e32 v107, v244, v5
	v_cndmask_b32_e64 v244, v107, v106, s[88:89]
	v_min_u32_e32 v104, v246, v6
	v_max_u32_e32 v105, v246, v6
	v_cndmask_b32_e64 v246, v105, v104, s[88:89]
	v_min_u32_e32 v106, v248, v7
	v_max_u32_e32 v107, v248, v7
	v_cndmask_b32_e64 v248, v107, v106, s[88:89]
	v_xor_b32_e32 v116, 4, v234
	ds_bpermute_b32 v0, v116, v241
	ds_bpermute_b32 v1, v116, v243
	ds_bpermute_b32 v2, v116, v245
	ds_bpermute_b32 v3, v116, v247
	ds_bpermute_b32 v4, v116, v242
	ds_bpermute_b32 v5, v116, v244
	ds_bpermute_b32 v6, v116, v246
	ds_bpermute_b32 v7, v116, v248
	s_waitcnt lgkmcnt(0)
	s_mov_b32 s88, 0x55555555
	s_mov_b32 s89, 0x55555555
	v_min_u32_e32 v104, v241, v0
	v_max_u32_e32 v105, v241, v0
	v_cndmask_b32_e64 v241, v105, v104, s[88:89]
	v_min_u32_e32 v106, v243, v1
	v_max_u32_e32 v107, v243, v1
	v_cndmask_b32_e64 v243, v107, v106, s[88:89]
	v_min_u32_e32 v104, v245, v2
	v_max_u32_e32 v105, v245, v2
	v_cndmask_b32_e64 v245, v105, v104, s[88:89]
	v_min_u32_e32 v106, v247, v3
	v_max_u32_e32 v107, v247, v3
	v_cndmask_b32_e64 v247, v107, v106, s[88:89]
	v_min_u32_e32 v104, v242, v4
	v_max_u32_e32 v105, v242, v4
	v_cndmask_b32_e64 v242, v105, v104, s[88:89]
	v_min_u32_e32 v106, v244, v5
	v_max_u32_e32 v107, v244, v5
	v_cndmask_b32_e64 v244, v107, v106, s[88:89]
	v_min_u32_e32 v104, v246, v6
	v_max_u32_e32 v105, v246, v6
	v_cndmask_b32_e64 v246, v105, v104, s[88:89]
	v_min_u32_e32 v106, v248, v7
	v_max_u32_e32 v107, v248, v7
	v_cndmask_b32_e64 v248, v107, v106, s[88:89]
	v_mov_b32_e32 v117, 0
	s_lshl_b32 s98, s2, 11
	s_add_u32 s98, s98, s101
	v_add_u32_e32 v116, s98, v234
	v_lshl_add_u32 v119, v235, 2, v237
	v_add_u32_e32 v119, s98, v119
	ds_write_b32 v119, v241 offset:0
	ds_write_b32 v119, v242 offset:32
	ds_write_b32 v119, v243 offset:512
	ds_write_b32 v119, v244 offset:544
	ds_write_b32 v119, v245 offset:1024
	ds_write_b32 v119, v246 offset:1056
	ds_write_b32 v119, v247 offset:1536
	ds_write_b32 v119, v248 offset:1568
	v_add_u32_e32 v118, 0x10000, v116
	ds_write_b32 v118, v117 offset:0
	ds_write_b32 v118, v117 offset:256
	ds_write_b32 v118, v117 offset:512
	ds_write_b32 v118, v117 offset:768
	ds_write_b32 v118, v117 offset:1024
	ds_write_b32 v118, v117 offset:1280
	ds_write_b32 v118, v117 offset:1536
	ds_write_b32 v118, v117 offset:1792
	s_add_u32 s2, s2, 1
	s_cmp_lt_u32 s2, 4
	s_cbranch_scc1 .Lpg0_p0
; #define PG_ISSUE(BUF, TAB, e0_) do { const int isrc_ = ((e0_) < 64) ? myi0 : myi1; \
;       _Pragma("unroll") for (int e = 0; e < 8; ++e) { const int idx_ = __builtin_amdgcn_readlane(isrc_, ((e0_) + e) & 63); \
;         BUF[e] = *(const u32x4*)((TAB) + (size_t)idx_ * 1024 + lane * 16); } } while (0)
; DEV void peer_gather(const Params& P, int l, int m0, const int* idxs, const float* gs) {
;     ...
;     PG_ISSUE(b0, U, 0);
; #pragma nounroll
;     for (int e0 = 0; e0 < 128; e0 += 16) {
;       PG_ISSUE(b1, U, e0 + 8);
;       PG_U8(b0, 0, e0);
;       if (e0 + 16 < 128) PG_ISSUE(b0, U, e0 + 16); else PG_ISSUE(b0, V, 0);
;       PG_U8(b1, 0, e0 + 8);
	s_waitcnt lgkmcnt(0)
	v_readfirstlane_b32 s82, v128
	v_readfirstlane_b32 s83, v129
	s_nop 4
	v_readfirstlane_b32 s80, v124
	v_readfirstlane_b32 s81, v125
	s_nop 4
	s_mov_b32 s2, 0xffffff80
	s_mov_b32 s86, 0xcccccccc
	s_mov_b32 s87, 0xcccccccc
	s_mov_b32 s88, 0xaaaaaaaa
	s_mov_b32 s89, 0xaaaaaaaa
	s_mov_b32 s90, 0xf0f0f0f0
	s_mov_b32 s91, 0xf0f0f0f0
	s_lshl_b32 vcc_lo, s3, 11
	s_add_u32 s82, s82, vcc_lo
	s_addc_u32 s83, s83, 0
	v_lshl_add_u32 v246, v237, 4, s101
	v_lshrrev_b32_e32 v247, 2, v235
	v_add_u32_e32 v247, v247, v246
	v_add_u32_e32 v247, 0x10000, v247
	s_mov_b32 s100, 0
	s_mov_b32 s98, 0
	s_mov_b32 s99, 0
	s_lshl3_add_u32 vcc_lo, s98, s99
	v_lshl_add_u32 v119, vcc_lo, 8, v236
	global_load_dwordx4 v[80:83], v119, s[82:83]
	global_load_dwordx4 v[84:87], v119, s[82:83] offset:16
	v_lshl_add_u32 v116, s98, 9, v246
	ds_read_b128 v[112:115], v116
	ds_read_b128 v[138:141], v116 offset:16
	ds_read_b128 v[250:253], v116 offset:32
	ds_read_b128 v[242:245], v116 offset:48
	v_lshl_or_b32 v240, s99, 21, v235
	s_waitcnt lgkmcnt(0)
	v_and_or_b32 v112, v112, s2, v240
	v_and_or_b32 v113, v113, s2, v240
	global_load_dwordx4 v[0:3], v112, s[80:81]
	global_load_dwordx4 v[4:7], v113, s[80:81]
	v_and_or_b32 v114, v114, s2, v240
	v_and_or_b32 v115, v115, s2, v240
	global_load_dwordx4 v[8:11], v114, s[80:81]
	global_load_dwordx4 v[12:15], v115, s[80:81]
	v_and_or_b32 v138, v138, s2, v240
	v_and_or_b32 v139, v139, s2, v240
	global_load_dwordx4 v[16:19], v138, s[80:81]
	global_load_dwordx4 v[20:23], v139, s[80:81]
	v_and_or_b32 v140, v140, s2, v240
	v_and_or_b32 v141, v141, s2, v240
	global_load_dwordx4 v[24:27], v140, s[80:81]
	global_load_dwordx4 v[28:31], v141, s[80:81]
	v_and_or_b32 v250, v250, s2, v240
	v_and_or_b32 v251, v251, s2, v240
	global_load_dwordx4 v[32:35], v250, s[80:81]
	global_load_dwordx4 v[36:39], v251, s[80:81]
	v_and_or_b32 v252, v252, s2, v240
	v_and_or_b32 v253, v253, s2, v240
	global_load_dwordx4 v[40:43], v252, s[80:81]
	global_load_dwordx4 v[44:47], v253, s[80:81]
	v_and_or_b32 v242, v242, s2, v240
	v_and_or_b32 v243, v243, s2, v240
	global_load_dwordx4 v[48:51], v242, s[80:81]
	global_load_dwordx4 v[52:55], v243, s[80:81]
	v_and_or_b32 v244, v244, s2, v240
	v_and_or_b32 v245, v245, s2, v240
	global_load_dwordx4 v[56:59], v244, s[80:81]
	global_load_dwordx4 v[60:63], v245, s[80:81]
	s_mov_b32 s92, 1
	v_lshl_add_u32 v116, s92, 9, v246
	ds_read_b128 v[112:115], v116
	ds_read_b128 v[138:141], v116 offset:16
	ds_read_b128 v[250:253], v116 offset:32
	ds_read_b128 v[242:245], v116 offset:48
.Lpg0_uloop:
	s_and_b32 s98, s100, 15
	s_add_u32 s92, s100, 1
	s_min_u32 s92, s92, 127
	s_lshr_b32 s93, s92, 4
	s_and_b32 s92, s92, 15
	s_waitcnt vmcnt(16) lgkmcnt(0)
	v_mov_b32_e32 v64, v80
	v_mov_b32_e32 v65, v81
	v_mov_b32_e32 v66, v82
	v_mov_b32_e32 v67, v83
	v_mov_b32_e32 v68, v84
	v_mov_b32_e32 v69, v85
	v_mov_b32_e32 v70, v86
	v_mov_b32_e32 v71, v87
	s_lshl3_add_u32 vcc_lo, s92, s93
	v_lshl_add_u32 v119, vcc_lo, 8, v236
	global_load_dwordx4 v[80:83], v119, s[82:83]
	global_load_dwordx4 v[84:87], v119, s[82:83] offset:16
	v_lshl_or_b32 v240, s93, 21, v235
	s_waitcnt vmcnt(16)
	v_cvt_scalef32_pk_bf16_fp8 v104, v0, 1.0
	v_cvt_scalef32_pk_bf16_fp8 v105, v0, 1.0 op_sel:[1,0,0]
	v_cvt_scalef32_pk_bf16_fp8 v106, v4, 1.0
	v_cvt_scalef32_pk_bf16_fp8 v107, v4, 1.0 op_sel:[1,0,0]
	v_cvt_scalef32_pk_bf16_fp8 v108, v1, 1.0
	v_cvt_scalef32_pk_bf16_fp8 v109, v1, 1.0 op_sel:[1,0,0]
	v_mfma_f32_4x4x4_16b_bf16 v[72:75], v[104:105], v[64:65], 0
	v_cvt_scalef32_pk_bf16_fp8 v110, v5, 1.0
	v_cvt_scalef32_pk_bf16_fp8 v111, v5, 1.0 op_sel:[1,0,0]
	v_mfma_f32_4x4x4_16b_bf16 v[76:79], v[106:107], v[64:65], 0
	v_cvt_scalef32_pk_bf16_fp8 v104, v2, 1.0
	v_cvt_scalef32_pk_bf16_fp8 v105, v2, 1.0 op_sel:[1,0,0]
	v_mfma_f32_4x4x4_16b_bf16 v[72:75], v[108:109], v[66:67], v[72:75]
	v_cvt_scalef32_pk_bf16_fp8 v106, v6, 1.0
	v_cvt_scalef32_pk_bf16_fp8 v107, v6, 1.0 op_sel:[1,0,0]
	v_mfma_f32_4x4x4_16b_bf16 v[76:79], v[110:111], v[66:67], v[76:79]
	v_cvt_scalef32_pk_bf16_fp8 v108, v3, 1.0
	v_cvt_scalef32_pk_bf16_fp8 v109, v3, 1.0 op_sel:[1,0,0]
	v_mfma_f32_4x4x4_16b_bf16 v[72:75], v[104:105], v[68:69], v[72:75]
	v_cvt_scalef32_pk_bf16_fp8 v110, v7, 1.0
	v_cvt_scalef32_pk_bf16_fp8 v111, v7, 1.0 op_sel:[1,0,0]
	v_mfma_f32_4x4x4_16b_bf16 v[76:79], v[106:107], v[68:69], v[76:79]
	v_and_or_b32 v112, v112, s2, v240
	v_and_or_b32 v113, v113, s2, v240
	global_load_dwordx4 v[0:3], v112, s[80:81]
	global_load_dwordx4 v[4:7], v113, s[80:81]
	s_waitcnt vmcnt(16)
	v_cvt_scalef32_pk_bf16_fp8 v104, v8, 1.0
	v_cvt_scalef32_pk_bf16_fp8 v105, v8, 1.0 op_sel:[1,0,0]
	v_mfma_f32_4x4x4_16b_bf16 v[72:75], v[108:109], v[70:71], v[72:75]
	v_cvt_scalef32_pk_bf16_fp8 v106, v12, 1.0
	v_cvt_scalef32_pk_bf16_fp8 v107, v12, 1.0 op_sel:[1,0,0]
	v_mfma_f32_4x4x4_16b_bf16 v[76:79], v[110:111], v[70:71], v[76:79]
	v_cvt_scalef32_pk_bf16_fp8 v108, v9, 1.0
	v_cvt_scalef32_pk_bf16_fp8 v109, v9, 1.0 op_sel:[1,0,0]
	v_cvt_scalef32_pk_bf16_fp8 v110, v13, 1.0
	v_cvt_scalef32_pk_bf16_fp8 v111, v13, 1.0 op_sel:[1,0,0]
	v_add_f32_dpp v148, v73, v72 quad_perm:[1,0,3,2] row_mask:0xf bank_mask:0xf
	v_add_f32_dpp v149, v75, v74 quad_perm:[1,0,3,2] row_mask:0xf bank_mask:0xf
	v_add_f32_dpp v150, v76, v77 quad_perm:[1,0,3,2] row_mask:0xf bank_mask:0xf
	v_add_f32_dpp v151, v78, v79 quad_perm:[1,0,3,2] row_mask:0xf bank_mask:0xf
	v_mfma_f32_4x4x4_16b_bf16 v[72:75], v[104:105], v[64:65], 0
	v_add_f32_dpp v88, v149, v148 quad_perm:[2,3,0,1] row_mask:0xf bank_mask:0xf
	v_mfma_f32_4x4x4_16b_bf16 v[76:79], v[106:107], v[64:65], 0
	v_add_f32_dpp v89, v151, v150 quad_perm:[2,3,0,1] row_mask:0xf bank_mask:0xf
	v_cvt_scalef32_pk_bf16_fp8 v104, v10, 1.0
	v_cvt_scalef32_pk_bf16_fp8 v105, v10, 1.0 op_sel:[1,0,0]
	v_mfma_f32_4x4x4_16b_bf16 v[72:75], v[108:109], v[66:67], v[72:75]
	v_cvt_scalef32_pk_bf16_fp8 v106, v14, 1.0
	v_cvt_scalef32_pk_bf16_fp8 v107, v14, 1.0 op_sel:[1,0,0]
	v_mfma_f32_4x4x4_16b_bf16 v[76:79], v[110:111], v[66:67], v[76:79]
	v_cvt_scalef32_pk_bf16_fp8 v108, v11, 1.0
	v_cvt_scalef32_pk_bf16_fp8 v109, v11, 1.0 op_sel:[1,0,0]
	v_mfma_f32_4x4x4_16b_bf16 v[72:75], v[104:105], v[68:69], v[72:75]
	v_cvt_scalef32_pk_bf16_fp8 v110, v15, 1.0
	v_cvt_scalef32_pk_bf16_fp8 v111, v15, 1.0 op_sel:[1,0,0]
	v_mfma_f32_4x4x4_16b_bf16 v[76:79], v[106:107], v[68:69], v[76:79]
	v_and_or_b32 v114, v114, s2, v240
	v_and_or_b32 v115, v115, s2, v240
	global_load_dwordx4 v[8:11], v114, s[80:81]
	global_load_dwordx4 v[12:15], v115, s[80:81]
	s_waitcnt vmcnt(16)
	v_cvt_scalef32_pk_bf16_fp8 v104, v16, 1.0
	v_cvt_scalef32_pk_bf16_fp8 v105, v16, 1.0 op_sel:[1,0,0]
	v_mfma_f32_4x4x4_16b_bf16 v[72:75], v[108:109], v[70:71], v[72:75]
	v_cvt_scalef32_pk_bf16_fp8 v106, v20, 1.0
	v_cvt_scalef32_pk_bf16_fp8 v107, v20, 1.0 op_sel:[1,0,0]
	v_mfma_f32_4x4x4_16b_bf16 v[76:79], v[110:111], v[70:71], v[76:79]
	v_cvt_scalef32_pk_bf16_fp8 v108, v17, 1.0
	v_cvt_scalef32_pk_bf16_fp8 v109, v17, 1.0 op_sel:[1,0,0]
	v_cvt_scalef32_pk_bf16_fp8 v110, v21, 1.0
	v_cvt_scalef32_pk_bf16_fp8 v111, v21, 1.0 op_sel:[1,0,0]
	v_add_f32_dpp v148, v75, v74 quad_perm:[1,0,3,2] row_mask:0xf bank_mask:0xf
	v_add_f32_dpp v149, v73, v72 quad_perm:[1,0,3,2] row_mask:0xf bank_mask:0xf
	v_add_f32_dpp v150, v78, v79 quad_perm:[1,0,3,2] row_mask:0xf bank_mask:0xf
	v_add_f32_dpp v151, v76, v77 quad_perm:[1,0,3,2] row_mask:0xf bank_mask:0xf
	v_mfma_f32_4x4x4_16b_bf16 v[72:75], v[104:105], v[64:65], 0
	v_add_f32_dpp v90, v149, v148 quad_perm:[2,3,0,1] row_mask:0xf bank_mask:0xf
	v_mfma_f32_4x4x4_16b_bf16 v[76:79], v[106:107], v[64:65], 0
	v_add_f32_dpp v91, v151, v150 quad_perm:[2,3,0,1] row_mask:0xf bank_mask:0xf
	v_cvt_scalef32_pk_bf16_fp8 v104, v18, 1.0
	v_cvt_scalef32_pk_bf16_fp8 v105, v18, 1.0 op_sel:[1,0,0]
	v_mfma_f32_4x4x4_16b_bf16 v[72:75], v[108:109], v[66:67], v[72:75]
	v_cvt_scalef32_pk_bf16_fp8 v106, v22, 1.0
	v_cvt_scalef32_pk_bf16_fp8 v107, v22, 1.0 op_sel:[1,0,0]
	v_mfma_f32_4x4x4_16b_bf16 v[76:79], v[110:111], v[66:67], v[76:79]
	v_cvt_scalef32_pk_bf16_fp8 v108, v19, 1.0
	v_cvt_scalef32_pk_bf16_fp8 v109, v19, 1.0 op_sel:[1,0,0]
	v_mfma_f32_4x4x4_16b_bf16 v[72:75], v[104:105], v[68:69], v[72:75]
	v_cvt_scalef32_pk_bf16_fp8 v110, v23, 1.0
	v_cvt_scalef32_pk_bf16_fp8 v111, v23, 1.0 op_sel:[1,0,0]
	v_mfma_f32_4x4x4_16b_bf16 v[76:79], v[106:107], v[68:69], v[76:79]
	v_and_or_b32 v138, v138, s2, v240
	v_and_or_b32 v139, v139, s2, v240
	global_load_dwordx4 v[16:19], v138, s[80:81]
	global_load_dwordx4 v[20:23], v139, s[80:81]
	s_waitcnt vmcnt(16)
	v_cvt_scalef32_pk_bf16_fp8 v104, v24, 1.0
	v_cvt_scalef32_pk_bf16_fp8 v105, v24, 1.0 op_sel:[1,0,0]
	v_mfma_f32_4x4x4_16b_bf16 v[72:75], v[108:109], v[70:71], v[72:75]
	v_cvt_scalef32_pk_bf16_fp8 v106, v28, 1.0
	v_cvt_scalef32_pk_bf16_fp8 v107, v28, 1.0 op_sel:[1,0,0]
	v_mfma_f32_4x4x4_16b_bf16 v[76:79], v[110:111], v[70:71], v[76:79]
	v_cvt_scalef32_pk_bf16_fp8 v108, v25, 1.0
	v_cvt_scalef32_pk_bf16_fp8 v109, v25, 1.0 op_sel:[1,0,0]
	v_cvt_scalef32_pk_bf16_fp8 v110, v29, 1.0
	v_cvt_scalef32_pk_bf16_fp8 v111, v29, 1.0 op_sel:[1,0,0]
	v_add_f32_dpp v148, v73, v72 quad_perm:[1,0,3,2] row_mask:0xf bank_mask:0xf
	v_add_f32_dpp v149, v75, v74 quad_perm:[1,0,3,2] row_mask:0xf bank_mask:0xf
	v_add_f32_dpp v150, v76, v77 quad_perm:[1,0,3,2] row_mask:0xf bank_mask:0xf
	v_add_f32_dpp v151, v78, v79 quad_perm:[1,0,3,2] row_mask:0xf bank_mask:0xf
	v_mfma_f32_4x4x4_16b_bf16 v[72:75], v[104:105], v[64:65], 0
	v_add_f32_dpp v92, v149, v148 quad_perm:[2,3,0,1] row_mask:0xf bank_mask:0xf
	v_mfma_f32_4x4x4_16b_bf16 v[76:79], v[106:107], v[64:65], 0
	v_add_f32_dpp v93, v151, v150 quad_perm:[2,3,0,1] row_mask:0xf bank_mask:0xf
	v_cvt_scalef32_pk_bf16_fp8 v104, v26, 1.0
	v_cvt_scalef32_pk_bf16_fp8 v105, v26, 1.0 op_sel:[1,0,0]
	v_mfma_f32_4x4x4_16b_bf16 v[72:75], v[108:109], v[66:67], v[72:75]
	v_cvt_scalef32_pk_bf16_fp8 v106, v30, 1.0
	v_cvt_scalef32_pk_bf16_fp8 v107, v30, 1.0 op_sel:[1,0,0]
	v_mfma_f32_4x4x4_16b_bf16 v[76:79], v[110:111], v[66:67], v[76:79]
	v_cvt_scalef32_pk_bf16_fp8 v108, v27, 1.0
	v_cvt_scalef32_pk_bf16_fp8 v109, v27, 1.0 op_sel:[1,0,0]
	v_mfma_f32_4x4x4_16b_bf16 v[72:75], v[104:105], v[68:69], v[72:75]
	v_cvt_scalef32_pk_bf16_fp8 v110, v31, 1.0
	v_cvt_scalef32_pk_bf16_fp8 v111, v31, 1.0 op_sel:[1,0,0]
	v_mfma_f32_4x4x4_16b_bf16 v[76:79], v[106:107], v[68:69], v[76:79]
	v_and_or_b32 v140, v140, s2, v240
	v_and_or_b32 v141, v141, s2, v240
	global_load_dwordx4 v[24:27], v140, s[80:81]
	global_load_dwordx4 v[28:31], v141, s[80:81]
	s_waitcnt vmcnt(16)
	v_cvt_scalef32_pk_bf16_fp8 v104, v32, 1.0
	v_cvt_scalef32_pk_bf16_fp8 v105, v32, 1.0 op_sel:[1,0,0]
	v_mfma_f32_4x4x4_16b_bf16 v[72:75], v[108:109], v[70:71], v[72:75]
	v_cvt_scalef32_pk_bf16_fp8 v106, v36, 1.0
	v_cvt_scalef32_pk_bf16_fp8 v107, v36, 1.0 op_sel:[1,0,0]
	v_mfma_f32_4x4x4_16b_bf16 v[76:79], v[110:111], v[70:71], v[76:79]
	v_cvt_scalef32_pk_bf16_fp8 v108, v33, 1.0
	v_cvt_scalef32_pk_bf16_fp8 v109, v33, 1.0 op_sel:[1,0,0]
	v_cvt_scalef32_pk_bf16_fp8 v110, v37, 1.0
	v_cvt_scalef32_pk_bf16_fp8 v111, v37, 1.0 op_sel:[1,0,0]
	v_add_f32_dpp v148, v75, v74 quad_perm:[1,0,3,2] row_mask:0xf bank_mask:0xf
	v_add_f32_dpp v149, v73, v72 quad_perm:[1,0,3,2] row_mask:0xf bank_mask:0xf
	v_add_f32_dpp v150, v78, v79 quad_perm:[1,0,3,2] row_mask:0xf bank_mask:0xf
	v_add_f32_dpp v151, v76, v77 quad_perm:[1,0,3,2] row_mask:0xf bank_mask:0xf
	v_mfma_f32_4x4x4_16b_bf16 v[72:75], v[104:105], v[64:65], 0
	v_add_f32_dpp v94, v149, v148 quad_perm:[2,3,0,1] row_mask:0xf bank_mask:0xf
	v_mfma_f32_4x4x4_16b_bf16 v[76:79], v[106:107], v[64:65], 0
	v_add_f32_dpp v95, v151, v150 quad_perm:[2,3,0,1] row_mask:0xf bank_mask:0xf
	v_cvt_scalef32_pk_bf16_fp8 v104, v34, 1.0
	v_cvt_scalef32_pk_bf16_fp8 v105, v34, 1.0 op_sel:[1,0,0]
	v_mfma_f32_4x4x4_16b_bf16 v[72:75], v[108:109], v[66:67], v[72:75]
	v_cvt_scalef32_pk_bf16_fp8 v106, v38, 1.0
	v_cvt_scalef32_pk_bf16_fp8 v107, v38, 1.0 op_sel:[1,0,0]
	v_mfma_f32_4x4x4_16b_bf16 v[76:79], v[110:111], v[66:67], v[76:79]
	v_cvt_scalef32_pk_bf16_fp8 v108, v35, 1.0
	v_cvt_scalef32_pk_bf16_fp8 v109, v35, 1.0 op_sel:[1,0,0]
	v_mfma_f32_4x4x4_16b_bf16 v[72:75], v[104:105], v[68:69], v[72:75]
	v_cvt_scalef32_pk_bf16_fp8 v110, v39, 1.0
	v_cvt_scalef32_pk_bf16_fp8 v111, v39, 1.0 op_sel:[1,0,0]
	v_mfma_f32_4x4x4_16b_bf16 v[76:79], v[106:107], v[68:69], v[76:79]
	v_and_or_b32 v250, v250, s2, v240
	v_and_or_b32 v251, v251, s2, v240
	global_load_dwordx4 v[32:35], v250, s[80:81]
	global_load_dwordx4 v[36:39], v251, s[80:81]
	s_waitcnt vmcnt(16)
	v_cvt_scalef32_pk_bf16_fp8 v104, v40, 1.0
	v_cvt_scalef32_pk_bf16_fp8 v105, v40, 1.0 op_sel:[1,0,0]
	v_mfma_f32_4x4x4_16b_bf16 v[72:75], v[108:109], v[70:71], v[72:75]
	v_cvt_scalef32_pk_bf16_fp8 v106, v44, 1.0
	v_cvt_scalef32_pk_bf16_fp8 v107, v44, 1.0 op_sel:[1,0,0]
	v_mfma_f32_4x4x4_16b_bf16 v[76:79], v[110:111], v[70:71], v[76:79]
	v_cvt_scalef32_pk_bf16_fp8 v108, v41, 1.0
	v_cvt_scalef32_pk_bf16_fp8 v109, v41, 1.0 op_sel:[1,0,0]
	v_cvt_scalef32_pk_bf16_fp8 v110, v45, 1.0
	v_cvt_scalef32_pk_bf16_fp8 v111, v45, 1.0 op_sel:[1,0,0]
	v_add_f32_dpp v148, v73, v72 quad_perm:[1,0,3,2] row_mask:0xf bank_mask:0xf
	v_add_f32_dpp v149, v75, v74 quad_perm:[1,0,3,2] row_mask:0xf bank_mask:0xf
	v_add_f32_dpp v150, v76, v77 quad_perm:[1,0,3,2] row_mask:0xf bank_mask:0xf
	v_add_f32_dpp v151, v78, v79 quad_perm:[1,0,3,2] row_mask:0xf bank_mask:0xf
	v_mfma_f32_4x4x4_16b_bf16 v[72:75], v[104:105], v[64:65], 0
	v_add_f32_dpp v96, v149, v148 quad_perm:[2,3,0,1] row_mask:0xf bank_mask:0xf
	v_mfma_f32_4x4x4_16b_bf16 v[76:79], v[106:107], v[64:65], 0
	v_add_f32_dpp v97, v151, v150 quad_perm:[2,3,0,1] row_mask:0xf bank_mask:0xf
	v_cvt_scalef32_pk_bf16_fp8 v104, v42, 1.0
	v_cvt_scalef32_pk_bf16_fp8 v105, v42, 1.0 op_sel:[1,0,0]
	v_mfma_f32_4x4x4_16b_bf16 v[72:75], v[108:109], v[66:67], v[72:75]
	v_cvt_scalef32_pk_bf16_fp8 v106, v46, 1.0
	v_cvt_scalef32_pk_bf16_fp8 v107, v46, 1.0 op_sel:[1,0,0]
	v_mfma_f32_4x4x4_16b_bf16 v[76:79], v[110:111], v[66:67], v[76:79]
	v_cvt_scalef32_pk_bf16_fp8 v108, v43, 1.0
	v_cvt_scalef32_pk_bf16_fp8 v109, v43, 1.0 op_sel:[1,0,0]
	v_mfma_f32_4x4x4_16b_bf16 v[72:75], v[104:105], v[68:69], v[72:75]
	v_cvt_scalef32_pk_bf16_fp8 v110, v47, 1.0
	v_cvt_scalef32_pk_bf16_fp8 v111, v47, 1.0 op_sel:[1,0,0]
	v_mfma_f32_4x4x4_16b_bf16 v[76:79], v[106:107], v[68:69], v[76:79]
	v_and_or_b32 v252, v252, s2, v240
	v_and_or_b32 v253, v253, s2, v240
	global_load_dwordx4 v[40:43], v252, s[80:81]
	global_load_dwordx4 v[44:47], v253, s[80:81]
	s_waitcnt vmcnt(16)
	v_cvt_scalef32_pk_bf16_fp8 v104, v48, 1.0
	v_cvt_scalef32_pk_bf16_fp8 v105, v48, 1.0 op_sel:[1,0,0]
	v_mfma_f32_4x4x4_16b_bf16 v[72:75], v[108:109], v[70:71], v[72:75]
	v_cvt_scalef32_pk_bf16_fp8 v106, v52, 1.0
	v_cvt_scalef32_pk_bf16_fp8 v107, v52, 1.0 op_sel:[1,0,0]
	v_mfma_f32_4x4x4_16b_bf16 v[76:79], v[110:111], v[70:71], v[76:79]
	v_cvt_scalef32_pk_bf16_fp8 v108, v49, 1.0
	v_cvt_scalef32_pk_bf16_fp8 v109, v49, 1.0 op_sel:[1,0,0]
	v_cvt_scalef32_pk_bf16_fp8 v110, v53, 1.0
	v_cvt_scalef32_pk_bf16_fp8 v111, v53, 1.0 op_sel:[1,0,0]
	v_add_f32_dpp v148, v75, v74 quad_perm:[1,0,3,2] row_mask:0xf bank_mask:0xf
	v_add_f32_dpp v149, v73, v72 quad_perm:[1,0,3,2] row_mask:0xf bank_mask:0xf
	v_add_f32_dpp v150, v78, v79 quad_perm:[1,0,3,2] row_mask:0xf bank_mask:0xf
	v_add_f32_dpp v151, v76, v77 quad_perm:[1,0,3,2] row_mask:0xf bank_mask:0xf
	v_mfma_f32_4x4x4_16b_bf16 v[72:75], v[104:105], v[64:65], 0
	v_add_f32_dpp v98, v149, v148 quad_perm:[2,3,0,1] row_mask:0xf bank_mask:0xf
	v_mfma_f32_4x4x4_16b_bf16 v[76:79], v[106:107], v[64:65], 0
	v_add_f32_dpp v99, v151, v150 quad_perm:[2,3,0,1] row_mask:0xf bank_mask:0xf
	v_cvt_scalef32_pk_bf16_fp8 v104, v50, 1.0
	v_cvt_scalef32_pk_bf16_fp8 v105, v50, 1.0 op_sel:[1,0,0]
	v_mfma_f32_4x4x4_16b_bf16 v[72:75], v[108:109], v[66:67], v[72:75]
	v_cvt_scalef32_pk_bf16_fp8 v106, v54, 1.0
	v_cvt_scalef32_pk_bf16_fp8 v107, v54, 1.0 op_sel:[1,0,0]
	v_mfma_f32_4x4x4_16b_bf16 v[76:79], v[110:111], v[66:67], v[76:79]
	v_cvt_scalef32_pk_bf16_fp8 v108, v51, 1.0
	v_cvt_scalef32_pk_bf16_fp8 v109, v51, 1.0 op_sel:[1,0,0]
	v_mfma_f32_4x4x4_16b_bf16 v[72:75], v[104:105], v[68:69], v[72:75]
	v_cvt_scalef32_pk_bf16_fp8 v110, v55, 1.0
	v_cvt_scalef32_pk_bf16_fp8 v111, v55, 1.0 op_sel:[1,0,0]
	v_mfma_f32_4x4x4_16b_bf16 v[76:79], v[106:107], v[68:69], v[76:79]
	v_and_or_b32 v242, v242, s2, v240
	v_and_or_b32 v243, v243, s2, v240
	global_load_dwordx4 v[48:51], v242, s[80:81]
	global_load_dwordx4 v[52:55], v243, s[80:81]
	s_waitcnt vmcnt(16)
	v_cvt_scalef32_pk_bf16_fp8 v104, v56, 1.0
	v_cvt_scalef32_pk_bf16_fp8 v105, v56, 1.0 op_sel:[1,0,0]
	v_mfma_f32_4x4x4_16b_bf16 v[72:75], v[108:109], v[70:71], v[72:75]
	v_cvt_scalef32_pk_bf16_fp8 v106, v60, 1.0
	v_cvt_scalef32_pk_bf16_fp8 v107, v60, 1.0 op_sel:[1,0,0]
	v_mfma_f32_4x4x4_16b_bf16 v[76:79], v[110:111], v[70:71], v[76:79]
	v_cvt_scalef32_pk_bf16_fp8 v108, v57, 1.0
	v_cvt_scalef32_pk_bf16_fp8 v109, v57, 1.0 op_sel:[1,0,0]
	v_cvt_scalef32_pk_bf16_fp8 v110, v61, 1.0
	v_cvt_scalef32_pk_bf16_fp8 v111, v61, 1.0 op_sel:[1,0,0]
	v_add_f32_dpp v148, v73, v72 quad_perm:[1,0,3,2] row_mask:0xf bank_mask:0xf
	v_add_f32_dpp v149, v75, v74 quad_perm:[1,0,3,2] row_mask:0xf bank_mask:0xf
	v_add_f32_dpp v150, v76, v77 quad_perm:[1,0,3,2] row_mask:0xf bank_mask:0xf
	v_add_f32_dpp v151, v78, v79 quad_perm:[1,0,3,2] row_mask:0xf bank_mask:0xf
	v_mfma_f32_4x4x4_16b_bf16 v[72:75], v[104:105], v[64:65], 0
	v_add_f32_dpp v100, v149, v148 quad_perm:[2,3,0,1] row_mask:0xf bank_mask:0xf
	v_mfma_f32_4x4x4_16b_bf16 v[76:79], v[106:107], v[64:65], 0
	v_add_f32_dpp v101, v151, v150 quad_perm:[2,3,0,1] row_mask:0xf bank_mask:0xf
	v_cvt_scalef32_pk_bf16_fp8 v104, v58, 1.0
	v_cvt_scalef32_pk_bf16_fp8 v105, v58, 1.0 op_sel:[1,0,0]
	v_mfma_f32_4x4x4_16b_bf16 v[72:75], v[108:109], v[66:67], v[72:75]
	v_cvt_scalef32_pk_bf16_fp8 v106, v62, 1.0
	v_cvt_scalef32_pk_bf16_fp8 v107, v62, 1.0 op_sel:[1,0,0]
	v_mfma_f32_4x4x4_16b_bf16 v[76:79], v[110:111], v[66:67], v[76:79]
	v_cvt_scalef32_pk_bf16_fp8 v108, v59, 1.0
	v_cvt_scalef32_pk_bf16_fp8 v109, v59, 1.0 op_sel:[1,0,0]
	v_mfma_f32_4x4x4_16b_bf16 v[72:75], v[104:105], v[68:69], v[72:75]
	v_cvt_scalef32_pk_bf16_fp8 v110, v63, 1.0
	v_cvt_scalef32_pk_bf16_fp8 v111, v63, 1.0 op_sel:[1,0,0]
	v_mfma_f32_4x4x4_16b_bf16 v[76:79], v[106:107], v[68:69], v[76:79]
	v_and_or_b32 v244, v244, s2, v240
	v_and_or_b32 v245, v245, s2, v240
	global_load_dwordx4 v[56:59], v244, s[80:81]
	global_load_dwordx4 v[60:63], v245, s[80:81]
	v_mfma_f32_4x4x4_16b_bf16 v[72:75], v[108:109], v[70:71], v[72:75]
	v_mfma_f32_4x4x4_16b_bf16 v[76:79], v[110:111], v[70:71], v[76:79]
	s_add_u32 s92, s100, 2
	s_and_b32 s92, s92, 15
	v_lshl_add_u32 v116, s92, 9, v246
	ds_read_b128 v[112:115], v116
	ds_read_b128 v[138:141], v116 offset:16
	ds_read_b128 v[250:253], v116 offset:32
	ds_read_b128 v[242:245], v116 offset:48
	v_lshl_add_u32 v117, s98, 9, v247
	ds_read_b32 v136, v117
	ds_read_b32 v137, v117 offset:32
	v_add_f32_dpp v148, v75, v74 quad_perm:[1,0,3,2] row_mask:0xf bank_mask:0xf
	v_add_f32_dpp v149, v73, v72 quad_perm:[1,0,3,2] row_mask:0xf bank_mask:0xf
	v_add_f32_dpp v150, v78, v79 quad_perm:[1,0,3,2] row_mask:0xf bank_mask:0xf
	v_add_f32_dpp v151, v76, v77 quad_perm:[1,0,3,2] row_mask:0xf bank_mask:0xf
	v_add_f32_dpp v102, v149, v148 quad_perm:[2,3,0,1] row_mask:0xf bank_mask:0xf
	s_nop 0
	v_add_f32_dpp v103, v151, v150 quad_perm:[2,3,0,1] row_mask:0xf bank_mask:0xf
	v_cndmask_b32_e64 v144, v88, v89, s[88:89]
	v_cndmask_b32_e64 v145, v90, v91, s[88:89]
	v_cndmask_b32_e64 v88, v144, v145, s[86:87]
	v_cndmask_b32_e64 v144, v92, v93, s[88:89]
	v_cndmask_b32_e64 v145, v94, v95, s[88:89]
	v_cndmask_b32_e64 v92, v144, v145, s[86:87]
	v_cndmask_b32_e64 v144, v96, v97, s[88:89]
	v_cndmask_b32_e64 v145, v98, v99, s[88:89]
	v_cndmask_b32_e64 v96, v144, v145, s[86:87]
	v_cndmask_b32_e64 v144, v100, v101, s[88:89]
	v_cndmask_b32_e64 v145, v102, v103, s[88:89]
	v_cndmask_b32_e64 v100, v144, v145, s[86:87]
	v_cndmask_b32_e64 v144, v88, v92, s[90:91]
	v_cndmask_b32_e64 v145, v92, v88, s[90:91]
	v_cndmask_b32_e64 v146, v96, v100, s[90:91]
	v_cndmask_b32_e64 v147, v100, v96, s[90:91]
	s_nop 1
	v_add_f32_dpp v88, v145, v144 row_shl:4 row_mask:0xf bank_mask:0x5
	v_add_f32_dpp v88, v145, v144 row_shr:4 row_mask:0xf bank_mask:0xa
	v_add_f32_dpp v96, v147, v146 row_shl:4 row_mask:0xf bank_mask:0x5
	v_add_f32_dpp v96, v147, v146 row_shr:4 row_mask:0xf bank_mask:0xa
	s_waitcnt lgkmcnt(0)
	v_add_f32_e32 v136, v136, v88
	v_add_f32_e32 v137, v137, v96
	ds_write_b32 v117, v136
	ds_write_b32 v117, v137 offset:32
	s_add_u32 s100, s100, 1
	s_cmp_lt_u32 s100, 128
	s_cbranch_scc1 .Lpg0_uloop
	s_waitcnt vmcnt(0) lgkmcnt(0)
	s_mov_b32 s2, 0
.Lpg0_act:
	v_readlane_b32 s82, v231, 28
	v_readlane_b32 s83, v231, 29
	s_nop 4
	s_lshl_b32 s98, s2, 11
	s_add_u32 s98, s98, s101
	v_add_u32_e32 v116, s98, v234
	v_add_u32_e32 v117, 0x10000, v116
	ds_read_b32 v0, v116 offset:0
	ds_read_b32 v8, v117 offset:0
	ds_read_b32 v1, v116 offset:256
	ds_read_b32 v9, v117 offset:256
	ds_read_b32 v2, v116 offset:512
	ds_read_b32 v10, v117 offset:512
	ds_read_b32 v3, v116 offset:768
	ds_read_b32 v11, v117 offset:768
	ds_read_b32 v4, v116 offset:1024
	ds_read_b32 v12, v117 offset:1024
	ds_read_b32 v5, v116 offset:1280
	ds_read_b32 v13, v117 offset:1280
	ds_read_b32 v6, v116 offset:1536
	ds_read_b32 v14, v117 offset:1536
	ds_read_b32 v7, v116 offset:1792
	ds_read_b32 v15, v117 offset:1792
	s_waitcnt lgkmcnt(0)
	s_lshl_b32 s99, s2, 2
	s_add_u32 s99, s99, s33
	s_add_u32 s99, s99, 0
	s_lshl_b32 s99, s99, 9
	v_and_b32_e32 v0, 0x7f, v0
	v_lshl_add_u32 v0, v0, 2, s99
	global_load_dword v16, v0, s[82:83]
	v_and_b32_e32 v1, 0x7f, v1
	v_lshl_add_u32 v1, v1, 2, s99
	global_load_dword v17, v1, s[82:83]
	s_lshl_b32 s99, s2, 2
	s_add_u32 s99, s99, s33
	s_add_u32 s99, s99, 1
	s_lshl_b32 s99, s99, 9
	v_and_b32_e32 v2, 0x7f, v2
	v_lshl_add_u32 v2, v2, 2, s99
	global_load_dword v18, v2, s[82:83]
	v_and_b32_e32 v3, 0x7f, v3
	v_lshl_add_u32 v3, v3, 2, s99
	global_load_dword v19, v3, s[82:83]
	s_lshl_b32 s99, s2, 2
	s_add_u32 s99, s99, s33
	s_add_u32 s99, s99, 2
	s_lshl_b32 s99, s99, 9
	v_and_b32_e32 v4, 0x7f, v4
	v_lshl_add_u32 v4, v4, 2, s99
	global_load_dword v20, v4, s[82:83]
	v_and_b32_e32 v5, 0x7f, v5
	v_lshl_add_u32 v5, v5, 2, s99
	global_load_dword v21, v5, s[82:83]
	s_lshl_b32 s99, s2, 2
	s_add_u32 s99, s99, s33
	s_add_u32 s99, s99, 3
	s_lshl_b32 s99, s99, 9
	v_and_b32_e32 v6, 0x7f, v6
	v_lshl_add_u32 v6, v6, 2, s99
	global_load_dword v22, v6, s[82:83]
	v_and_b32_e32 v7, 0x7f, v7
	v_lshl_add_u32 v7, v7, 2, s99
	global_load_dword v23, v7, s[82:83]
	v_mul_f32_e32 v8, 0x3c800000, v8
	v_mul_f32_e32 v9, 0x3c800000, v9
	v_mul_f32_e32 v10, 0x3c800000, v10
	v_mul_f32_e32 v11, 0x3c800000, v11
	v_mul_f32_e32 v12, 0x3c800000, v12
	v_mul_f32_e32 v13, 0x3c800000, v13
	v_mul_f32_e32 v14, 0x3c800000, v14
	v_mul_f32_e32 v15, 0x3c800000, v15
	v_mul_f32_e32 v24, 0x3d372713, v8
	v_mul_f32_e32 v25, 0x3d372713, v9
	v_mul_f32_e32 v26, 0x3d372713, v10
	v_mul_f32_e32 v27, 0x3d372713, v11
	v_mul_f32_e32 v28, 0x3d372713, v12
	v_mul_f32_e32 v29, 0x3d372713, v13
	v_mul_f32_e32 v30, 0x3d372713, v14
	v_mul_f32_e32 v31, 0x3d372713, v15
	v_mul_f32_e32 v24, v8, v24
	v_mul_f32_e32 v25, v9, v25
	v_mul_f32_e32 v26, v10, v26
	v_mul_f32_e32 v27, v11, v27
	v_mul_f32_e32 v28, v12, v28
	v_mul_f32_e32 v29, v13, v29
	v_mul_f32_e32 v30, v14, v30
	v_mul_f32_e32 v31, v15, v31
	v_fma_f32 v24, v8, v24, v8
	v_fma_f32 v25, v9, v25, v9
	v_fma_f32 v26, v10, v26, v10
	v_fma_f32 v27, v11, v27, v11
	v_fma_f32 v28, v12, v28, v12
	v_fma_f32 v29, v13, v29, v13
	v_fma_f32 v30, v14, v30, v14
	v_fma_f32 v31, v15, v31, v15
	v_mul_f32_e32 v24, 0xbfcc422a, v24
	v_mul_f32_e32 v25, 0xbfcc422a, v25
	v_mul_f32_e32 v26, 0xbfcc422a, v26
	v_mul_f32_e32 v27, 0xbfcc422a, v27
	v_mul_f32_e32 v28, 0xbfcc422a, v28
	v_mul_f32_e32 v29, 0xbfcc422a, v29
	v_mul_f32_e32 v30, 0xbfcc422a, v30
	v_mul_f32_e32 v31, 0xbfcc422a, v31
	v_mul_f32_e32 v24, 0x3fb8aa3b, v24
	v_mul_f32_e32 v25, 0x3fb8aa3b, v25
	v_mul_f32_e32 v26, 0x3fb8aa3b, v26
	v_mul_f32_e32 v27, 0x3fb8aa3b, v27
	v_mul_f32_e32 v28, 0x3fb8aa3b, v28
	v_mul_f32_e32 v29, 0x3fb8aa3b, v29
	v_mul_f32_e32 v30, 0x3fb8aa3b, v30
	v_mul_f32_e32 v31, 0x3fb8aa3b, v31
	v_exp_f32_e32 v24, v24
	v_exp_f32_e32 v25, v25
	v_exp_f32_e32 v26, v26
	v_exp_f32_e32 v27, v27
	v_exp_f32_e32 v28, v28
	v_exp_f32_e32 v29, v29
	v_exp_f32_e32 v30, v30
	v_exp_f32_e32 v31, v31
	s_nop 0
	v_add_f32_e32 v24, 1.0, v24
	v_add_f32_e32 v25, 1.0, v25
	v_add_f32_e32 v26, 1.0, v26
	v_add_f32_e32 v27, 1.0, v27
	v_add_f32_e32 v28, 1.0, v28
	v_add_f32_e32 v29, 1.0, v29
	v_add_f32_e32 v30, 1.0, v30
	v_add_f32_e32 v31, 1.0, v31
	v_rcp_f32_e32 v24, v24
	v_rcp_f32_e32 v25, v25
	v_rcp_f32_e32 v26, v26
	v_rcp_f32_e32 v27, v27
	v_rcp_f32_e32 v28, v28
	v_rcp_f32_e32 v29, v29
	v_rcp_f32_e32 v30, v30
	v_rcp_f32_e32 v31, v31
	s_nop 0
	v_mul_f32_e32 v24, v8, v24
	v_mul_f32_e32 v25, v9, v25
	v_mul_f32_e32 v26, v10, v26
	v_mul_f32_e32 v27, v11, v27
	v_mul_f32_e32 v28, v12, v28
	v_mul_f32_e32 v29, v13, v29
	v_mul_f32_e32 v30, v14, v30
	v_mul_f32_e32 v31, v15, v31
	s_waitcnt vmcnt(0)
; #define PG_ISSUE(BUF, TAB, e0_) do { const int isrc_ = ((e0_) < 64) ? myi0 : myi1; \
;       _Pragma("unroll") for (int e = 0; e < 8; ++e) { const int idx_ = __builtin_amdgcn_readlane(isrc_, ((e0_) + e) & 63); \
;         BUF[e] = *(const u32x4*)((TAB) + (size_t)idx_ * 1024 + lane * 16); } } while (0)
; DEV void peer_gather(const Params& P, int l, int m0, const int* idxs, const float* gs) {
;     ...
; #pragma nounroll
;     for (int e0 = 0; e0 < 128; e0 += 16) {
;       PG_ISSUE(b1, V, e0 + 8);
;       if (e0 == 64 && i + 1 < 16) sort_lists(lane, ni0, ni1, ng0, ng1);
;       PG_V16(b0, e0);
;       if (e0 + 16 < 128) PG_ISSUE(b0, V, e0 + 16);
;       PG_V16(b1, e0 + 8);
;     }
	v_mul_f32_e32 v24, v24, v16
	ds_write_b32 v117, v24 offset:0
	v_mul_f32_e32 v25, v25, v17
	ds_write_b32 v117, v25 offset:256
	v_mul_f32_e32 v26, v26, v18
	ds_write_b32 v117, v26 offset:512
	v_mul_f32_e32 v27, v27, v19
	ds_write_b32 v117, v27 offset:768
	v_mul_f32_e32 v28, v28, v20
	ds_write_b32 v117, v28 offset:1024
	v_mul_f32_e32 v29, v29, v21
	ds_write_b32 v117, v29 offset:1280
	v_mul_f32_e32 v30, v30, v22
	ds_write_b32 v117, v30 offset:1536
	v_mul_f32_e32 v31, v31, v23
	ds_write_b32 v117, v31 offset:1792
	s_add_u32 s2, s2, 1
	s_cmp_lt_u32 s2, 4
	s_cbranch_scc1 .Lpg0_act
	s_waitcnt lgkmcnt(0)
	v_readfirstlane_b32 s80, v126
	v_readfirstlane_b32 s81, v127
	s_nop 4
	v_readfirstlane_b32 s82, v132
	v_readfirstlane_b32 s83, v133
	s_nop 4
	s_mov_b32 s2, 0xffffff80
	s_lshl_b32 vcc_lo, s3, 12
	s_add_u32 s82, s82, vcc_lo
	s_addc_u32 s83, s83, 0
	s_mov_b32 s88, 0xff00ff00
	s_mov_b32 s89, 0xff00ff00
	v_lshl_add_u32 v246, v237, 4, s101
	v_add_u32_e32 v247, 0x10000, v246
	s_mov_b32 s100, 0
	s_mov_b32 s98, 0
	s_mov_b32 s99, 0
	v_lshl_add_u32 v116, s98, 9, v246
	ds_read_b128 v[112:115], v116
	ds_read_b128 v[138:141], v116 offset:16
	ds_read_b128 v[250:253], v116 offset:32
	ds_read_b128 v[242:245], v116 offset:48
	v_lshl_or_b32 v240, s99, 21, v235
	s_waitcnt lgkmcnt(0)
	v_and_or_b32 v112, v112, s2, v240
	v_and_or_b32 v113, v113, s2, v240
	global_load_dwordx4 v[0:3], v112, s[80:81]
	global_load_dwordx4 v[4:7], v113, s[80:81]
	v_and_or_b32 v114, v114, s2, v240
	v_and_or_b32 v115, v115, s2, v240
	global_load_dwordx4 v[8:11], v114, s[80:81]
	global_load_dwordx4 v[12:15], v115, s[80:81]
	v_and_or_b32 v138, v138, s2, v240
	v_and_or_b32 v139, v139, s2, v240
	global_load_dwordx4 v[16:19], v138, s[80:81]
	global_load_dwordx4 v[20:23], v139, s[80:81]
	v_and_or_b32 v140, v140, s2, v240
	v_and_or_b32 v141, v141, s2, v240
	global_load_dwordx4 v[24:27], v140, s[80:81]
	global_load_dwordx4 v[28:31], v141, s[80:81]
	v_and_or_b32 v250, v250, s2, v240
	v_and_or_b32 v251, v251, s2, v240
	global_load_dwordx4 v[32:35], v250, s[80:81]
	global_load_dwordx4 v[36:39], v251, s[80:81]
	v_and_or_b32 v252, v252, s2, v240
	v_and_or_b32 v253, v253, s2, v240
	global_load_dwordx4 v[40:43], v252, s[80:81]
	global_load_dwordx4 v[44:47], v253, s[80:81]
	v_and_or_b32 v242, v242, s2, v240
	v_and_or_b32 v243, v243, s2, v240
	global_load_dwordx4 v[48:51], v242, s[80:81]
	global_load_dwordx4 v[52:55], v243, s[80:81]
	v_and_or_b32 v244, v244, s2, v240
	v_and_or_b32 v245, v245, s2, v240
	global_load_dwordx4 v[56:59], v244, s[80:81]
	global_load_dwordx4 v[60:63], v245, s[80:81]
	s_mov_b32 s92, 1
	v_lshl_add_u32 v116, s92, 9, v246
	ds_read_b128 v[112:115], v116
	ds_read_b128 v[138:141], v116 offset:16
	ds_read_b128 v[250:253], v116 offset:32
	ds_read_b128 v[242:245], v116 offset:48
	v_lshl_add_u32 v117, s98, 9, v247
	ds_read_b128 v[84:87], v117
	ds_read_b128 v[88:91], v117 offset:16
	ds_read_b128 v[92:95], v117 offset:32
	ds_read_b128 v[96:99], v117 offset:48
	s_waitcnt vmcnt(0)
.Lpg0_vloop:
	s_and_b32 s98, s100, 15
	s_lshr_b32 s99, s100, 4
	s_add_u32 s93, s100, 1
	s_min_u32 s93, s93, 127
	s_lshr_b32 s93, s93, 4
	s_lshl3_add_u32 vcc_lo, s98, s99
	v_lshl_add_u32 v119, vcc_lo, 9, v238
	global_load_dword v80, v119, s[82:83]
	global_load_dword v81, v119, s[82:83] offset:32
	v_lshl_or_b32 v240, s93, 21, v235
	s_waitcnt lgkmcnt(0)
	s_waitcnt vmcnt(18)
	v_cvt_pk_f32_fp8_e32 v[104:105], v0
	v_cvt_pk_f32_fp8_e32 v[108:109], v4
	v_cvt_pk_f32_fp8_sdwa v[106:107], v0 src0_sel:WORD_1
	v_cvt_pk_f32_fp8_sdwa v[110:111], v4 src0_sel:WORD_1
	v_pk_mul_f32 v[64:65], v[104:105], v[84:85] op_sel_hi:[1,0]
	v_pk_mul_f32 v[66:67], v[106:107], v[84:85] op_sel_hi:[1,0]
	v_pk_fma_f32 v[64:65], v[108:109], v[84:85], v[64:65] op_sel:[0,1,0] op_sel_hi:[1,1,1]
	v_pk_fma_f32 v[66:67], v[110:111], v[84:85], v[66:67] op_sel:[0,1,0] op_sel_hi:[1,1,1]
	v_cvt_pk_f32_fp8_e32 v[104:105], v1
	v_cvt_pk_f32_fp8_e32 v[108:109], v5
	v_cvt_pk_f32_fp8_sdwa v[106:107], v1 src0_sel:WORD_1
	v_cvt_pk_f32_fp8_sdwa v[110:111], v5 src0_sel:WORD_1
	v_pk_mul_f32 v[68:69], v[104:105], v[84:85] op_sel_hi:[1,0]
	v_pk_mul_f32 v[70:71], v[106:107], v[84:85] op_sel_hi:[1,0]
	v_pk_fma_f32 v[68:69], v[108:109], v[84:85], v[68:69] op_sel:[0,1,0] op_sel_hi:[1,1,1]
	v_pk_fma_f32 v[70:71], v[110:111], v[84:85], v[70:71] op_sel:[0,1,0] op_sel_hi:[1,1,1]
	v_cvt_pk_f32_fp8_e32 v[104:105], v2
	v_cvt_pk_f32_fp8_e32 v[108:109], v6
	v_cvt_pk_f32_fp8_sdwa v[106:107], v2 src0_sel:WORD_1
	v_cvt_pk_f32_fp8_sdwa v[110:111], v6 src0_sel:WORD_1
	v_pk_mul_f32 v[72:73], v[104:105], v[84:85] op_sel_hi:[1,0]
	v_pk_mul_f32 v[74:75], v[106:107], v[84:85] op_sel_hi:[1,0]
	v_pk_fma_f32 v[72:73], v[108:109], v[84:85], v[72:73] op_sel:[0,1,0] op_sel_hi:[1,1,1]
	v_pk_fma_f32 v[74:75], v[110:111], v[84:85], v[74:75] op_sel:[0,1,0] op_sel_hi:[1,1,1]
	v_cvt_pk_f32_fp8_e32 v[104:105], v3
	v_cvt_pk_f32_fp8_e32 v[108:109], v7
	v_cvt_pk_f32_fp8_sdwa v[106:107], v3 src0_sel:WORD_1
	v_cvt_pk_f32_fp8_sdwa v[110:111], v7 src0_sel:WORD_1
	v_pk_mul_f32 v[76:77], v[104:105], v[84:85] op_sel_hi:[1,0]
	v_pk_mul_f32 v[78:79], v[106:107], v[84:85] op_sel_hi:[1,0]
	v_and_or_b32 v112, v112, s2, v240
	v_and_or_b32 v113, v113, s2, v240
	global_load_dwordx4 v[0:3], v112, s[80:81]
	global_load_dwordx4 v[4:7], v113, s[80:81]
	v_pk_fma_f32 v[76:77], v[108:109], v[84:85], v[76:77] op_sel:[0,1,0] op_sel_hi:[1,1,1]
	v_pk_fma_f32 v[78:79], v[110:111], v[84:85], v[78:79] op_sel:[0,1,0] op_sel_hi:[1,1,1]
	s_waitcnt vmcnt(18)
	v_cvt_pk_f32_fp8_e32 v[104:105], v8
	v_cvt_pk_f32_fp8_e32 v[108:109], v12
	v_cvt_pk_f32_fp8_sdwa v[106:107], v8 src0_sel:WORD_1
	v_cvt_pk_f32_fp8_sdwa v[110:111], v12 src0_sel:WORD_1
	v_pk_fma_f32 v[64:65], v[104:105], v[86:87], v[64:65] op_sel_hi:[1,0,1]
	v_pk_fma_f32 v[66:67], v[106:107], v[86:87], v[66:67] op_sel_hi:[1,0,1]
	v_pk_fma_f32 v[64:65], v[108:109], v[86:87], v[64:65] op_sel:[0,1,0] op_sel_hi:[1,1,1]
	v_pk_fma_f32 v[66:67], v[110:111], v[86:87], v[66:67] op_sel:[0,1,0] op_sel_hi:[1,1,1]
	v_cvt_pk_f32_fp8_e32 v[104:105], v9
	v_cvt_pk_f32_fp8_e32 v[108:109], v13
	v_cvt_pk_f32_fp8_sdwa v[106:107], v9 src0_sel:WORD_1
	v_cvt_pk_f32_fp8_sdwa v[110:111], v13 src0_sel:WORD_1
	v_pk_fma_f32 v[68:69], v[104:105], v[86:87], v[68:69] op_sel_hi:[1,0,1]
	v_pk_fma_f32 v[70:71], v[106:107], v[86:87], v[70:71] op_sel_hi:[1,0,1]
	v_pk_fma_f32 v[68:69], v[108:109], v[86:87], v[68:69] op_sel:[0,1,0] op_sel_hi:[1,1,1]
	v_pk_fma_f32 v[70:71], v[110:111], v[86:87], v[70:71] op_sel:[0,1,0] op_sel_hi:[1,1,1]
	v_cvt_pk_f32_fp8_e32 v[104:105], v10
	v_cvt_pk_f32_fp8_e32 v[108:109], v14
	v_cvt_pk_f32_fp8_sdwa v[106:107], v10 src0_sel:WORD_1
	v_cvt_pk_f32_fp8_sdwa v[110:111], v14 src0_sel:WORD_1
	v_pk_fma_f32 v[72:73], v[104:105], v[86:87], v[72:73] op_sel_hi:[1,0,1]
	v_pk_fma_f32 v[74:75], v[106:107], v[86:87], v[74:75] op_sel_hi:[1,0,1]
	v_pk_fma_f32 v[72:73], v[108:109], v[86:87], v[72:73] op_sel:[0,1,0] op_sel_hi:[1,1,1]
	v_pk_fma_f32 v[74:75], v[110:111], v[86:87], v[74:75] op_sel:[0,1,0] op_sel_hi:[1,1,1]
	v_cvt_pk_f32_fp8_e32 v[104:105], v11
	v_cvt_pk_f32_fp8_e32 v[108:109], v15
	v_cvt_pk_f32_fp8_sdwa v[106:107], v11 src0_sel:WORD_1
	v_cvt_pk_f32_fp8_sdwa v[110:111], v15 src0_sel:WORD_1
	v_pk_fma_f32 v[76:77], v[104:105], v[86:87], v[76:77] op_sel_hi:[1,0,1]
	v_pk_fma_f32 v[78:79], v[106:107], v[86:87], v[78:79] op_sel_hi:[1,0,1]
	v_and_or_b32 v114, v114, s2, v240
	v_and_or_b32 v115, v115, s2, v240
	global_load_dwordx4 v[8:11], v114, s[80:81]
	global_load_dwordx4 v[12:15], v115, s[80:81]
	v_pk_fma_f32 v[76:77], v[108:109], v[86:87], v[76:77] op_sel:[0,1,0] op_sel_hi:[1,1,1]
	v_pk_fma_f32 v[78:79], v[110:111], v[86:87], v[78:79] op_sel:[0,1,0] op_sel_hi:[1,1,1]
	s_waitcnt vmcnt(18)
	v_cvt_pk_f32_fp8_e32 v[104:105], v16
	v_cvt_pk_f32_fp8_e32 v[108:109], v20
	v_cvt_pk_f32_fp8_sdwa v[106:107], v16 src0_sel:WORD_1
	v_cvt_pk_f32_fp8_sdwa v[110:111], v20 src0_sel:WORD_1
	v_pk_fma_f32 v[64:65], v[104:105], v[88:89], v[64:65] op_sel_hi:[1,0,1]
	v_pk_fma_f32 v[66:67], v[106:107], v[88:89], v[66:67] op_sel_hi:[1,0,1]
	v_pk_fma_f32 v[64:65], v[108:109], v[88:89], v[64:65] op_sel:[0,1,0] op_sel_hi:[1,1,1]
	v_pk_fma_f32 v[66:67], v[110:111], v[88:89], v[66:67] op_sel:[0,1,0] op_sel_hi:[1,1,1]
	v_cvt_pk_f32_fp8_e32 v[104:105], v17
	v_cvt_pk_f32_fp8_e32 v[108:109], v21
	v_cvt_pk_f32_fp8_sdwa v[106:107], v17 src0_sel:WORD_1
	v_cvt_pk_f32_fp8_sdwa v[110:111], v21 src0_sel:WORD_1
	v_pk_fma_f32 v[68:69], v[104:105], v[88:89], v[68:69] op_sel_hi:[1,0,1]
	v_pk_fma_f32 v[70:71], v[106:107], v[88:89], v[70:71] op_sel_hi:[1,0,1]
	v_pk_fma_f32 v[68:69], v[108:109], v[88:89], v[68:69] op_sel:[0,1,0] op_sel_hi:[1,1,1]
	v_pk_fma_f32 v[70:71], v[110:111], v[88:89], v[70:71] op_sel:[0,1,0] op_sel_hi:[1,1,1]
	v_cvt_pk_f32_fp8_e32 v[104:105], v18
	v_cvt_pk_f32_fp8_e32 v[108:109], v22
	v_cvt_pk_f32_fp8_sdwa v[106:107], v18 src0_sel:WORD_1
	v_cvt_pk_f32_fp8_sdwa v[110:111], v22 src0_sel:WORD_1
	v_pk_fma_f32 v[72:73], v[104:105], v[88:89], v[72:73] op_sel_hi:[1,0,1]
	v_pk_fma_f32 v[74:75], v[106:107], v[88:89], v[74:75] op_sel_hi:[1,0,1]
	v_pk_fma_f32 v[72:73], v[108:109], v[88:89], v[72:73] op_sel:[0,1,0] op_sel_hi:[1,1,1]
	v_pk_fma_f32 v[74:75], v[110:111], v[88:89], v[74:75] op_sel:[0,1,0] op_sel_hi:[1,1,1]
	v_cvt_pk_f32_fp8_e32 v[104:105], v19
	v_cvt_pk_f32_fp8_e32 v[108:109], v23
	v_cvt_pk_f32_fp8_sdwa v[106:107], v19 src0_sel:WORD_1
	v_cvt_pk_f32_fp8_sdwa v[110:111], v23 src0_sel:WORD_1
	v_pk_fma_f32 v[76:77], v[104:105], v[88:89], v[76:77] op_sel_hi:[1,0,1]
	v_pk_fma_f32 v[78:79], v[106:107], v[88:89], v[78:79] op_sel_hi:[1,0,1]
	v_and_or_b32 v138, v138, s2, v240
	v_and_or_b32 v139, v139, s2, v240
	global_load_dwordx4 v[16:19], v138, s[80:81]
	global_load_dwordx4 v[20:23], v139, s[80:81]
	v_pk_fma_f32 v[76:77], v[108:109], v[88:89], v[76:77] op_sel:[0,1,0] op_sel_hi:[1,1,1]
	v_pk_fma_f32 v[78:79], v[110:111], v[88:89], v[78:79] op_sel:[0,1,0] op_sel_hi:[1,1,1]
	s_waitcnt vmcnt(18)
	v_cvt_pk_f32_fp8_e32 v[104:105], v24
	v_cvt_pk_f32_fp8_e32 v[108:109], v28
	v_cvt_pk_f32_fp8_sdwa v[106:107], v24 src0_sel:WORD_1
	v_cvt_pk_f32_fp8_sdwa v[110:111], v28 src0_sel:WORD_1
	v_pk_fma_f32 v[64:65], v[104:105], v[90:91], v[64:65] op_sel_hi:[1,0,1]
	v_pk_fma_f32 v[66:67], v[106:107], v[90:91], v[66:67] op_sel_hi:[1,0,1]
	v_pk_fma_f32 v[64:65], v[108:109], v[90:91], v[64:65] op_sel:[0,1,0] op_sel_hi:[1,1,1]
	v_pk_fma_f32 v[66:67], v[110:111], v[90:91], v[66:67] op_sel:[0,1,0] op_sel_hi:[1,1,1]
	v_cvt_pk_f32_fp8_e32 v[104:105], v25
	v_cvt_pk_f32_fp8_e32 v[108:109], v29
	v_cvt_pk_f32_fp8_sdwa v[106:107], v25 src0_sel:WORD_1
	v_cvt_pk_f32_fp8_sdwa v[110:111], v29 src0_sel:WORD_1
	v_pk_fma_f32 v[68:69], v[104:105], v[90:91], v[68:69] op_sel_hi:[1,0,1]
	v_pk_fma_f32 v[70:71], v[106:107], v[90:91], v[70:71] op_sel_hi:[1,0,1]
	v_pk_fma_f32 v[68:69], v[108:109], v[90:91], v[68:69] op_sel:[0,1,0] op_sel_hi:[1,1,1]
	v_pk_fma_f32 v[70:71], v[110:111], v[90:91], v[70:71] op_sel:[0,1,0] op_sel_hi:[1,1,1]
	v_cvt_pk_f32_fp8_e32 v[104:105], v26
	v_cvt_pk_f32_fp8_e32 v[108:109], v30
	v_cvt_pk_f32_fp8_sdwa v[106:107], v26 src0_sel:WORD_1
	v_cvt_pk_f32_fp8_sdwa v[110:111], v30 src0_sel:WORD_1
	v_pk_fma_f32 v[72:73], v[104:105], v[90:91], v[72:73] op_sel_hi:[1,0,1]
	v_pk_fma_f32 v[74:75], v[106:107], v[90:91], v[74:75] op_sel_hi:[1,0,1]
	v_pk_fma_f32 v[72:73], v[108:109], v[90:91], v[72:73] op_sel:[0,1,0] op_sel_hi:[1,1,1]
	v_pk_fma_f32 v[74:75], v[110:111], v[90:91], v[74:75] op_sel:[0,1,0] op_sel_hi:[1,1,1]
	v_cvt_pk_f32_fp8_e32 v[104:105], v27
	v_cvt_pk_f32_fp8_e32 v[108:109], v31
	v_cvt_pk_f32_fp8_sdwa v[106:107], v27 src0_sel:WORD_1
	v_cvt_pk_f32_fp8_sdwa v[110:111], v31 src0_sel:WORD_1
	v_pk_fma_f32 v[76:77], v[104:105], v[90:91], v[76:77] op_sel_hi:[1,0,1]
	v_pk_fma_f32 v[78:79], v[106:107], v[90:91], v[78:79] op_sel_hi:[1,0,1]
	v_and_or_b32 v140, v140, s2, v240
	v_and_or_b32 v141, v141, s2, v240
	global_load_dwordx4 v[24:27], v140, s[80:81]
	global_load_dwordx4 v[28:31], v141, s[80:81]
	v_pk_fma_f32 v[76:77], v[108:109], v[90:91], v[76:77] op_sel:[0,1,0] op_sel_hi:[1,1,1]
	v_pk_fma_f32 v[78:79], v[110:111], v[90:91], v[78:79] op_sel:[0,1,0] op_sel_hi:[1,1,1]
	s_waitcnt vmcnt(18)
	v_cvt_pk_f32_fp8_e32 v[104:105], v32
	v_cvt_pk_f32_fp8_e32 v[108:109], v36
	v_cvt_pk_f32_fp8_sdwa v[106:107], v32 src0_sel:WORD_1
	v_cvt_pk_f32_fp8_sdwa v[110:111], v36 src0_sel:WORD_1
	v_pk_fma_f32 v[64:65], v[104:105], v[92:93], v[64:65] op_sel_hi:[1,0,1]
	v_pk_fma_f32 v[66:67], v[106:107], v[92:93], v[66:67] op_sel_hi:[1,0,1]
	v_pk_fma_f32 v[64:65], v[108:109], v[92:93], v[64:65] op_sel:[0,1,0] op_sel_hi:[1,1,1]
	v_pk_fma_f32 v[66:67], v[110:111], v[92:93], v[66:67] op_sel:[0,1,0] op_sel_hi:[1,1,1]
	v_cvt_pk_f32_fp8_e32 v[104:105], v33
	v_cvt_pk_f32_fp8_e32 v[108:109], v37
	v_cvt_pk_f32_fp8_sdwa v[106:107], v33 src0_sel:WORD_1
	v_cvt_pk_f32_fp8_sdwa v[110:111], v37 src0_sel:WORD_1
	v_pk_fma_f32 v[68:69], v[104:105], v[92:93], v[68:69] op_sel_hi:[1,0,1]
	v_pk_fma_f32 v[70:71], v[106:107], v[92:93], v[70:71] op_sel_hi:[1,0,1]
	v_pk_fma_f32 v[68:69], v[108:109], v[92:93], v[68:69] op_sel:[0,1,0] op_sel_hi:[1,1,1]
	v_pk_fma_f32 v[70:71], v[110:111], v[92:93], v[70:71] op_sel:[0,1,0] op_sel_hi:[1,1,1]
	v_cvt_pk_f32_fp8_e32 v[104:105], v34
	v_cvt_pk_f32_fp8_e32 v[108:109], v38
	v_cvt_pk_f32_fp8_sdwa v[106:107], v34 src0_sel:WORD_1
	v_cvt_pk_f32_fp8_sdwa v[110:111], v38 src0_sel:WORD_1
	v_pk_fma_f32 v[72:73], v[104:105], v[92:93], v[72:73] op_sel_hi:[1,0,1]
	v_pk_fma_f32 v[74:75], v[106:107], v[92:93], v[74:75] op_sel_hi:[1,0,1]
	v_pk_fma_f32 v[72:73], v[108:109], v[92:93], v[72:73] op_sel:[0,1,0] op_sel_hi:[1,1,1]
	v_pk_fma_f32 v[74:75], v[110:111], v[92:93], v[74:75] op_sel:[0,1,0] op_sel_hi:[1,1,1]
	v_cvt_pk_f32_fp8_e32 v[104:105], v35
	v_cvt_pk_f32_fp8_e32 v[108:109], v39
	v_cvt_pk_f32_fp8_sdwa v[106:107], v35 src0_sel:WORD_1
	v_cvt_pk_f32_fp8_sdwa v[110:111], v39 src0_sel:WORD_1
	v_pk_fma_f32 v[76:77], v[104:105], v[92:93], v[76:77] op_sel_hi:[1,0,1]
	v_pk_fma_f32 v[78:79], v[106:107], v[92:93], v[78:79] op_sel_hi:[1,0,1]
	v_and_or_b32 v250, v250, s2, v240
	v_and_or_b32 v251, v251, s2, v240
	global_load_dwordx4 v[32:35], v250, s[80:81]
	global_load_dwordx4 v[36:39], v251, s[80:81]
	v_pk_fma_f32 v[76:77], v[108:109], v[92:93], v[76:77] op_sel:[0,1,0] op_sel_hi:[1,1,1]
	v_pk_fma_f32 v[78:79], v[110:111], v[92:93], v[78:79] op_sel:[0,1,0] op_sel_hi:[1,1,1]
	s_waitcnt vmcnt(18)
	v_cvt_pk_f32_fp8_e32 v[104:105], v40
	v_cvt_pk_f32_fp8_e32 v[108:109], v44
	v_cvt_pk_f32_fp8_sdwa v[106:107], v40 src0_sel:WORD_1
	v_cvt_pk_f32_fp8_sdwa v[110:111], v44 src0_sel:WORD_1
	v_pk_fma_f32 v[64:65], v[104:105], v[94:95], v[64:65] op_sel_hi:[1,0,1]
	v_pk_fma_f32 v[66:67], v[106:107], v[94:95], v[66:67] op_sel_hi:[1,0,1]
	v_pk_fma_f32 v[64:65], v[108:109], v[94:95], v[64:65] op_sel:[0,1,0] op_sel_hi:[1,1,1]
	v_pk_fma_f32 v[66:67], v[110:111], v[94:95], v[66:67] op_sel:[0,1,0] op_sel_hi:[1,1,1]
	v_cvt_pk_f32_fp8_e32 v[104:105], v41
	v_cvt_pk_f32_fp8_e32 v[108:109], v45
	v_cvt_pk_f32_fp8_sdwa v[106:107], v41 src0_sel:WORD_1
	v_cvt_pk_f32_fp8_sdwa v[110:111], v45 src0_sel:WORD_1
	v_pk_fma_f32 v[68:69], v[104:105], v[94:95], v[68:69] op_sel_hi:[1,0,1]
	v_pk_fma_f32 v[70:71], v[106:107], v[94:95], v[70:71] op_sel_hi:[1,0,1]
	v_pk_fma_f32 v[68:69], v[108:109], v[94:95], v[68:69] op_sel:[0,1,0] op_sel_hi:[1,1,1]
	v_pk_fma_f32 v[70:71], v[110:111], v[94:95], v[70:71] op_sel:[0,1,0] op_sel_hi:[1,1,1]
	v_cvt_pk_f32_fp8_e32 v[104:105], v42
	v_cvt_pk_f32_fp8_e32 v[108:109], v46
	v_cvt_pk_f32_fp8_sdwa v[106:107], v42 src0_sel:WORD_1
	v_cvt_pk_f32_fp8_sdwa v[110:111], v46 src0_sel:WORD_1
	v_pk_fma_f32 v[72:73], v[104:105], v[94:95], v[72:73] op_sel_hi:[1,0,1]
	v_pk_fma_f32 v[74:75], v[106:107], v[94:95], v[74:75] op_sel_hi:[1,0,1]
	v_pk_fma_f32 v[72:73], v[108:109], v[94:95], v[72:73] op_sel:[0,1,0] op_sel_hi:[1,1,1]
	v_pk_fma_f32 v[74:75], v[110:111], v[94:95], v[74:75] op_sel:[0,1,0] op_sel_hi:[1,1,1]
	v_cvt_pk_f32_fp8_e32 v[104:105], v43
	v_cvt_pk_f32_fp8_e32 v[108:109], v47
	v_cvt_pk_f32_fp8_sdwa v[106:107], v43 src0_sel:WORD_1
	v_cvt_pk_f32_fp8_sdwa v[110:111], v47 src0_sel:WORD_1
	v_pk_fma_f32 v[76:77], v[104:105], v[94:95], v[76:77] op_sel_hi:[1,0,1]
	v_pk_fma_f32 v[78:79], v[106:107], v[94:95], v[78:79] op_sel_hi:[1,0,1]
	v_and_or_b32 v252, v252, s2, v240
	v_and_or_b32 v253, v253, s2, v240
	global_load_dwordx4 v[40:43], v252, s[80:81]
	global_load_dwordx4 v[44:47], v253, s[80:81]
	v_pk_fma_f32 v[76:77], v[108:109], v[94:95], v[76:77] op_sel:[0,1,0] op_sel_hi:[1,1,1]
	v_pk_fma_f32 v[78:79], v[110:111], v[94:95], v[78:79] op_sel:[0,1,0] op_sel_hi:[1,1,1]
	s_waitcnt vmcnt(18)
; #define PG_ISSUE(BUF, TAB, e0_) do { const int isrc_ = ((e0_) < 64) ? myi0 : myi1; \
;       _Pragma("unroll") for (int e = 0; e < 8; ++e) { const int idx_ = __builtin_amdgcn_readlane(isrc_, ((e0_) + e) & 63); \
;         BUF[e] = *(const u32x4*)((TAB) + (size_t)idx_ * 1024 + lane * 16); } } while (0)
; DEV void peer_gather(const Params& P, int l, int m0, const int* idxs, const float* gs) {
;     ...
;     PG_ISSUE(b0, U, 0);
; #pragma nounroll
;     for (int e0 = 0; e0 < 128; e0 += 16) {
;       PG_ISSUE(b1, U, e0 + 8);
;       PG_U8(b0, 0, e0);
;       if (e0 + 16 < 128) PG_ISSUE(b0, U, e0 + 16); else PG_ISSUE(b0, V, 0);
;       PG_U8(b1, 0, e0 + 8);
;     }
;     float* hrow = P.out + tok * DM + lane * 16;
;     f32x4 hv[4];
; #pragma unroll
;     for (int q = 0; q < 4; ++q) hv[q] = *(const f32x4*)(hrow + 4 * q);
;     if (i + 1 < 16) {
;       const int tn = tt + 1;
;       nxa = *(const u32x4*)(hn + (size_t)(m0 + tn) * DM + lane * 16); nxb = *(const u32x4*)(hn + (size_t)(m0 + tn) * DM + lane * 16 + 8);
;       ni0 = idxs[tn * 128 + lane]; ni1 = idxs[tn * 128 + 64 + lane]; ng0 = gs[tn * 128 + lane]; ng1 = gs[tn * 128 + 64 + lane];
;     }
; #pragma nounroll
;     for (int e0 = 0; e0 < 128; e0 += 16) {
;       PG_ISSUE(b1, V, e0 + 8);
;       if (e0 == 64 && i + 1 < 16) sort_lists(lane, ni0, ni1, ng0, ng1);
;       PG_V16(b0, e0);
;       if (e0 + 16 < 128) PG_ISSUE(b0, V, e0 + 16);
;       PG_V16(b1, e0 + 8);
;     }
;     ...
;     float ss = 0.f;
; #pragma unroll
;     for (int q = 0; q < 4; ++q) {
;       hv[q][0] += acc[2 * q][0] * TAB_INV; hv[q][1] += acc[2 * q][1] * TAB_INV; hv[q][2] += acc[2 * q + 1][0] * TAB_INV; hv[q][3] += acc[2 * q + 1][1] * TAB_INV;
;       ss += hv[q][0] * hv[q][0] + hv[q][1] * hv[q][1] + hv[q][2] * hv[q][2] + hv[q][3] * hv[q][3];
;       *(f32x4*)(hrow + 4 * q) = hv[q];
	v_cvt_pk_f32_fp8_e32 v[104:105], v48
	v_cvt_pk_f32_fp8_e32 v[108:109], v52
	v_cvt_pk_f32_fp8_sdwa v[106:107], v48 src0_sel:WORD_1
	v_cvt_pk_f32_fp8_sdwa v[110:111], v52 src0_sel:WORD_1
	v_pk_fma_f32 v[64:65], v[104:105], v[96:97], v[64:65] op_sel_hi:[1,0,1]
	v_pk_fma_f32 v[66:67], v[106:107], v[96:97], v[66:67] op_sel_hi:[1,0,1]
	v_pk_fma_f32 v[64:65], v[108:109], v[96:97], v[64:65] op_sel:[0,1,0] op_sel_hi:[1,1,1]
	v_pk_fma_f32 v[66:67], v[110:111], v[96:97], v[66:67] op_sel:[0,1,0] op_sel_hi:[1,1,1]
	v_cvt_pk_f32_fp8_e32 v[104:105], v49
	v_cvt_pk_f32_fp8_e32 v[108:109], v53
	v_cvt_pk_f32_fp8_sdwa v[106:107], v49 src0_sel:WORD_1
	v_cvt_pk_f32_fp8_sdwa v[110:111], v53 src0_sel:WORD_1
	v_pk_fma_f32 v[68:69], v[104:105], v[96:97], v[68:69] op_sel_hi:[1,0,1]
	v_pk_fma_f32 v[70:71], v[106:107], v[96:97], v[70:71] op_sel_hi:[1,0,1]
	v_pk_fma_f32 v[68:69], v[108:109], v[96:97], v[68:69] op_sel:[0,1,0] op_sel_hi:[1,1,1]
	v_pk_fma_f32 v[70:71], v[110:111], v[96:97], v[70:71] op_sel:[0,1,0] op_sel_hi:[1,1,1]
	v_cvt_pk_f32_fp8_e32 v[104:105], v50
	v_cvt_pk_f32_fp8_e32 v[108:109], v54
	v_cvt_pk_f32_fp8_sdwa v[106:107], v50 src0_sel:WORD_1
	v_cvt_pk_f32_fp8_sdwa v[110:111], v54 src0_sel:WORD_1
	v_pk_fma_f32 v[72:73], v[104:105], v[96:97], v[72:73] op_sel_hi:[1,0,1]
	v_pk_fma_f32 v[74:75], v[106:107], v[96:97], v[74:75] op_sel_hi:[1,0,1]
	v_pk_fma_f32 v[72:73], v[108:109], v[96:97], v[72:73] op_sel:[0,1,0] op_sel_hi:[1,1,1]
	v_pk_fma_f32 v[74:75], v[110:111], v[96:97], v[74:75] op_sel:[0,1,0] op_sel_hi:[1,1,1]
	v_cvt_pk_f32_fp8_e32 v[104:105], v51
	v_cvt_pk_f32_fp8_e32 v[108:109], v55
	v_cvt_pk_f32_fp8_sdwa v[106:107], v51 src0_sel:WORD_1
	v_cvt_pk_f32_fp8_sdwa v[110:111], v55 src0_sel:WORD_1
	v_pk_fma_f32 v[76:77], v[104:105], v[96:97], v[76:77] op_sel_hi:[1,0,1]
	v_pk_fma_f32 v[78:79], v[106:107], v[96:97], v[78:79] op_sel_hi:[1,0,1]
	v_and_or_b32 v242, v242, s2, v240
	v_and_or_b32 v243, v243, s2, v240
	global_load_dwordx4 v[48:51], v242, s[80:81]
	global_load_dwordx4 v[52:55], v243, s[80:81]
	v_pk_fma_f32 v[76:77], v[108:109], v[96:97], v[76:77] op_sel:[0,1,0] op_sel_hi:[1,1,1]
	v_pk_fma_f32 v[78:79], v[110:111], v[96:97], v[78:79] op_sel:[0,1,0] op_sel_hi:[1,1,1]
	s_waitcnt vmcnt(18)
	v_cvt_pk_f32_fp8_e32 v[104:105], v56
	v_cvt_pk_f32_fp8_e32 v[108:109], v60
	v_cvt_pk_f32_fp8_sdwa v[106:107], v56 src0_sel:WORD_1
	v_cvt_pk_f32_fp8_sdwa v[110:111], v60 src0_sel:WORD_1
	v_pk_fma_f32 v[64:65], v[104:105], v[98:99], v[64:65] op_sel_hi:[1,0,1]
	v_pk_fma_f32 v[66:67], v[106:107], v[98:99], v[66:67] op_sel_hi:[1,0,1]
	v_pk_fma_f32 v[64:65], v[108:109], v[98:99], v[64:65] op_sel:[0,1,0] op_sel_hi:[1,1,1]
	v_pk_fma_f32 v[66:67], v[110:111], v[98:99], v[66:67] op_sel:[0,1,0] op_sel_hi:[1,1,1]
	v_cvt_pk_f32_fp8_e32 v[104:105], v57
	v_cvt_pk_f32_fp8_e32 v[108:109], v61
	v_cvt_pk_f32_fp8_sdwa v[106:107], v57 src0_sel:WORD_1
	v_cvt_pk_f32_fp8_sdwa v[110:111], v61 src0_sel:WORD_1
	v_pk_fma_f32 v[68:69], v[104:105], v[98:99], v[68:69] op_sel_hi:[1,0,1]
	v_pk_fma_f32 v[70:71], v[106:107], v[98:99], v[70:71] op_sel_hi:[1,0,1]
	v_pk_fma_f32 v[68:69], v[108:109], v[98:99], v[68:69] op_sel:[0,1,0] op_sel_hi:[1,1,1]
	v_pk_fma_f32 v[70:71], v[110:111], v[98:99], v[70:71] op_sel:[0,1,0] op_sel_hi:[1,1,1]
	v_cvt_pk_f32_fp8_e32 v[104:105], v58
	v_cvt_pk_f32_fp8_e32 v[108:109], v62
	v_cvt_pk_f32_fp8_sdwa v[106:107], v58 src0_sel:WORD_1
	v_cvt_pk_f32_fp8_sdwa v[110:111], v62 src0_sel:WORD_1
	v_pk_fma_f32 v[72:73], v[104:105], v[98:99], v[72:73] op_sel_hi:[1,0,1]
	v_pk_fma_f32 v[74:75], v[106:107], v[98:99], v[74:75] op_sel_hi:[1,0,1]
	v_pk_fma_f32 v[72:73], v[108:109], v[98:99], v[72:73] op_sel:[0,1,0] op_sel_hi:[1,1,1]
	v_pk_fma_f32 v[74:75], v[110:111], v[98:99], v[74:75] op_sel:[0,1,0] op_sel_hi:[1,1,1]
	v_cvt_pk_f32_fp8_e32 v[104:105], v59
	v_cvt_pk_f32_fp8_e32 v[108:109], v63
	v_cvt_pk_f32_fp8_sdwa v[106:107], v59 src0_sel:WORD_1
	v_cvt_pk_f32_fp8_sdwa v[110:111], v63 src0_sel:WORD_1
	v_pk_fma_f32 v[76:77], v[104:105], v[98:99], v[76:77] op_sel_hi:[1,0,1]
	v_pk_fma_f32 v[78:79], v[106:107], v[98:99], v[78:79] op_sel_hi:[1,0,1]
	v_and_or_b32 v244, v244, s2, v240
	v_and_or_b32 v245, v245, s2, v240
	global_load_dwordx4 v[56:59], v244, s[80:81]
	global_load_dwordx4 v[60:63], v245, s[80:81]
	v_pk_fma_f32 v[76:77], v[108:109], v[98:99], v[76:77] op_sel:[0,1,0] op_sel_hi:[1,1,1]
	v_pk_fma_f32 v[78:79], v[110:111], v[98:99], v[78:79] op_sel:[0,1,0] op_sel_hi:[1,1,1]
	s_add_u32 s92, s100, 2
	s_and_b32 s92, s92, 15
	v_lshl_add_u32 v116, s92, 9, v246
	ds_read_b128 v[112:115], v116
	ds_read_b128 v[138:141], v116 offset:16
	ds_read_b128 v[250:253], v116 offset:32
	ds_read_b128 v[242:245], v116 offset:48
	s_add_u32 s92, s100, 1
	s_and_b32 s92, s92, 15
	v_lshl_add_u32 v117, s92, 9, v247
	ds_read_b128 v[84:87], v117
	ds_read_b128 v[88:91], v117 offset:16
	ds_read_b128 v[92:95], v117 offset:32
	ds_read_b128 v[96:99], v117 offset:48
	s_nop 1
	v_permlane32_swap_b32_e32 v64, v65
	v_permlane32_swap_b32_e32 v66, v67
	v_permlane32_swap_b32_e32 v68, v69
	v_permlane32_swap_b32_e32 v70, v71
	v_permlane32_swap_b32_e32 v72, v73
	v_permlane32_swap_b32_e32 v74, v75
	v_permlane32_swap_b32_e32 v76, v77
	v_permlane32_swap_b32_e32 v78, v79
	v_add_f32_e32 v64, v64, v65
	v_add_f32_e32 v66, v66, v67
	v_add_f32_e32 v68, v68, v69
	v_add_f32_e32 v70, v70, v71
	v_add_f32_e32 v72, v72, v73
	v_add_f32_e32 v74, v74, v75
	v_add_f32_e32 v76, v76, v77
	v_add_f32_e32 v78, v78, v79
	s_nop 1
	v_permlane16_swap_b32_e32 v64, v66
	v_permlane16_swap_b32_e32 v68, v70
	v_permlane16_swap_b32_e32 v72, v74
	v_permlane16_swap_b32_e32 v76, v78
	v_add_f32_e32 v64, v64, v66
	v_add_f32_e32 v68, v68, v70
	v_add_f32_e32 v72, v72, v74
	v_add_f32_e32 v76, v76, v78
	s_nop 0
	v_cndmask_b32_e64 v65, v64, v68, s[88:89]
	v_cndmask_b32_e64 v66, v68, v64, s[88:89]
	v_cndmask_b32_e64 v73, v72, v76, s[88:89]
	v_cndmask_b32_e64 v74, v76, v72, s[88:89]
	s_nop 1
	v_add_f32_dpp v64, v66, v65 row_ror:8 row_mask:0xf bank_mask:0xf
	v_add_f32_dpp v72, v74, v73 row_ror:8 row_mask:0xf bank_mask:0xf
	s_waitcnt vmcnt(16)
	v_fmac_f32_e32 v80, 0x3c800000, v64
	v_fmac_f32_e32 v81, 0x3c800000, v72
	global_store_dword v119, v80, s[82:83]
	global_store_dword v119, v81, s[82:83] offset:32
	s_add_u32 s100, s100, 1
	s_cmp_lt_u32 s100, 128
	s_cbranch_scc1 .Lpg0_vloop
	s_waitcnt vmcnt(0) lgkmcnt(0)
	v_readfirstlane_b32 s88, v130
	v_readfirstlane_b32 s89, v131
	s_nop 4
	v_lshlrev_b32_e32 v117, 6, v233
	global_load_dwordx4 v[16:19], v117, s[88:89] offset:0
	global_load_dwordx4 v[20:23], v117, s[88:89] offset:16
	global_load_dwordx4 v[24:27], v117, s[88:89] offset:32
	global_load_dwordx4 v[28:31], v117, s[88:89] offset:48
	s_mov_b32 s2, 0

; DEV void sort_lists(int lane, int& myi0, int& myi1, float& myg0, float& myg1) {
; #pragma unroll
;     for (int k = 2; k <= 128; k <<= 1) {
; #pragma unroll
;       for (int j = k >> 1; j >= 1; j >>= 1) {
;         if (j == 64) {
;           const bool sw_ = myi1 < myi0;
;           const int ti = sw_ ? myi1 : myi0, tj = sw_ ? myi0 : myi1; const float tg = sw_ ? myg1 : myg0, th = sw_ ? myg0 : myg1;
;           myi0 = ti; myi1 = tj; myg0 = tg; myg1 = th;
;         } else {
;           const bool lower = (lane & j) == 0;
;           {
;             const bool up = (k == 128) ? true : ((k == 64) ? true : ((lane & k) == 0));
;             const int oi = __shfl_xor(myi0, j); const float og = __shfl_xor(myg0, j);
;             const bool take = (lower == up) ? (oi < myi0) : (oi > myi0);
;             myi0 = take ? oi : myi0; myg0 = take ? og : myg0;
;           }
;           {
;             const bool up = (k == 128) ? true : ((k == 64) ? false : ((lane & k) == 0));
;             const int oi = __shfl_xor(myi1, j); const float og = __shfl_xor(myg1, j);
;             const bool take = (lower == up) ? (oi < myi1) : (oi > myi1);
;             myi1 = take ? oi : myi1; myg1 = take ? og : myg1;
;           }
;         }
;       }
;     }
; }
; DEV void peer_gather(const Params& P, int l, int m0, const int* idxs, const float* gs) {
;     ...
;   int ni0 = idxs[(wid * 16) * 128 + lane], ni1 = idxs[(wid * 16) * 128 + 64 + lane];
;   float ng0 = gs[(wid * 16) * 128 + lane], ng1 = gs[(wid * 16) * 128 + 64 + lane];
;   sort_lists(lane, ni0, ni1, ng0, ng1);
.Lpg1_p0:
	v_readlane_b32 s82, v231, 13
	v_readlane_b32 s83, v231, 14
	s_nop 4
	s_lshl_b32 s98, s2, 2
	s_add_u32 s98, s98, s33
	s_add_u32 s98, s98, 0
	s_lshl_b32 s98, s98, 9
	v_add_u32_e32 v116, s98, v234
	global_load_dword v241, v116, s[82:83]
	global_load_dword v242, v116, s[82:83] offset:256
	s_lshl_b32 s98, s2, 2
	s_add_u32 s98, s98, s33
	s_add_u32 s98, s98, 1
	s_lshl_b32 s98, s98, 9
	v_add_u32_e32 v117, s98, v234
	global_load_dword v243, v117, s[82:83]
	global_load_dword v244, v117, s[82:83] offset:256
	s_lshl_b32 s98, s2, 2
	s_add_u32 s98, s98, s33
	s_add_u32 s98, s98, 2
	s_lshl_b32 s98, s98, 9
	v_add_u32_e32 v118, s98, v234
	global_load_dword v245, v118, s[82:83]
	global_load_dword v246, v118, s[82:83] offset:256
	s_lshl_b32 s98, s2, 2
	s_add_u32 s98, s98, s33
	s_add_u32 s98, s98, 3
	s_lshl_b32 s98, s98, 9
	v_add_u32_e32 v119, s98, v234
	global_load_dword v247, v119, s[82:83]
	global_load_dword v248, v119, s[82:83] offset:256
	s_waitcnt vmcnt(0)
	v_or_b32_e32 v116, 64, v233
	v_lshl_or_b32 v241, v241, 7, v233
	v_lshl_or_b32 v242, v242, 7, v116
	v_lshl_or_b32 v243, v243, 7, v233
	v_lshl_or_b32 v244, v244, 7, v116
	v_lshl_or_b32 v245, v245, 7, v233
	v_lshl_or_b32 v246, v246, 7, v116
	v_lshl_or_b32 v247, v247, 7, v233
	v_lshl_or_b32 v248, v248, 7, v116
	v_xor_b32_e32 v116, 4, v234
	ds_bpermute_b32 v0, v116, v241
	ds_bpermute_b32 v1, v116, v243
	ds_bpermute_b32 v2, v116, v245
	ds_bpermute_b32 v3, v116, v247
	ds_bpermute_b32 v4, v116, v242
	ds_bpermute_b32 v5, v116, v244
	ds_bpermute_b32 v6, v116, v246
	ds_bpermute_b32 v7, v116, v248
	s_waitcnt lgkmcnt(0)
	s_mov_b32 s88, 0x99999999
	s_mov_b32 s89, 0x99999999
	v_min_u32_e32 v104, v241, v0
	v_max_u32_e32 v105, v241, v0
	v_cndmask_b32_e64 v241, v105, v104, s[88:89]
	v_min_u32_e32 v106, v243, v1
	v_max_u32_e32 v107, v243, v1
	v_cndmask_b32_e64 v243, v107, v106, s[88:89]
	v_min_u32_e32 v104, v245, v2
	v_max_u32_e32 v105, v245, v2
	v_cndmask_b32_e64 v245, v105, v104, s[88:89]
	v_min_u32_e32 v106, v247, v3
	v_max_u32_e32 v107, v247, v3
	v_cndmask_b32_e64 v247, v107, v106, s[88:89]
	v_min_u32_e32 v104, v242, v4
	v_max_u32_e32 v105, v242, v4
	v_cndmask_b32_e64 v242, v105, v104, s[88:89]
	v_min_u32_e32 v106, v244, v5
	v_max_u32_e32 v107, v244, v5
	v_cndmask_b32_e64 v244, v107, v106, s[88:89]
	v_min_u32_e32 v104, v246, v6
	v_max_u32_e32 v105, v246, v6
	v_cndmask_b32_e64 v246, v105, v104, s[88:89]
	v_min_u32_e32 v106, v248, v7
	v_max_u32_e32 v107, v248, v7
	v_cndmask_b32_e64 v248, v107, v106, s[88:89]
	v_xor_b32_e32 v116, 8, v234
	ds_bpermute_b32 v0, v116, v241
	ds_bpermute_b32 v1, v116, v243
	ds_bpermute_b32 v2, v116, v245
	ds_bpermute_b32 v3, v116, v247
	ds_bpermute_b32 v4, v116, v242
	ds_bpermute_b32 v5, v116, v244
	ds_bpermute_b32 v6, v116, v246
	ds_bpermute_b32 v7, v116, v248
	s_waitcnt lgkmcnt(0)
	s_mov_b32 s88, 0xc3c3c3c3
	s_mov_b32 s89, 0xc3c3c3c3
	v_min_u32_e32 v104, v241, v0
	v_max_u32_e32 v105, v241, v0
	v_cndmask_b32_e64 v241, v105, v104, s[88:89]
	v_min_u32_e32 v106, v243, v1
	v_max_u32_e32 v107, v243, v1
	v_cndmask_b32_e64 v243, v107, v106, s[88:89]
	v_min_u32_e32 v104, v245, v2
	v_max_u32_e32 v105, v245, v2
	v_cndmask_b32_e64 v245, v105, v104, s[88:89]
	v_min_u32_e32 v106, v247, v3
	v_max_u32_e32 v107, v247, v3
	v_cndmask_b32_e64 v247, v107, v106, s[88:89]
	v_min_u32_e32 v104, v242, v4
	v_max_u32_e32 v105, v242, v4
	v_cndmask_b32_e64 v242, v105, v104, s[88:89]
	v_min_u32_e32 v106, v244, v5
	v_max_u32_e32 v107, v244, v5
	v_cndmask_b32_e64 v244, v107, v106, s[88:89]
	v_min_u32_e32 v104, v246, v6
	v_max_u32_e32 v105, v246, v6
	v_cndmask_b32_e64 v246, v105, v104, s[88:89]
	v_min_u32_e32 v106, v248, v7
	v_max_u32_e32 v107, v248, v7
	v_cndmask_b32_e64 v248, v107, v106, s[88:89]
	v_xor_b32_e32 v116, 4, v234
	ds_bpermute_b32 v0, v116, v241
	ds_bpermute_b32 v1, v116, v243
	ds_bpermute_b32 v2, v116, v245
	ds_bpermute_b32 v3, v116, v247
	ds_bpermute_b32 v4, v116, v242
	ds_bpermute_b32 v5, v116, v244
	ds_bpermute_b32 v6, v116, v246
	ds_bpermute_b32 v7, v116, v248
	s_waitcnt lgkmcnt(0)
	s_mov_b32 s88, 0xa5a5a5a5
	s_mov_b32 s89, 0xa5a5a5a5
	v_min_u32_e32 v104, v241, v0
	v_max_u32_e32 v105, v241, v0
	v_cndmask_b32_e64 v241, v105, v104, s[88:89]
	v_min_u32_e32 v106, v243, v1
	v_max_u32_e32 v107, v243, v1
	v_cndmask_b32_e64 v243, v107, v106, s[88:89]
	v_min_u32_e32 v104, v245, v2
	v_max_u32_e32 v105, v245, v2
	v_cndmask_b32_e64 v245, v105, v104, s[88:89]
	v_min_u32_e32 v106, v247, v3
	v_max_u32_e32 v107, v247, v3
	v_cndmask_b32_e64 v247, v107, v106, s[88:89]
	v_min_u32_e32 v104, v242, v4
	v_max_u32_e32 v105, v242, v4
	v_cndmask_b32_e64 v242, v105, v104, s[88:89]
	v_min_u32_e32 v106, v244, v5
	v_max_u32_e32 v107, v244, v5
	v_cndmask_b32_e64 v244, v107, v106, s[88:89]
	v_min_u32_e32 v104, v246, v6
	v_max_u32_e32 v105, v246, v6
	v_cndmask_b32_e64 v246, v105, v104, s[88:89]
	v_min_u32_e32 v106, v248, v7
	v_max_u32_e32 v107, v248, v7
	v_cndmask_b32_e64 v248, v107, v106, s[88:89]
	v_xor_b32_e32 v116, 16, v234
	ds_bpermute_b32 v0, v116, v241
	ds_bpermute_b32 v1, v116, v243
	ds_bpermute_b32 v2, v116, v245
	ds_bpermute_b32 v3, v116, v247
	ds_bpermute_b32 v4, v116, v242
	ds_bpermute_b32 v5, v116, v244
	ds_bpermute_b32 v6, v116, v246
	ds_bpermute_b32 v7, v116, v248
	s_waitcnt lgkmcnt(0)
; DEV void sort_lists(int lane, int& myi0, int& myi1, float& myg0, float& myg1) {
; #pragma unroll
;     for (int k = 2; k <= 128; k <<= 1) {
; #pragma unroll
;       for (int j = k >> 1; j >= 1; j >>= 1) {
;         if (j == 64) {
;           const bool sw_ = myi1 < myi0;
;           const int ti = sw_ ? myi1 : myi0, tj = sw_ ? myi0 : myi1; const float tg = sw_ ? myg1 : myg0, th = sw_ ? myg0 : myg1;
;           myi0 = ti; myi1 = tj; myg0 = tg; myg1 = th;
;         } else {
;           const bool lower = (lane & j) == 0;
;           {
;             const bool up = (k == 128) ? true : ((k == 64) ? true : ((lane & k) == 0));
;             const int oi = __shfl_xor(myi0, j); const float og = __shfl_xor(myg0, j);
;             const bool take = (lower == up) ? (oi < myi0) : (oi > myi0);
;             myi0 = take ? oi : myi0; myg0 = take ? og : myg0;
;           }
;           {
;             const bool up = (k == 128) ? true : ((k == 64) ? false : ((lane & k) == 0));
;             const int oi = __shfl_xor(myi1, j); const float og = __shfl_xor(myg1, j);
;             const bool take = (lower == up) ? (oi < myi1) : (oi > myi1);
;             myi1 = take ? oi : myi1; myg1 = take ? og : myg1;
;           }
;         }
;       }
;     }
; }
	s_mov_b32 s88, 0xf00ff00f
	s_mov_b32 s89, 0xf00ff00f
	v_min_u32_e32 v104, v241, v0
	v_max_u32_e32 v105, v241, v0
	v_cndmask_b32_e64 v241, v105, v104, s[88:89]
	v_min_u32_e32 v106, v243, v1
	v_max_u32_e32 v107, v243, v1
	v_cndmask_b32_e64 v243, v107, v106, s[88:89]
	v_min_u32_e32 v104, v245, v2
	v_max_u32_e32 v105, v245, v2
	v_cndmask_b32_e64 v245, v105, v104, s[88:89]
	v_min_u32_e32 v106, v247, v3
	v_max_u32_e32 v107, v247, v3
	v_cndmask_b32_e64 v247, v107, v106, s[88:89]
	v_min_u32_e32 v104, v242, v4
	v_max_u32_e32 v105, v242, v4
	v_cndmask_b32_e64 v242, v105, v104, s[88:89]
	v_min_u32_e32 v106, v244, v5
	v_max_u32_e32 v107, v244, v5
	v_cndmask_b32_e64 v244, v107, v106, s[88:89]
	v_min_u32_e32 v104, v246, v6
	v_max_u32_e32 v105, v246, v6
	v_cndmask_b32_e64 v246, v105, v104, s[88:89]
	v_min_u32_e32 v106, v248, v7
	v_max_u32_e32 v107, v248, v7
	v_cndmask_b32_e64 v248, v107, v106, s[88:89]
	v_xor_b32_e32 v116, 8, v234
	ds_bpermute_b32 v0, v116, v241
	ds_bpermute_b32 v1, v116, v243
	ds_bpermute_b32 v2, v116, v245
	ds_bpermute_b32 v3, v116, v247
	ds_bpermute_b32 v4, v116, v242
	ds_bpermute_b32 v5, v116, v244
	ds_bpermute_b32 v6, v116, v246
	ds_bpermute_b32 v7, v116, v248
	s_waitcnt lgkmcnt(0)
	s_mov_b32 s88, 0xcc33cc33
	s_mov_b32 s89, 0xcc33cc33
	v_min_u32_e32 v104, v241, v0
	v_max_u32_e32 v105, v241, v0
	v_cndmask_b32_e64 v241, v105, v104, s[88:89]
	v_min_u32_e32 v106, v243, v1
	v_max_u32_e32 v107, v243, v1
	v_cndmask_b32_e64 v243, v107, v106, s[88:89]
	v_min_u32_e32 v104, v245, v2
	v_max_u32_e32 v105, v245, v2
	v_cndmask_b32_e64 v245, v105, v104, s[88:89]
	v_min_u32_e32 v106, v247, v3
	v_max_u32_e32 v107, v247, v3
	v_cndmask_b32_e64 v247, v107, v106, s[88:89]
	v_min_u32_e32 v104, v242, v4
	v_max_u32_e32 v105, v242, v4
	v_cndmask_b32_e64 v242, v105, v104, s[88:89]
	v_min_u32_e32 v106, v244, v5
	v_max_u32_e32 v107, v244, v5
	v_cndmask_b32_e64 v244, v107, v106, s[88:89]
	v_min_u32_e32 v104, v246, v6
	v_max_u32_e32 v105, v246, v6
	v_cndmask_b32_e64 v246, v105, v104, s[88:89]
	v_min_u32_e32 v106, v248, v7
	v_max_u32_e32 v107, v248, v7
	v_cndmask_b32_e64 v248, v107, v106, s[88:89]
	v_xor_b32_e32 v116, 4, v234
	ds_bpermute_b32 v0, v116, v241
	ds_bpermute_b32 v1, v116, v243
	ds_bpermute_b32 v2, v116, v245
	ds_bpermute_b32 v3, v116, v247
	ds_bpermute_b32 v4, v116, v242
	ds_bpermute_b32 v5, v116, v244
	ds_bpermute_b32 v6, v116, v246
	ds_bpermute_b32 v7, v116, v248
	s_waitcnt lgkmcnt(0)
	s_mov_b32 s88, 0xaa55aa55
	s_mov_b32 s89, 0xaa55aa55
	v_min_u32_e32 v104, v241, v0
	v_max_u32_e32 v105, v241, v0
	v_cndmask_b32_e64 v241, v105, v104, s[88:89]
	v_min_u32_e32 v106, v243, v1
	v_max_u32_e32 v107, v243, v1
	v_cndmask_b32_e64 v243, v107, v106, s[88:89]
	v_min_u32_e32 v104, v245, v2
	v_max_u32_e32 v105, v245, v2
	v_cndmask_b32_e64 v245, v105, v104, s[88:89]
	v_min_u32_e32 v106, v247, v3
	v_max_u32_e32 v107, v247, v3
	v_cndmask_b32_e64 v247, v107, v106, s[88:89]
	v_min_u32_e32 v104, v242, v4
	v_max_u32_e32 v105, v242, v4
	v_cndmask_b32_e64 v242, v105, v104, s[88:89]
	v_min_u32_e32 v106, v244, v5
	v_max_u32_e32 v107, v244, v5
	v_cndmask_b32_e64 v244, v107, v106, s[88:89]
	v_min_u32_e32 v104, v246, v6
	v_max_u32_e32 v105, v246, v6
	v_cndmask_b32_e64 v246, v105, v104, s[88:89]
	v_min_u32_e32 v106, v248, v7
	v_max_u32_e32 v107, v248, v7
	v_cndmask_b32_e64 v248, v107, v106, s[88:89]
	v_xor_b32_e32 v116, 32, v234
	ds_bpermute_b32 v0, v116, v241
	ds_bpermute_b32 v1, v116, v243
	ds_bpermute_b32 v2, v116, v245
	ds_bpermute_b32 v3, v116, v247
	ds_bpermute_b32 v4, v116, v242
	ds_bpermute_b32 v5, v116, v244
	ds_bpermute_b32 v6, v116, v246
	ds_bpermute_b32 v7, v116, v248
	s_waitcnt lgkmcnt(0)
	s_mov_b32 s88, 0xff0000ff
	s_mov_b32 s89, 0xff0000ff
	v_min_u32_e32 v104, v241, v0
	v_max_u32_e32 v105, v241, v0
	v_cndmask_b32_e64 v241, v105, v104, s[88:89]
	v_min_u32_e32 v106, v243, v1
	v_max_u32_e32 v107, v243, v1
	v_cndmask_b32_e64 v243, v107, v106, s[88:89]
	v_min_u32_e32 v104, v245, v2
	v_max_u32_e32 v105, v245, v2
	v_cndmask_b32_e64 v245, v105, v104, s[88:89]
	v_min_u32_e32 v106, v247, v3
	v_max_u32_e32 v107, v247, v3
	v_cndmask_b32_e64 v247, v107, v106, s[88:89]
	v_min_u32_e32 v104, v242, v4
	v_max_u32_e32 v105, v242, v4
	v_cndmask_b32_e64 v242, v105, v104, s[88:89]
	v_min_u32_e32 v106, v244, v5
	v_max_u32_e32 v107, v244, v5
	v_cndmask_b32_e64 v244, v107, v106, s[88:89]
	v_min_u32_e32 v104, v246, v6
	v_max_u32_e32 v105, v246, v6
	v_cndmask_b32_e64 v246, v105, v104, s[88:89]
	v_min_u32_e32 v106, v248, v7
	v_max_u32_e32 v107, v248, v7
	v_cndmask_b32_e64 v248, v107, v106, s[88:89]
	v_xor_b32_e32 v116, 16, v234
	ds_bpermute_b32 v0, v116, v241
	ds_bpermute_b32 v1, v116, v243
	ds_bpermute_b32 v2, v116, v245
	ds_bpermute_b32 v3, v116, v247
	ds_bpermute_b32 v4, v116, v242
	ds_bpermute_b32 v5, v116, v244
	ds_bpermute_b32 v6, v116, v246
	ds_bpermute_b32 v7, v116, v248
	s_waitcnt lgkmcnt(0)
	s_mov_b32 s88, 0xf0f00f0f
	s_mov_b32 s89, 0xf0f00f0f
	v_min_u32_e32 v104, v241, v0
	v_max_u32_e32 v105, v241, v0
	v_cndmask_b32_e64 v241, v105, v104, s[88:89]
	v_min_u32_e32 v106, v243, v1
	v_max_u32_e32 v107, v243, v1
	v_cndmask_b32_e64 v243, v107, v106, s[88:89]
	v_min_u32_e32 v104, v245, v2
	v_max_u32_e32 v105, v245, v2
	v_cndmask_b32_e64 v245, v105, v104, s[88:89]
	v_min_u32_e32 v106, v247, v3
	v_max_u32_e32 v107, v247, v3
	v_cndmask_b32_e64 v247, v107, v106, s[88:89]
	v_min_u32_e32 v104, v242, v4
	v_max_u32_e32 v105, v242, v4
	v_cndmask_b32_e64 v242, v105, v104, s[88:89]
	v_min_u32_e32 v106, v244, v5
	v_max_u32_e32 v107, v244, v5
	v_cndmask_b32_e64 v244, v107, v106, s[88:89]
	v_min_u32_e32 v104, v246, v6
	v_max_u32_e32 v105, v246, v6
	v_cndmask_b32_e64 v246, v105, v104, s[88:89]
	v_min_u32_e32 v106, v248, v7
	v_max_u32_e32 v107, v248, v7
	v_cndmask_b32_e64 v248, v107, v106, s[88:89]
	v_xor_b32_e32 v116, 8, v234
	ds_bpermute_b32 v0, v116, v241
	ds_bpermute_b32 v1, v116, v243
	ds_bpermute_b32 v2, v116, v245
	ds_bpermute_b32 v3, v116, v247
	ds_bpermute_b32 v4, v116, v242
	ds_bpermute_b32 v5, v116, v244
	ds_bpermute_b32 v6, v116, v246
	ds_bpermute_b32 v7, v116, v248
	s_waitcnt lgkmcnt(0)
; DEV void sort_lists(int lane, int& myi0, int& myi1, float& myg0, float& myg1) {
; #pragma unroll
;     for (int k = 2; k <= 128; k <<= 1) {
; #pragma unroll
;       for (int j = k >> 1; j >= 1; j >>= 1) {
;         if (j == 64) {
;           const bool sw_ = myi1 < myi0;
;           const int ti = sw_ ? myi1 : myi0, tj = sw_ ? myi0 : myi1; const float tg = sw_ ? myg1 : myg0, th = sw_ ? myg0 : myg1;
;           myi0 = ti; myi1 = tj; myg0 = tg; myg1 = th;
;         } else {
;           const bool lower = (lane & j) == 0;
;           {
;             const bool up = (k == 128) ? true : ((k == 64) ? true : ((lane & k) == 0));
;             const int oi = __shfl_xor(myi0, j); const float og = __shfl_xor(myg0, j);
;             const bool take = (lower == up) ? (oi < myi0) : (oi > myi0);
;             myi0 = take ? oi : myi0; myg0 = take ? og : myg0;
;           }
;           {
;             const bool up = (k == 128) ? true : ((k == 64) ? false : ((lane & k) == 0));
;             const int oi = __shfl_xor(myi1, j); const float og = __shfl_xor(myg1, j);
;             const bool take = (lower == up) ? (oi < myi1) : (oi > myi1);
;             myi1 = take ? oi : myi1; myg1 = take ? og : myg1;
;           }
;         }
;       }
;     }
; }
	s_mov_b32 s88, 0xcccc3333
	s_mov_b32 s89, 0xcccc3333
	v_min_u32_e32 v104, v241, v0
	v_max_u32_e32 v105, v241, v0
	v_cndmask_b32_e64 v241, v105, v104, s[88:89]
	v_min_u32_e32 v106, v243, v1
	v_max_u32_e32 v107, v243, v1
	v_cndmask_b32_e64 v243, v107, v106, s[88:89]
	v_min_u32_e32 v104, v245, v2
	v_max_u32_e32 v105, v245, v2
	v_cndmask_b32_e64 v245, v105, v104, s[88:89]
	v_min_u32_e32 v106, v247, v3
	v_max_u32_e32 v107, v247, v3
	v_cndmask_b32_e64 v247, v107, v106, s[88:89]
	v_min_u32_e32 v104, v242, v4
	v_max_u32_e32 v105, v242, v4
	v_cndmask_b32_e64 v242, v105, v104, s[88:89]
	v_min_u32_e32 v106, v244, v5
	v_max_u32_e32 v107, v244, v5
	v_cndmask_b32_e64 v244, v107, v106, s[88:89]
	v_min_u32_e32 v104, v246, v6
	v_max_u32_e32 v105, v246, v6
	v_cndmask_b32_e64 v246, v105, v104, s[88:89]
	v_min_u32_e32 v106, v248, v7
	v_max_u32_e32 v107, v248, v7
	v_cndmask_b32_e64 v248, v107, v106, s[88:89]
	v_xor_b32_e32 v116, 4, v234
	ds_bpermute_b32 v0, v116, v241
	ds_bpermute_b32 v1, v116, v243
	ds_bpermute_b32 v2, v116, v245
	ds_bpermute_b32 v3, v116, v247
	ds_bpermute_b32 v4, v116, v242
	ds_bpermute_b32 v5, v116, v244
	ds_bpermute_b32 v6, v116, v246
	ds_bpermute_b32 v7, v116, v248
	s_waitcnt lgkmcnt(0)
	s_mov_b32 s88, 0xaaaa5555
	s_mov_b32 s89, 0xaaaa5555
	v_min_u32_e32 v104, v241, v0
	v_max_u32_e32 v105, v241, v0
	v_cndmask_b32_e64 v241, v105, v104, s[88:89]
	v_min_u32_e32 v106, v243, v1
	v_max_u32_e32 v107, v243, v1
	v_cndmask_b32_e64 v243, v107, v106, s[88:89]
	v_min_u32_e32 v104, v245, v2
	v_max_u32_e32 v105, v245, v2
	v_cndmask_b32_e64 v245, v105, v104, s[88:89]
	v_min_u32_e32 v106, v247, v3
	v_max_u32_e32 v107, v247, v3
	v_cndmask_b32_e64 v247, v107, v106, s[88:89]
	v_min_u32_e32 v104, v242, v4
	v_max_u32_e32 v105, v242, v4
	v_cndmask_b32_e64 v242, v105, v104, s[88:89]
	v_min_u32_e32 v106, v244, v5
	v_max_u32_e32 v107, v244, v5
	v_cndmask_b32_e64 v244, v107, v106, s[88:89]
	v_min_u32_e32 v104, v246, v6
	v_max_u32_e32 v105, v246, v6
	v_cndmask_b32_e64 v246, v105, v104, s[88:89]
	v_min_u32_e32 v106, v248, v7
	v_max_u32_e32 v107, v248, v7
	v_cndmask_b32_e64 v248, v107, v106, s[88:89]
	v_xor_b32_e32 v116, 64, v234
	ds_bpermute_b32 v0, v116, v241
	ds_bpermute_b32 v1, v116, v243
	ds_bpermute_b32 v2, v116, v245
	ds_bpermute_b32 v3, v116, v247
	ds_bpermute_b32 v4, v116, v242
	ds_bpermute_b32 v5, v116, v244
	ds_bpermute_b32 v6, v116, v246
	ds_bpermute_b32 v7, v116, v248
	s_waitcnt lgkmcnt(0)
	s_mov_b32 s88, 0xffff
	s_mov_b32 s89, 0xffff0000
	v_min_u32_e32 v104, v241, v0
	v_max_u32_e32 v105, v241, v0
	v_cndmask_b32_e64 v241, v105, v104, s[88:89]
	v_min_u32_e32 v106, v243, v1
	v_max_u32_e32 v107, v243, v1
	v_cndmask_b32_e64 v243, v107, v106, s[88:89]
	v_min_u32_e32 v104, v245, v2
	v_max_u32_e32 v105, v245, v2
	v_cndmask_b32_e64 v245, v105, v104, s[88:89]
	v_min_u32_e32 v106, v247, v3
	v_max_u32_e32 v107, v247, v3
	v_cndmask_b32_e64 v247, v107, v106, s[88:89]
	v_min_u32_e32 v104, v242, v4
	v_max_u32_e32 v105, v242, v4
	v_cndmask_b32_e64 v242, v105, v104, s[88:89]
	v_min_u32_e32 v106, v244, v5
	v_max_u32_e32 v107, v244, v5
	v_cndmask_b32_e64 v244, v107, v106, s[88:89]
	v_min_u32_e32 v104, v246, v6
	v_max_u32_e32 v105, v246, v6
	v_cndmask_b32_e64 v246, v105, v104, s[88:89]
	v_min_u32_e32 v106, v248, v7
	v_max_u32_e32 v107, v248, v7
	v_cndmask_b32_e64 v248, v107, v106, s[88:89]
	v_xor_b32_e32 v116, 32, v234
	ds_bpermute_b32 v0, v116, v241
	ds_bpermute_b32 v1, v116, v243
	ds_bpermute_b32 v2, v116, v245
	ds_bpermute_b32 v3, v116, v247
	ds_bpermute_b32 v4, v116, v242
	ds_bpermute_b32 v5, v116, v244
	ds_bpermute_b32 v6, v116, v246
	ds_bpermute_b32 v7, v116, v248
	s_waitcnt lgkmcnt(0)
	s_mov_b32 s88, 0xff00ff
	s_mov_b32 s89, 0xff00ff00
	v_min_u32_e32 v104, v241, v0
	v_max_u32_e32 v105, v241, v0
	v_cndmask_b32_e64 v241, v105, v104, s[88:89]
	v_min_u32_e32 v106, v243, v1
	v_max_u32_e32 v107, v243, v1
	v_cndmask_b32_e64 v243, v107, v106, s[88:89]
	v_min_u32_e32 v104, v245, v2
	v_max_u32_e32 v105, v245, v2
	v_cndmask_b32_e64 v245, v105, v104, s[88:89]
	v_min_u32_e32 v106, v247, v3
	v_max_u32_e32 v107, v247, v3
	v_cndmask_b32_e64 v247, v107, v106, s[88:89]
	v_min_u32_e32 v104, v242, v4
	v_max_u32_e32 v105, v242, v4
	v_cndmask_b32_e64 v242, v105, v104, s[88:89]
	v_min_u32_e32 v106, v244, v5
	v_max_u32_e32 v107, v244, v5
	v_cndmask_b32_e64 v244, v107, v106, s[88:89]
	v_min_u32_e32 v104, v246, v6
	v_max_u32_e32 v105, v246, v6
	v_cndmask_b32_e64 v246, v105, v104, s[88:89]
	v_min_u32_e32 v106, v248, v7
	v_max_u32_e32 v107, v248, v7
	v_cndmask_b32_e64 v248, v107, v106, s[88:89]
	v_xor_b32_e32 v116, 16, v234
	ds_bpermute_b32 v0, v116, v241
	ds_bpermute_b32 v1, v116, v243
	ds_bpermute_b32 v2, v116, v245
	ds_bpermute_b32 v3, v116, v247
	ds_bpermute_b32 v4, v116, v242
	ds_bpermute_b32 v5, v116, v244
	ds_bpermute_b32 v6, v116, v246
	ds_bpermute_b32 v7, v116, v248
	s_waitcnt lgkmcnt(0)
	s_mov_b32 s88, 0xf0f0f0f
	s_mov_b32 s89, 0xf0f0f0f0
	v_min_u32_e32 v104, v241, v0
	v_max_u32_e32 v105, v241, v0
	v_cndmask_b32_e64 v241, v105, v104, s[88:89]
	v_min_u32_e32 v106, v243, v1
	v_max_u32_e32 v107, v243, v1
	v_cndmask_b32_e64 v243, v107, v106, s[88:89]
	v_min_u32_e32 v104, v245, v2
	v_max_u32_e32 v105, v245, v2
	v_cndmask_b32_e64 v245, v105, v104, s[88:89]
	v_min_u32_e32 v106, v247, v3
	v_max_u32_e32 v107, v247, v3
	v_cndmask_b32_e64 v247, v107, v106, s[88:89]
	v_min_u32_e32 v104, v242, v4
	v_max_u32_e32 v105, v242, v4
	v_cndmask_b32_e64 v242, v105, v104, s[88:89]
	v_min_u32_e32 v106, v244, v5
	v_max_u32_e32 v107, v244, v5
	v_cndmask_b32_e64 v244, v107, v106, s[88:89]
	v_min_u32_e32 v104, v246, v6
	v_max_u32_e32 v105, v246, v6
	v_cndmask_b32_e64 v246, v105, v104, s[88:89]
	v_min_u32_e32 v106, v248, v7
	v_max_u32_e32 v107, v248, v7
	v_cndmask_b32_e64 v248, v107, v106, s[88:89]
	v_xor_b32_e32 v116, 8, v234
	ds_bpermute_b32 v0, v116, v241
	ds_bpermute_b32 v1, v116, v243
	ds_bpermute_b32 v2, v116, v245
	ds_bpermute_b32 v3, v116, v247
	ds_bpermute_b32 v4, v116, v242
	ds_bpermute_b32 v5, v116, v244
	ds_bpermute_b32 v6, v116, v246
	ds_bpermute_b32 v7, v116, v248
	s_waitcnt lgkmcnt(0)
; DEV void sort_lists(int lane, int& myi0, int& myi1, float& myg0, float& myg1) {
; #pragma unroll
;     for (int k = 2; k <= 128; k <<= 1) {
; #pragma unroll
;       for (int j = k >> 1; j >= 1; j >>= 1) {
;         if (j == 64) {
;           const bool sw_ = myi1 < myi0;
;           const int ti = sw_ ? myi1 : myi0, tj = sw_ ? myi0 : myi1; const float tg = sw_ ? myg1 : myg0, th = sw_ ? myg0 : myg1;
;           myi0 = ti; myi1 = tj; myg0 = tg; myg1 = th;
;         } else {
;           const bool lower = (lane & j) == 0;
;           {
;             const bool up = (k == 128) ? true : ((k == 64) ? true : ((lane & k) == 0));
;             const int oi = __shfl_xor(myi0, j); const float og = __shfl_xor(myg0, j);
;             const bool take = (lower == up) ? (oi < myi0) : (oi > myi0);
;             myi0 = take ? oi : myi0; myg0 = take ? og : myg0;
;           }
;           {
;             const bool up = (k == 128) ? true : ((k == 64) ? false : ((lane & k) == 0));
;             const int oi = __shfl_xor(myi1, j); const float og = __shfl_xor(myg1, j);
;             const bool take = (lower == up) ? (oi < myi1) : (oi > myi1);
;             myi1 = take ? oi : myi1; myg1 = take ? og : myg1;
;           }
;         }
;       }
;     }
; }
	s_mov_b32 s88, 0x33333333
	s_mov_b32 s89, 0xcccccccc
	v_min_u32_e32 v104, v241, v0
	v_max_u32_e32 v105, v241, v0
	v_cndmask_b32_e64 v241, v105, v104, s[88:89]
	v_min_u32_e32 v106, v243, v1
	v_max_u32_e32 v107, v243, v1
	v_cndmask_b32_e64 v243, v107, v106, s[88:89]
	v_min_u32_e32 v104, v245, v2
	v_max_u32_e32 v105, v245, v2
	v_cndmask_b32_e64 v245, v105, v104, s[88:89]
	v_min_u32_e32 v106, v247, v3
	v_max_u32_e32 v107, v247, v3
	v_cndmask_b32_e64 v247, v107, v106, s[88:89]
	v_min_u32_e32 v104, v242, v4
	v_max_u32_e32 v105, v242, v4
	v_cndmask_b32_e64 v242, v105, v104, s[88:89]
	v_min_u32_e32 v106, v244, v5
	v_max_u32_e32 v107, v244, v5
	v_cndmask_b32_e64 v244, v107, v106, s[88:89]
	v_min_u32_e32 v104, v246, v6
	v_max_u32_e32 v105, v246, v6
	v_cndmask_b32_e64 v246, v105, v104, s[88:89]
	v_min_u32_e32 v106, v248, v7
	v_max_u32_e32 v107, v248, v7
	v_cndmask_b32_e64 v248, v107, v106, s[88:89]
	v_xor_b32_e32 v116, 4, v234
	ds_bpermute_b32 v0, v116, v241
	ds_bpermute_b32 v1, v116, v243
	ds_bpermute_b32 v2, v116, v245
	ds_bpermute_b32 v3, v116, v247
	ds_bpermute_b32 v4, v116, v242
	ds_bpermute_b32 v5, v116, v244
	ds_bpermute_b32 v6, v116, v246
	ds_bpermute_b32 v7, v116, v248
	s_waitcnt lgkmcnt(0)
	s_mov_b32 s88, 0x55555555
	s_mov_b32 s89, 0xaaaaaaaa
	v_min_u32_e32 v104, v241, v0
	v_max_u32_e32 v105, v241, v0
	v_cndmask_b32_e64 v241, v105, v104, s[88:89]
	v_min_u32_e32 v106, v243, v1
	v_max_u32_e32 v107, v243, v1
	v_cndmask_b32_e64 v243, v107, v106, s[88:89]
	v_min_u32_e32 v104, v245, v2
	v_max_u32_e32 v105, v245, v2
	v_cndmask_b32_e64 v245, v105, v104, s[88:89]
	v_min_u32_e32 v106, v247, v3
	v_max_u32_e32 v107, v247, v3
	v_cndmask_b32_e64 v247, v107, v106, s[88:89]
	v_min_u32_e32 v104, v242, v4
	v_max_u32_e32 v105, v242, v4
	v_cndmask_b32_e64 v242, v105, v104, s[88:89]
	v_min_u32_e32 v106, v244, v5
	v_max_u32_e32 v107, v244, v5
	v_cndmask_b32_e64 v244, v107, v106, s[88:89]
	v_min_u32_e32 v104, v246, v6
	v_max_u32_e32 v105, v246, v6
	v_cndmask_b32_e64 v246, v105, v104, s[88:89]
	v_min_u32_e32 v106, v248, v7
	v_max_u32_e32 v107, v248, v7
	v_cndmask_b32_e64 v248, v107, v106, s[88:89]
	v_xor_b32_e32 v116, 128, v234
	ds_bpermute_b32 v0, v116, v241
	ds_bpermute_b32 v1, v116, v243
	ds_bpermute_b32 v2, v116, v245
	ds_bpermute_b32 v3, v116, v247
	ds_bpermute_b32 v4, v116, v242
	ds_bpermute_b32 v5, v116, v244
	ds_bpermute_b32 v6, v116, v246
	ds_bpermute_b32 v7, v116, v248
	s_waitcnt lgkmcnt(0)
	s_mov_b32 s88, 0xffffffff
	s_mov_b32 s89, 0x0
	v_min_u32_e32 v104, v241, v0
	v_max_u32_e32 v105, v241, v0
	v_cndmask_b32_e64 v241, v105, v104, s[88:89]
	v_min_u32_e32 v106, v243, v1
	v_max_u32_e32 v107, v243, v1
	v_cndmask_b32_e64 v243, v107, v106, s[88:89]
	v_min_u32_e32 v104, v245, v2
	v_max_u32_e32 v105, v245, v2
	v_cndmask_b32_e64 v245, v105, v104, s[88:89]
	v_min_u32_e32 v106, v247, v3
	v_max_u32_e32 v107, v247, v3
	v_cndmask_b32_e64 v247, v107, v106, s[88:89]
	s_mov_b32 s88, 0x0
	s_mov_b32 s89, 0xffffffff
	v_min_u32_e32 v104, v242, v4
	v_max_u32_e32 v105, v242, v4
	v_cndmask_b32_e64 v242, v105, v104, s[88:89]
	v_min_u32_e32 v106, v244, v5
	v_max_u32_e32 v107, v244, v5
	v_cndmask_b32_e64 v244, v107, v106, s[88:89]
	v_min_u32_e32 v104, v246, v6
	v_max_u32_e32 v105, v246, v6
	v_cndmask_b32_e64 v246, v105, v104, s[88:89]
	v_min_u32_e32 v106, v248, v7
	v_max_u32_e32 v107, v248, v7
	v_cndmask_b32_e64 v248, v107, v106, s[88:89]
	v_xor_b32_e32 v116, 64, v234
	ds_bpermute_b32 v0, v116, v241
	ds_bpermute_b32 v1, v116, v243
	ds_bpermute_b32 v2, v116, v245
	ds_bpermute_b32 v3, v116, v247
	ds_bpermute_b32 v4, v116, v242
	ds_bpermute_b32 v5, v116, v244
	ds_bpermute_b32 v6, v116, v246
	ds_bpermute_b32 v7, v116, v248
	s_waitcnt lgkmcnt(0)
	s_mov_b32 s88, 0xffff
	s_mov_b32 s89, 0xffff
	v_min_u32_e32 v104, v241, v0
	v_max_u32_e32 v105, v241, v0
	v_cndmask_b32_e64 v241, v105, v104, s[88:89]
	v_min_u32_e32 v106, v243, v1
	v_max_u32_e32 v107, v243, v1
	v_cndmask_b32_e64 v243, v107, v106, s[88:89]
	v_min_u32_e32 v104, v245, v2
	v_max_u32_e32 v105, v245, v2
	v_cndmask_b32_e64 v245, v105, v104, s[88:89]
	v_min_u32_e32 v106, v247, v3
	v_max_u32_e32 v107, v247, v3
	v_cndmask_b32_e64 v247, v107, v106, s[88:89]
	s_mov_b32 s88, 0xffff0000
	s_mov_b32 s89, 0xffff0000
	v_min_u32_e32 v104, v242, v4
	v_max_u32_e32 v105, v242, v4
	v_cndmask_b32_e64 v242, v105, v104, s[88:89]
	v_min_u32_e32 v106, v244, v5
	v_max_u32_e32 v107, v244, v5
	v_cndmask_b32_e64 v244, v107, v106, s[88:89]
	v_min_u32_e32 v104, v246, v6
	v_max_u32_e32 v105, v246, v6
	v_cndmask_b32_e64 v246, v105, v104, s[88:89]
	v_min_u32_e32 v106, v248, v7
	v_max_u32_e32 v107, v248, v7
	v_cndmask_b32_e64 v248, v107, v106, s[88:89]
	v_xor_b32_e32 v116, 32, v234
	ds_bpermute_b32 v0, v116, v241
	ds_bpermute_b32 v1, v116, v243
	ds_bpermute_b32 v2, v116, v245
	ds_bpermute_b32 v3, v116, v247
	ds_bpermute_b32 v4, v116, v242
	ds_bpermute_b32 v5, v116, v244
	ds_bpermute_b32 v6, v116, v246
	ds_bpermute_b32 v7, v116, v248
	s_waitcnt lgkmcnt(0)
	s_mov_b32 s88, 0xff00ff
	s_mov_b32 s89, 0xff00ff
	v_min_u32_e32 v104, v241, v0
	v_max_u32_e32 v105, v241, v0
	v_cndmask_b32_e64 v241, v105, v104, s[88:89]
	v_min_u32_e32 v106, v243, v1
	v_max_u32_e32 v107, v243, v1
	v_cndmask_b32_e64 v243, v107, v106, s[88:89]
	v_min_u32_e32 v104, v245, v2
	v_max_u32_e32 v105, v245, v2
	v_cndmask_b32_e64 v245, v105, v104, s[88:89]
	v_min_u32_e32 v106, v247, v3
	v_max_u32_e32 v107, v247, v3
	v_cndmask_b32_e64 v247, v107, v106, s[88:89]
	s_mov_b32 s88, 0xff00ff00
	s_mov_b32 s89, 0xff00ff00
	v_min_u32_e32 v104, v242, v4
	v_max_u32_e32 v105, v242, v4
	v_cndmask_b32_e64 v242, v105, v104, s[88:89]
	v_min_u32_e32 v106, v244, v5
	v_max_u32_e32 v107, v244, v5
	v_cndmask_b32_e64 v244, v107, v106, s[88:89]
	v_min_u32_e32 v104, v246, v6
	v_max_u32_e32 v105, v246, v6
	v_cndmask_b32_e64 v246, v105, v104, s[88:89]
	v_min_u32_e32 v106, v248, v7
	v_max_u32_e32 v107, v248, v7
	v_cndmask_b32_e64 v248, v107, v106, s[88:89]
	v_xor_b32_e32 v116, 16, v234
	ds_bpermute_b32 v0, v116, v241
	ds_bpermute_b32 v1, v116, v243
	ds_bpermute_b32 v2, v116, v245
	ds_bpermute_b32 v3, v116, v247
	ds_bpermute_b32 v4, v116, v242
	ds_bpermute_b32 v5, v116, v244
	ds_bpermute_b32 v6, v116, v246
	ds_bpermute_b32 v7, v116, v248
	s_waitcnt lgkmcnt(0)
; DEV void sort_lists(int lane, int& myi0, int& myi1, float& myg0, float& myg1) {
; #pragma unroll
;     for (int k = 2; k <= 128; k <<= 1) {
; #pragma unroll
;       for (int j = k >> 1; j >= 1; j >>= 1) {
;         if (j == 64) {
;           const bool sw_ = myi1 < myi0;
;           const int ti = sw_ ? myi1 : myi0, tj = sw_ ? myi0 : myi1; const float tg = sw_ ? myg1 : myg0, th = sw_ ? myg0 : myg1;
;           myi0 = ti; myi1 = tj; myg0 = tg; myg1 = th;
;         } else {
;           const bool lower = (lane & j) == 0;
;           {
;             const bool up = (k == 128) ? true : ((k == 64) ? true : ((lane & k) == 0));
;             const int oi = __shfl_xor(myi0, j); const float og = __shfl_xor(myg0, j);
;             const bool take = (lower == up) ? (oi < myi0) : (oi > myi0);
;             myi0 = take ? oi : myi0; myg0 = take ? og : myg0;
;           }
;           {
;             const bool up = (k == 128) ? true : ((k == 64) ? false : ((lane & k) == 0));
;             const int oi = __shfl_xor(myi1, j); const float og = __shfl_xor(myg1, j);
;             const bool take = (lower == up) ? (oi < myi1) : (oi > myi1);
;             myi1 = take ? oi : myi1; myg1 = take ? og : myg1;
;           }
;         }
;       }
;     }
; }
	s_mov_b32 s88, 0xf0f0f0f
	s_mov_b32 s89, 0xf0f0f0f
	v_min_u32_e32 v104, v241, v0
	v_max_u32_e32 v105, v241, v0
	v_cndmask_b32_e64 v241, v105, v104, s[88:89]
	v_min_u32_e32 v106, v243, v1
	v_max_u32_e32 v107, v243, v1
	v_cndmask_b32_e64 v243, v107, v106, s[88:89]
	v_min_u32_e32 v104, v245, v2
	v_max_u32_e32 v105, v245, v2
	v_cndmask_b32_e64 v245, v105, v104, s[88:89]
	v_min_u32_e32 v106, v247, v3
	v_max_u32_e32 v107, v247, v3
	v_cndmask_b32_e64 v247, v107, v106, s[88:89]
	s_mov_b32 s88, 0xf0f0f0f0
	s_mov_b32 s89, 0xf0f0f0f0
	v_min_u32_e32 v104, v242, v4
	v_max_u32_e32 v105, v242, v4
	v_cndmask_b32_e64 v242, v105, v104, s[88:89]
	v_min_u32_e32 v106, v244, v5
	v_max_u32_e32 v107, v244, v5
	v_cndmask_b32_e64 v244, v107, v106, s[88:89]
	v_min_u32_e32 v104, v246, v6
	v_max_u32_e32 v105, v246, v6
	v_cndmask_b32_e64 v246, v105, v104, s[88:89]
	v_min_u32_e32 v106, v248, v7
	v_max_u32_e32 v107, v248, v7
	v_cndmask_b32_e64 v248, v107, v106, s[88:89]
	v_xor_b32_e32 v116, 8, v234
	ds_bpermute_b32 v0, v116, v241
	ds_bpermute_b32 v1, v116, v243
	ds_bpermute_b32 v2, v116, v245
	ds_bpermute_b32 v3, v116, v247
	ds_bpermute_b32 v4, v116, v242
	ds_bpermute_b32 v5, v116, v244
	ds_bpermute_b32 v6, v116, v246
	ds_bpermute_b32 v7, v116, v248
	s_waitcnt lgkmcnt(0)
	s_mov_b32 s88, 0x33333333
	s_mov_b32 s89, 0x33333333
	v_min_u32_e32 v104, v241, v0
	v_max_u32_e32 v105, v241, v0
	v_cndmask_b32_e64 v241, v105, v104, s[88:89]
	v_min_u32_e32 v106, v243, v1
	v_max_u32_e32 v107, v243, v1
	v_cndmask_b32_e64 v243, v107, v106, s[88:89]
	v_min_u32_e32 v104, v245, v2
	v_max_u32_e32 v105, v245, v2
	v_cndmask_b32_e64 v245, v105, v104, s[88:89]
	v_min_u32_e32 v106, v247, v3
	v_max_u32_e32 v107, v247, v3
	v_cndmask_b32_e64 v247, v107, v106, s[88:89]
	s_mov_b32 s88, 0xcccccccc
	s_mov_b32 s89, 0xcccccccc
	v_min_u32_e32 v104, v242, v4
	v_max_u32_e32 v105, v242, v4
	v_cndmask_b32_e64 v242, v105, v104, s[88:89]
	v_min_u32_e32 v106, v244, v5
	v_max_u32_e32 v107, v244, v5
	v_cndmask_b32_e64 v244, v107, v106, s[88:89]
	v_min_u32_e32 v104, v246, v6
	v_max_u32_e32 v105, v246, v6
	v_cndmask_b32_e64 v246, v105, v104, s[88:89]
	v_min_u32_e32 v106, v248, v7
	v_max_u32_e32 v107, v248, v7
	v_cndmask_b32_e64 v248, v107, v106, s[88:89]
	v_xor_b32_e32 v116, 4, v234
	ds_bpermute_b32 v0, v116, v241
	ds_bpermute_b32 v1, v116, v243
	ds_bpermute_b32 v2, v116, v245
	ds_bpermute_b32 v3, v116, v247
	ds_bpermute_b32 v4, v116, v242
	ds_bpermute_b32 v5, v116, v244
	ds_bpermute_b32 v6, v116, v246
	ds_bpermute_b32 v7, v116, v248
	s_waitcnt lgkmcnt(0)
	s_mov_b32 s88, 0x55555555
	s_mov_b32 s89, 0x55555555
	v_min_u32_e32 v104, v241, v0
	v_max_u32_e32 v105, v241, v0
	v_cndmask_b32_e64 v241, v105, v104, s[88:89]
	v_min_u32_e32 v106, v243, v1
	v_max_u32_e32 v107, v243, v1
	v_cndmask_b32_e64 v243, v107, v106, s[88:89]
	v_min_u32_e32 v104, v245, v2
	v_max_u32_e32 v105, v245, v2
	v_cndmask_b32_e64 v245, v105, v104, s[88:89]
	v_min_u32_e32 v106, v247, v3
	v_max_u32_e32 v107, v247, v3
	v_cndmask_b32_e64 v247, v107, v106, s[88:89]
	s_mov_b32 s88, 0xaaaaaaaa
	s_mov_b32 s89, 0xaaaaaaaa
	v_min_u32_e32 v104, v242, v4
	v_max_u32_e32 v105, v242, v4
	v_cndmask_b32_e64 v242, v105, v104, s[88:89]
	v_min_u32_e32 v106, v244, v5
	v_max_u32_e32 v107, v244, v5
	v_cndmask_b32_e64 v244, v107, v106, s[88:89]
	v_min_u32_e32 v104, v246, v6
	v_max_u32_e32 v105, v246, v6
	v_cndmask_b32_e64 v246, v105, v104, s[88:89]
	v_min_u32_e32 v106, v248, v7
	v_max_u32_e32 v107, v248, v7
	v_cndmask_b32_e64 v248, v107, v106, s[88:89]
	v_min_u32_e32 v104, v241, v242
	v_max_u32_e32 v242, v241, v242
	v_mov_b32_e32 v241, v104
	v_min_u32_e32 v106, v243, v244
	v_max_u32_e32 v244, v243, v244
	v_mov_b32_e32 v243, v106
	v_min_u32_e32 v104, v245, v246
	v_max_u32_e32 v246, v245, v246
	v_mov_b32_e32 v245, v104
	v_min_u32_e32 v106, v247, v248
	v_max_u32_e32 v248, v247, v248
	v_mov_b32_e32 v247, v106
	v_xor_b32_e32 v116, 128, v234
	ds_bpermute_b32 v0, v116, v241
	ds_bpermute_b32 v1, v116, v243
	ds_bpermute_b32 v2, v116, v245
	ds_bpermute_b32 v3, v116, v247
	ds_bpermute_b32 v4, v116, v242
	ds_bpermute_b32 v5, v116, v244
	ds_bpermute_b32 v6, v116, v246
	ds_bpermute_b32 v7, v116, v248
	s_waitcnt lgkmcnt(0)
	s_mov_b32 s88, 0xffffffff
	s_mov_b32 s89, 0x0
	v_min_u32_e32 v104, v241, v0
	v_max_u32_e32 v105, v241, v0
	v_cndmask_b32_e64 v241, v105, v104, s[88:89]
	v_min_u32_e32 v106, v243, v1
	v_max_u32_e32 v107, v243, v1
	v_cndmask_b32_e64 v243, v107, v106, s[88:89]
	v_min_u32_e32 v104, v245, v2
	v_max_u32_e32 v105, v245, v2
	v_cndmask_b32_e64 v245, v105, v104, s[88:89]
	v_min_u32_e32 v106, v247, v3
	v_max_u32_e32 v107, v247, v3
	v_cndmask_b32_e64 v247, v107, v106, s[88:89]
	v_min_u32_e32 v104, v242, v4
	v_max_u32_e32 v105, v242, v4
	v_cndmask_b32_e64 v242, v105, v104, s[88:89]
	v_min_u32_e32 v106, v244, v5
	v_max_u32_e32 v107, v244, v5
	v_cndmask_b32_e64 v244, v107, v106, s[88:89]
	v_min_u32_e32 v104, v246, v6
	v_max_u32_e32 v105, v246, v6
	v_cndmask_b32_e64 v246, v105, v104, s[88:89]
	v_min_u32_e32 v106, v248, v7
	v_max_u32_e32 v107, v248, v7
	v_cndmask_b32_e64 v248, v107, v106, s[88:89]
	v_xor_b32_e32 v116, 64, v234
	ds_bpermute_b32 v0, v116, v241
	ds_bpermute_b32 v1, v116, v243
	ds_bpermute_b32 v2, v116, v245
	ds_bpermute_b32 v3, v116, v247
	ds_bpermute_b32 v4, v116, v242
	ds_bpermute_b32 v5, v116, v244
	ds_bpermute_b32 v6, v116, v246
	ds_bpermute_b32 v7, v116, v248
	s_waitcnt lgkmcnt(0)
; DEV void sort_lists(int lane, int& myi0, int& myi1, float& myg0, float& myg1) {
; #pragma unroll
;     for (int k = 2; k <= 128; k <<= 1) {
; #pragma unroll
;       for (int j = k >> 1; j >= 1; j >>= 1) {
;         if (j == 64) {
;           const bool sw_ = myi1 < myi0;
;           const int ti = sw_ ? myi1 : myi0, tj = sw_ ? myi0 : myi1; const float tg = sw_ ? myg1 : myg0, th = sw_ ? myg0 : myg1;
;           myi0 = ti; myi1 = tj; myg0 = tg; myg1 = th;
;         } else {
;           const bool lower = (lane & j) == 0;
;           {
;             const bool up = (k == 128) ? true : ((k == 64) ? true : ((lane & k) == 0));
;             const int oi = __shfl_xor(myi0, j); const float og = __shfl_xor(myg0, j);
;             const bool take = (lower == up) ? (oi < myi0) : (oi > myi0);
;             myi0 = take ? oi : myi0; myg0 = take ? og : myg0;
;           }
;           {
;             const bool up = (k == 128) ? true : ((k == 64) ? false : ((lane & k) == 0));
;             const int oi = __shfl_xor(myi1, j); const float og = __shfl_xor(myg1, j);
;             const bool take = (lower == up) ? (oi < myi1) : (oi > myi1);
;             myi1 = take ? oi : myi1; myg1 = take ? og : myg1;
;           }
;         }
;       }
;     }
; }
	s_mov_b32 s88, 0xffff
	s_mov_b32 s89, 0xffff
	v_min_u32_e32 v104, v241, v0
	v_max_u32_e32 v105, v241, v0
	v_cndmask_b32_e64 v241, v105, v104, s[88:89]
	v_min_u32_e32 v106, v243, v1
	v_max_u32_e32 v107, v243, v1
	v_cndmask_b32_e64 v243, v107, v106, s[88:89]
	v_min_u32_e32 v104, v245, v2
	v_max_u32_e32 v105, v245, v2
	v_cndmask_b32_e64 v245, v105, v104, s[88:89]
	v_min_u32_e32 v106, v247, v3
	v_max_u32_e32 v107, v247, v3
	v_cndmask_b32_e64 v247, v107, v106, s[88:89]
	v_min_u32_e32 v104, v242, v4
	v_max_u32_e32 v105, v242, v4
	v_cndmask_b32_e64 v242, v105, v104, s[88:89]
	v_min_u32_e32 v106, v244, v5
	v_max_u32_e32 v107, v244, v5
	v_cndmask_b32_e64 v244, v107, v106, s[88:89]
	v_min_u32_e32 v104, v246, v6
	v_max_u32_e32 v105, v246, v6
	v_cndmask_b32_e64 v246, v105, v104, s[88:89]
	v_min_u32_e32 v106, v248, v7
	v_max_u32_e32 v107, v248, v7
	v_cndmask_b32_e64 v248, v107, v106, s[88:89]
	v_xor_b32_e32 v116, 32, v234
	ds_bpermute_b32 v0, v116, v241
	ds_bpermute_b32 v1, v116, v243
	ds_bpermute_b32 v2, v116, v245
	ds_bpermute_b32 v3, v116, v247
	ds_bpermute_b32 v4, v116, v242
	ds_bpermute_b32 v5, v116, v244
	ds_bpermute_b32 v6, v116, v246
	ds_bpermute_b32 v7, v116, v248
	s_waitcnt lgkmcnt(0)
	s_mov_b32 s88, 0xff00ff
	s_mov_b32 s89, 0xff00ff
	v_min_u32_e32 v104, v241, v0
	v_max_u32_e32 v105, v241, v0
	v_cndmask_b32_e64 v241, v105, v104, s[88:89]
	v_min_u32_e32 v106, v243, v1
	v_max_u32_e32 v107, v243, v1
	v_cndmask_b32_e64 v243, v107, v106, s[88:89]
	v_min_u32_e32 v104, v245, v2
	v_max_u32_e32 v105, v245, v2
	v_cndmask_b32_e64 v245, v105, v104, s[88:89]
	v_min_u32_e32 v106, v247, v3
	v_max_u32_e32 v107, v247, v3
	v_cndmask_b32_e64 v247, v107, v106, s[88:89]
	v_min_u32_e32 v104, v242, v4
	v_max_u32_e32 v105, v242, v4
	v_cndmask_b32_e64 v242, v105, v104, s[88:89]
	v_min_u32_e32 v106, v244, v5
	v_max_u32_e32 v107, v244, v5
	v_cndmask_b32_e64 v244, v107, v106, s[88:89]
	v_min_u32_e32 v104, v246, v6
	v_max_u32_e32 v105, v246, v6
	v_cndmask_b32_e64 v246, v105, v104, s[88:89]
	v_min_u32_e32 v106, v248, v7
	v_max_u32_e32 v107, v248, v7
	v_cndmask_b32_e64 v248, v107, v106, s[88:89]
	v_xor_b32_e32 v116, 16, v234
	ds_bpermute_b32 v0, v116, v241
	ds_bpermute_b32 v1, v116, v243
	ds_bpermute_b32 v2, v116, v245
	ds_bpermute_b32 v3, v116, v247
	ds_bpermute_b32 v4, v116, v242
	ds_bpermute_b32 v5, v116, v244
	ds_bpermute_b32 v6, v116, v246
	ds_bpermute_b32 v7, v116, v248
	s_waitcnt lgkmcnt(0)
	s_mov_b32 s88, 0xf0f0f0f
	s_mov_b32 s89, 0xf0f0f0f
	v_min_u32_e32 v104, v241, v0
	v_max_u32_e32 v105, v241, v0
	v_cndmask_b32_e64 v241, v105, v104, s[88:89]
	v_min_u32_e32 v106, v243, v1
	v_max_u32_e32 v107, v243, v1
	v_cndmask_b32_e64 v243, v107, v106, s[88:89]
	v_min_u32_e32 v104, v245, v2
	v_max_u32_e32 v105, v245, v2
	v_cndmask_b32_e64 v245, v105, v104, s[88:89]
	v_min_u32_e32 v106, v247, v3
	v_max_u32_e32 v107, v247, v3
	v_cndmask_b32_e64 v247, v107, v106, s[88:89]
	v_min_u32_e32 v104, v242, v4
	v_max_u32_e32 v105, v242, v4
	v_cndmask_b32_e64 v242, v105, v104, s[88:89]
	v_min_u32_e32 v106, v244, v5
	v_max_u32_e32 v107, v244, v5
	v_cndmask_b32_e64 v244, v107, v106, s[88:89]
	v_min_u32_e32 v104, v246, v6
	v_max_u32_e32 v105, v246, v6
	v_cndmask_b32_e64 v246, v105, v104, s[88:89]
	v_min_u32_e32 v106, v248, v7
	v_max_u32_e32 v107, v248, v7
	v_cndmask_b32_e64 v248, v107, v106, s[88:89]
	v_xor_b32_e32 v116, 8, v234
	ds_bpermute_b32 v0, v116, v241
	ds_bpermute_b32 v1, v116, v243
	ds_bpermute_b32 v2, v116, v245
	ds_bpermute_b32 v3, v116, v247
	ds_bpermute_b32 v4, v116, v242
	ds_bpermute_b32 v5, v116, v244
	ds_bpermute_b32 v6, v116, v246
	ds_bpermute_b32 v7, v116, v248
	s_waitcnt lgkmcnt(0)
	s_mov_b32 s88, 0x33333333
	s_mov_b32 s89, 0x33333333
	v_min_u32_e32 v104, v241, v0
	v_max_u32_e32 v105, v241, v0
	v_cndmask_b32_e64 v241, v105, v104, s[88:89]
	v_min_u32_e32 v106, v243, v1
	v_max_u32_e32 v107, v243, v1
	v_cndmask_b32_e64 v243, v107, v106, s[88:89]
	v_min_u32_e32 v104, v245, v2
	v_max_u32_e32 v105, v245, v2
	v_cndmask_b32_e64 v245, v105, v104, s[88:89]
	v_min_u32_e32 v106, v247, v3
	v_max_u32_e32 v107, v247, v3
	v_cndmask_b32_e64 v247, v107, v106, s[88:89]
	v_min_u32_e32 v104, v242, v4
	v_max_u32_e32 v105, v242, v4
	v_cndmask_b32_e64 v242, v105, v104, s[88:89]
	v_min_u32_e32 v106, v244, v5
	v_max_u32_e32 v107, v244, v5
	v_cndmask_b32_e64 v244, v107, v106, s[88:89]
	v_min_u32_e32 v104, v246, v6
	v_max_u32_e32 v105, v246, v6
	v_cndmask_b32_e64 v246, v105, v104, s[88:89]
	v_min_u32_e32 v106, v248, v7
	v_max_u32_e32 v107, v248, v7
	v_cndmask_b32_e64 v248, v107, v106, s[88:89]
	v_xor_b32_e32 v116, 4, v234
	ds_bpermute_b32 v0, v116, v241
	ds_bpermute_b32 v1, v116, v243
	ds_bpermute_b32 v2, v116, v245
	ds_bpermute_b32 v3, v116, v247
	ds_bpermute_b32 v4, v116, v242
	ds_bpermute_b32 v5, v116, v244
	ds_bpermute_b32 v6, v116, v246
	ds_bpermute_b32 v7, v116, v248
	s_waitcnt lgkmcnt(0)
	s_mov_b32 s88, 0x55555555
	s_mov_b32 s89, 0x55555555
	v_min_u32_e32 v104, v241, v0
	v_max_u32_e32 v105, v241, v0
	v_cndmask_b32_e64 v241, v105, v104, s[88:89]
	v_min_u32_e32 v106, v243, v1
	v_max_u32_e32 v107, v243, v1
	v_cndmask_b32_e64 v243, v107, v106, s[88:89]
	v_min_u32_e32 v104, v245, v2
	v_max_u32_e32 v105, v245, v2
	v_cndmask_b32_e64 v245, v105, v104, s[88:89]
	v_min_u32_e32 v106, v247, v3
	v_max_u32_e32 v107, v247, v3
	v_cndmask_b32_e64 v247, v107, v106, s[88:89]
	v_min_u32_e32 v104, v242, v4
	v_max_u32_e32 v105, v242, v4
	v_cndmask_b32_e64 v242, v105, v104, s[88:89]
	v_min_u32_e32 v106, v244, v5
	v_max_u32_e32 v107, v244, v5
	v_cndmask_b32_e64 v244, v107, v106, s[88:89]
	v_min_u32_e32 v104, v246, v6
	v_max_u32_e32 v105, v246, v6
	v_cndmask_b32_e64 v246, v105, v104, s[88:89]
	v_min_u32_e32 v106, v248, v7
	v_max_u32_e32 v107, v248, v7
	v_cndmask_b32_e64 v248, v107, v106, s[88:89]
	v_mov_b32_e32 v117, 0
	s_lshl_b32 s98, s2, 11
	s_add_u32 s98, s98, s101
	v_add_u32_e32 v116, s98, v234
	v_lshl_add_u32 v119, v235, 2, v237
	v_add_u32_e32 v119, s98, v119
	ds_write_b32 v119, v241 offset:0
	ds_write_b32 v119, v242 offset:32
	ds_write_b32 v119, v243 offset:512
	ds_write_b32 v119, v244 offset:544
	ds_write_b32 v119, v245 offset:1024
	ds_write_b32 v119, v246 offset:1056
	ds_write_b32 v119, v247 offset:1536
	ds_write_b32 v119, v248 offset:1568
	v_add_u32_e32 v118, 0x10000, v116
	ds_write_b32 v118, v117 offset:0
	ds_write_b32 v118, v117 offset:256
	ds_write_b32 v118, v117 offset:512
	ds_write_b32 v118, v117 offset:768
	ds_write_b32 v118, v117 offset:1024
	ds_write_b32 v118, v117 offset:1280
	ds_write_b32 v118, v117 offset:1536
	ds_write_b32 v118, v117 offset:1792
	s_add_u32 s2, s2, 1
	s_cmp_lt_u32 s2, 4
	s_cbranch_scc1 .Lpg1_p0
; #define PG_ISSUE(BUF, TAB, e0_) do { const int isrc_ = ((e0_) < 64) ? myi0 : myi1; \
;       _Pragma("unroll") for (int e = 0; e < 8; ++e) { const int idx_ = __builtin_amdgcn_readlane(isrc_, ((e0_) + e) & 63); \
;         BUF[e] = *(const u32x4*)((TAB) + (size_t)idx_ * 1024 + lane * 16); } } while (0)
; DEV void peer_gather(const Params& P, int l, int m0, const int* idxs, const float* gs) {
;     ...
;     PG_ISSUE(b0, U, 0);
; #pragma nounroll
;     for (int e0 = 0; e0 < 128; e0 += 16) {
;       PG_ISSUE(b1, U, e0 + 8);
	s_waitcnt lgkmcnt(0)
	v_readfirstlane_b32 s82, v122
	v_readfirstlane_b32 s83, v123
	s_nop 4
	v_readfirstlane_b32 s80, v126
	v_readfirstlane_b32 s81, v127
	s_nop 4
	s_mov_b32 s2, 0xffffff80
	s_mov_b32 s86, 0xcccccccc
	s_mov_b32 s87, 0xcccccccc
	s_mov_b32 s88, 0xaaaaaaaa
	s_mov_b32 s89, 0xaaaaaaaa
	s_mov_b32 s90, 0xf0f0f0f0
	s_mov_b32 s91, 0xf0f0f0f0
	s_lshl_b32 vcc_lo, s3, 11
	s_add_u32 s82, s82, vcc_lo
	s_addc_u32 s83, s83, 0
	v_lshl_add_u32 v246, v237, 4, s101
	v_lshrrev_b32_e32 v247, 2, v235
	v_add_u32_e32 v247, v247, v246
	v_add_u32_e32 v247, 0x10000, v247
	s_mov_b32 s100, 0
	s_mov_b32 s98, 0
	s_mov_b32 s99, 0
	s_lshl3_add_u32 vcc_lo, s98, s99
	v_lshl_add_u32 v119, vcc_lo, 8, v236
	global_load_dwordx4 v[80:83], v119, s[82:83]
	global_load_dwordx4 v[84:87], v119, s[82:83] offset:16
	v_lshl_add_u32 v116, s98, 9, v246
	ds_read_b128 v[112:115], v116
	ds_read_b128 v[138:141], v116 offset:16
	ds_read_b128 v[250:253], v116 offset:32
	ds_read_b128 v[242:245], v116 offset:48
	v_lshl_or_b32 v240, s99, 21, v235
	s_waitcnt lgkmcnt(0)
	v_and_or_b32 v112, v112, s2, v240
	v_and_or_b32 v113, v113, s2, v240
	global_load_dwordx4 v[0:3], v112, s[80:81]
	global_load_dwordx4 v[4:7], v113, s[80:81]
	v_and_or_b32 v114, v114, s2, v240
	v_and_or_b32 v115, v115, s2, v240
	global_load_dwordx4 v[8:11], v114, s[80:81]
	global_load_dwordx4 v[12:15], v115, s[80:81]
	v_and_or_b32 v138, v138, s2, v240
	v_and_or_b32 v139, v139, s2, v240
	global_load_dwordx4 v[16:19], v138, s[80:81]
	global_load_dwordx4 v[20:23], v139, s[80:81]
	v_and_or_b32 v140, v140, s2, v240
	v_and_or_b32 v141, v141, s2, v240
	global_load_dwordx4 v[24:27], v140, s[80:81]
	global_load_dwordx4 v[28:31], v141, s[80:81]
	v_and_or_b32 v250, v250, s2, v240
	v_and_or_b32 v251, v251, s2, v240
	global_load_dwordx4 v[32:35], v250, s[80:81]
	global_load_dwordx4 v[36:39], v251, s[80:81]
	v_and_or_b32 v252, v252, s2, v240
	v_and_or_b32 v253, v253, s2, v240
	global_load_dwordx4 v[40:43], v252, s[80:81]
	global_load_dwordx4 v[44:47], v253, s[80:81]
	v_and_or_b32 v242, v242, s2, v240
	v_and_or_b32 v243, v243, s2, v240
	global_load_dwordx4 v[48:51], v242, s[80:81]
	global_load_dwordx4 v[52:55], v243, s[80:81]
	v_and_or_b32 v244, v244, s2, v240
	v_and_or_b32 v245, v245, s2, v240
	global_load_dwordx4 v[56:59], v244, s[80:81]
	global_load_dwordx4 v[60:63], v245, s[80:81]
	s_mov_b32 s92, 1
	v_lshl_add_u32 v116, s92, 9, v246
	ds_read_b128 v[112:115], v116
	ds_read_b128 v[138:141], v116 offset:16
	ds_read_b128 v[250:253], v116 offset:32
	ds_read_b128 v[242:245], v116 offset:48

.Lpg1_act:
	v_readlane_b32 s82, v232, 1
	v_readlane_b32 s83, v232, 2
	s_nop 4
	s_lshl_b32 s98, s2, 11
	s_add_u32 s98, s98, s101
	v_add_u32_e32 v116, s98, v234
	v_add_u32_e32 v117, 0x10000, v116
	ds_read_b32 v0, v116 offset:0
	ds_read_b32 v8, v117 offset:0
	ds_read_b32 v1, v116 offset:256
	ds_read_b32 v9, v117 offset:256
	ds_read_b32 v2, v116 offset:512
	ds_read_b32 v10, v117 offset:512
	ds_read_b32 v3, v116 offset:768
	ds_read_b32 v11, v117 offset:768
	ds_read_b32 v4, v116 offset:1024
	ds_read_b32 v12, v117 offset:1024
	ds_read_b32 v5, v116 offset:1280
	ds_read_b32 v13, v117 offset:1280
	ds_read_b32 v6, v116 offset:1536
	ds_read_b32 v14, v117 offset:1536
	ds_read_b32 v7, v116 offset:1792
	ds_read_b32 v15, v117 offset:1792
	s_waitcnt lgkmcnt(0)
	s_lshl_b32 s99, s2, 2
	s_add_u32 s99, s99, s33
	s_add_u32 s99, s99, 0
	s_lshl_b32 s99, s99, 9
	v_and_b32_e32 v0, 0x7f, v0
	v_lshl_add_u32 v0, v0, 2, s99
	global_load_dword v16, v0, s[82:83]
	v_and_b32_e32 v1, 0x7f, v1
	v_lshl_add_u32 v1, v1, 2, s99
	global_load_dword v17, v1, s[82:83]
	s_lshl_b32 s99, s2, 2
	s_add_u32 s99, s99, s33
	s_add_u32 s99, s99, 1
	s_lshl_b32 s99, s99, 9
	v_and_b32_e32 v2, 0x7f, v2
	v_lshl_add_u32 v2, v2, 2, s99
	global_load_dword v18, v2, s[82:83]
	v_and_b32_e32 v3, 0x7f, v3
	v_lshl_add_u32 v3, v3, 2, s99
	global_load_dword v19, v3, s[82:83]
	s_lshl_b32 s99, s2, 2
	s_add_u32 s99, s99, s33
	s_add_u32 s99, s99, 2
	s_lshl_b32 s99, s99, 9
	v_and_b32_e32 v4, 0x7f, v4
	v_lshl_add_u32 v4, v4, 2, s99
	global_load_dword v20, v4, s[82:83]
	v_and_b32_e32 v5, 0x7f, v5
	v_lshl_add_u32 v5, v5, 2, s99
	global_load_dword v21, v5, s[82:83]
	s_lshl_b32 s99, s2, 2
	s_add_u32 s99, s99, s33
	s_add_u32 s99, s99, 3
	s_lshl_b32 s99, s99, 9
	v_and_b32_e32 v6, 0x7f, v6
	v_lshl_add_u32 v6, v6, 2, s99
	global_load_dword v22, v6, s[82:83]
	v_and_b32_e32 v7, 0x7f, v7
	v_lshl_add_u32 v7, v7, 2, s99
	global_load_dword v23, v7, s[82:83]
	v_mul_f32_e32 v8, 0x3c800000, v8
	v_mul_f32_e32 v9, 0x3c800000, v9
	v_mul_f32_e32 v10, 0x3c800000, v10
	v_mul_f32_e32 v11, 0x3c800000, v11
	v_mul_f32_e32 v12, 0x3c800000, v12
	v_mul_f32_e32 v13, 0x3c800000, v13
	v_mul_f32_e32 v14, 0x3c800000, v14
	v_mul_f32_e32 v15, 0x3c800000, v15
	v_mul_f32_e32 v24, 0x3d372713, v8
	v_mul_f32_e32 v25, 0x3d372713, v9
	v_mul_f32_e32 v26, 0x3d372713, v10
	v_mul_f32_e32 v27, 0x3d372713, v11
	v_mul_f32_e32 v28, 0x3d372713, v12
	v_mul_f32_e32 v29, 0x3d372713, v13
	v_mul_f32_e32 v30, 0x3d372713, v14
	v_mul_f32_e32 v31, 0x3d372713, v15
	v_mul_f32_e32 v24, v8, v24
	v_mul_f32_e32 v25, v9, v25
	v_mul_f32_e32 v26, v10, v26
	v_mul_f32_e32 v27, v11, v27
	v_mul_f32_e32 v28, v12, v28
	v_mul_f32_e32 v29, v13, v29
	v_mul_f32_e32 v30, v14, v30
	v_mul_f32_e32 v31, v15, v31
	v_fma_f32 v24, v8, v24, v8
	v_fma_f32 v25, v9, v25, v9
	v_fma_f32 v26, v10, v26, v10
	v_fma_f32 v27, v11, v27, v11
	v_fma_f32 v28, v12, v28, v12
	v_fma_f32 v29, v13, v29, v13
	v_fma_f32 v30, v14, v30, v14
	v_fma_f32 v31, v15, v31, v15
	v_mul_f32_e32 v24, 0xbfcc422a, v24
	v_mul_f32_e32 v25, 0xbfcc422a, v25
	v_mul_f32_e32 v26, 0xbfcc422a, v26
	v_mul_f32_e32 v27, 0xbfcc422a, v27
	v_mul_f32_e32 v28, 0xbfcc422a, v28
	v_mul_f32_e32 v29, 0xbfcc422a, v29
	v_mul_f32_e32 v30, 0xbfcc422a, v30
	v_mul_f32_e32 v31, 0xbfcc422a, v31
	v_mul_f32_e32 v24, 0x3fb8aa3b, v24
	v_mul_f32_e32 v25, 0x3fb8aa3b, v25
	v_mul_f32_e32 v26, 0x3fb8aa3b, v26
	v_mul_f32_e32 v27, 0x3fb8aa3b, v27
	v_mul_f32_e32 v28, 0x3fb8aa3b, v28
	v_mul_f32_e32 v29, 0x3fb8aa3b, v29
	v_mul_f32_e32 v30, 0x3fb8aa3b, v30
	v_mul_f32_e32 v31, 0x3fb8aa3b, v31
	v_exp_f32_e32 v24, v24
	v_exp_f32_e32 v25, v25
	v_exp_f32_e32 v26, v26
	v_exp_f32_e32 v27, v27
	v_exp_f32_e32 v28, v28
	v_exp_f32_e32 v29, v29
	v_exp_f32_e32 v30, v30
	v_exp_f32_e32 v31, v31
	s_nop 0
	v_add_f32_e32 v24, 1.0, v24
	v_add_f32_e32 v25, 1.0, v25
	v_add_f32_e32 v26, 1.0, v26
	v_add_f32_e32 v27, 1.0, v27
	v_add_f32_e32 v28, 1.0, v28
	v_add_f32_e32 v29, 1.0, v29
	v_add_f32_e32 v30, 1.0, v30
	v_add_f32_e32 v31, 1.0, v31
	v_rcp_f32_e32 v24, v24
	v_rcp_f32_e32 v25, v25
	v_rcp_f32_e32 v26, v26
	v_rcp_f32_e32 v27, v27
	v_rcp_f32_e32 v28, v28
	v_rcp_f32_e32 v29, v29
	v_rcp_f32_e32 v30, v30
	v_rcp_f32_e32 v31, v31
	s_nop 0
	v_mul_f32_e32 v24, v8, v24
	v_mul_f32_e32 v25, v9, v25
	v_mul_f32_e32 v26, v10, v26
	v_mul_f32_e32 v27, v11, v27
	v_mul_f32_e32 v28, v12, v28
	v_mul_f32_e32 v29, v13, v29
	v_mul_f32_e32 v30, v14, v30
	v_mul_f32_e32 v31, v15, v31
	s_waitcnt vmcnt(0)
	v_mul_f32_e32 v24, v24, v16
	ds_write_b32 v117, v24 offset:0
	v_mul_f32_e32 v25, v25, v17
	ds_write_b32 v117, v25 offset:256
	v_mul_f32_e32 v26, v26, v18
	ds_write_b32 v117, v26 offset:512
	v_mul_f32_e32 v27, v27, v19
	ds_write_b32 v117, v27 offset:768
	v_mul_f32_e32 v28, v28, v20
	ds_write_b32 v117, v28 offset:1024
	v_mul_f32_e32 v29, v29, v21
	ds_write_b32 v117, v29 offset:1280
	v_mul_f32_e32 v30, v30, v22
	ds_write_b32 v117, v30 offset:1536
	v_mul_f32_e32 v31, v31, v23
	ds_write_b32 v117, v31 offset:1792
	s_add_u32 s2, s2, 1
	s_cmp_lt_u32 s2, 4
	s_cbranch_scc1 .Lpg1_act
; #define PG_ISSUE(BUF, TAB, e0_) do { const int isrc_ = ((e0_) < 64) ? myi0 : myi1; \
;       _Pragma("unroll") for (int e = 0; e < 8; ++e) { const int idx_ = __builtin_amdgcn_readlane(isrc_, ((e0_) + e) & 63); \
;         BUF[e] = *(const u32x4*)((TAB) + (size_t)idx_ * 1024 + lane * 16); } } while (0)
; DEV void peer_gather(const Params& P, int l, int m0, const int* idxs, const float* gs) {
;     ...
;     for (int e0 = 0; e0 < 128; e0 += 16) {
;       PG_ISSUE(b1, V, e0 + 8);
;       if (e0 == 64 && i + 1 < 16) sort_lists(lane, ni0, ni1, ng0, ng1);
;       PG_V16(b0, e0);
;       if (e0 + 16 < 128) PG_ISSUE(b0, V, e0 + 16);
	s_waitcnt lgkmcnt(0)
	v_readfirstlane_b32 s80, v128
	v_readfirstlane_b32 s81, v129
	s_nop 4
	v_readfirstlane_b32 s82, v132
	v_readfirstlane_b32 s83, v133
	s_nop 4
	s_mov_b32 s2, 0xffffff80
	s_lshl_b32 vcc_lo, s3, 12
	s_add_u32 s82, s82, vcc_lo
	s_addc_u32 s83, s83, 0
	s_mov_b32 s88, 0xff00ff00
	s_mov_b32 s89, 0xff00ff00
	v_lshl_add_u32 v246, v237, 4, s101
	v_add_u32_e32 v247, 0x10000, v246
	s_mov_b32 s100, 0
	s_mov_b32 s98, 0
	s_mov_b32 s99, 0
	v_lshl_add_u32 v116, s98, 9, v246
	ds_read_b128 v[112:115], v116
	ds_read_b128 v[138:141], v116 offset:16
	ds_read_b128 v[250:253], v116 offset:32
	ds_read_b128 v[242:245], v116 offset:48
	v_lshl_or_b32 v240, s99, 21, v235
	s_waitcnt lgkmcnt(0)
	v_and_or_b32 v112, v112, s2, v240
	v_and_or_b32 v113, v113, s2, v240
	global_load_dwordx4 v[0:3], v112, s[80:81]
	global_load_dwordx4 v[4:7], v113, s[80:81]
	v_and_or_b32 v114, v114, s2, v240
	v_and_or_b32 v115, v115, s2, v240
	global_load_dwordx4 v[8:11], v114, s[80:81]
	global_load_dwordx4 v[12:15], v115, s[80:81]
	v_and_or_b32 v138, v138, s2, v240
	v_and_or_b32 v139, v139, s2, v240
	global_load_dwordx4 v[16:19], v138, s[80:81]
	global_load_dwordx4 v[20:23], v139, s[80:81]
	v_and_or_b32 v140, v140, s2, v240
	v_and_or_b32 v141, v141, s2, v240
	global_load_dwordx4 v[24:27], v140, s[80:81]
	global_load_dwordx4 v[28:31], v141, s[80:81]
	v_and_or_b32 v250, v250, s2, v240
	v_and_or_b32 v251, v251, s2, v240
	global_load_dwordx4 v[32:35], v250, s[80:81]
	global_load_dwordx4 v[36:39], v251, s[80:81]
	v_and_or_b32 v252, v252, s2, v240
	v_and_or_b32 v253, v253, s2, v240
	global_load_dwordx4 v[40:43], v252, s[80:81]
	global_load_dwordx4 v[44:47], v253, s[80:81]
	v_and_or_b32 v242, v242, s2, v240
	v_and_or_b32 v243, v243, s2, v240
	global_load_dwordx4 v[48:51], v242, s[80:81]
	global_load_dwordx4 v[52:55], v243, s[80:81]
	v_and_or_b32 v244, v244, s2, v240
	v_and_or_b32 v245, v245, s2, v240
	global_load_dwordx4 v[56:59], v244, s[80:81]
	global_load_dwordx4 v[60:63], v245, s[80:81]
	s_mov_b32 s92, 1
	v_lshl_add_u32 v116, s92, 9, v246
	ds_read_b128 v[112:115], v116
	ds_read_b128 v[138:141], v116 offset:16
	ds_read_b128 v[250:253], v116 offset:32
	ds_read_b128 v[242:245], v116 offset:48
	v_lshl_add_u32 v117, s98, 9, v247
	ds_read_b128 v[84:87], v117
	ds_read_b128 v[88:91], v117 offset:16
	ds_read_b128 v[92:95], v117 offset:32
	ds_read_b128 v[96:99], v117 offset:48
	s_waitcnt vmcnt(0)
